# Every run of 16x16x32 MFMAs (GEMM phases) placed on an 8-byte boundary (one s_nop in front of 89 runs)
# baseline (speedup 1.0000x reference)
.LBB0_163:
	ds_read_b128 v[144:147], v151
	ds_read_b128 v[156:159], v151 offset:1024
	ds_read_b128 v[160:163], v151 offset:2048
	ds_read_b128 v[164:167], v151 offset:3072
	ds_read_b128 v[168:171], v152
	ds_read_b128 v[172:175], v152 offset:1024
	ds_read_b128 v[176:179], v152 offset:2048
	ds_read_b128 v[180:183], v152 offset:3072
	s_add_u32 s26, s24, 0xfffc0080
	s_addc_u32 s27, s25, -1
	s_cmp_eq_u32 s55, 12
	s_cselect_b32 s29, s19, s27
	s_cselect_b32 s28, s51, s26
	s_cselect_b32 s27, s17, s54
	s_cselect_b32 s26, s52, s53
	s_add_i32 m0, s38, 0xc000
	ds_read_b128 v[184:187], v153
	ds_read_b128 v[188:191], v153 offset:1024
	ds_read_b128 v[192:195], v153 offset:2048
	ds_read_b128 v[196:199], v153 offset:3072
	ds_read_b128 v[200:203], v153 offset:4096
	ds_read_b128 v[208:211], v153 offset:5120
	ds_read_b128 v[212:215], v153 offset:6144
	ds_read_b128 v[216:219], v153 offset:7168
	global_load_lds_dwordx4 v138, s[24:25]
	s_add_i32 m0, s38, 0xe000
	s_nop 0
	global_load_lds_dwordx4 v136, s[24:25]
	s_waitcnt vmcnt(8)
	s_waitcnt lgkmcnt(0)
	s_barrier
	s_waitcnt lgkmcnt(0)
	s_nop 0
	v_mfma_f32_16x16x32_bf16 v[124:127], v[144:147], v[184:187], v[124:127]
	v_mfma_f32_16x16x32_bf16 v[120:123], v[160:163], v[184:187], v[120:123]
	v_mfma_f32_16x16x32_bf16 v[108:111], v[144:147], v[192:195], v[108:111]
	v_mfma_f32_16x16x32_bf16 v[104:107], v[160:163], v[192:195], v[104:107]
	v_mfma_f32_16x16x32_bf16 v[92:95], v[144:147], v[200:203], v[92:95]
	v_mfma_f32_16x16x32_bf16 v[88:91], v[160:163], v[200:203], v[88:91]
	v_mfma_f32_16x16x32_bf16 v[76:79], v[144:147], v[212:215], v[76:79]
	v_mfma_f32_16x16x32_bf16 v[72:75], v[160:163], v[212:215], v[72:75]
	v_mfma_f32_16x16x32_bf16 v[124:127], v[156:159], v[188:191], v[124:127]
	v_mfma_f32_16x16x32_bf16 v[120:123], v[164:167], v[188:191], v[120:123]
	v_mfma_f32_16x16x32_bf16 v[108:111], v[156:159], v[196:199], v[108:111]
	v_mfma_f32_16x16x32_bf16 v[104:107], v[164:167], v[196:199], v[104:107]
	v_mfma_f32_16x16x32_bf16 v[92:95], v[156:159], v[208:211], v[92:95]
	v_mfma_f32_16x16x32_bf16 v[88:91], v[164:167], v[208:211], v[88:91]
	v_mfma_f32_16x16x32_bf16 v[76:79], v[156:159], v[216:219], v[76:79]
	v_mfma_f32_16x16x32_bf16 v[72:75], v[164:167], v[216:219], v[72:75]
	v_mfma_f32_16x16x32_bf16 v[116:119], v[168:171], v[184:187], v[116:119]
	v_mfma_f32_16x16x32_bf16 v[112:115], v[176:179], v[184:187], v[112:115]
	v_mfma_f32_16x16x32_bf16 v[100:103], v[168:171], v[192:195], v[100:103]
	v_mfma_f32_16x16x32_bf16 v[96:99], v[176:179], v[192:195], v[96:99]
	v_mfma_f32_16x16x32_bf16 v[84:87], v[168:171], v[200:203], v[84:87]
	v_mfma_f32_16x16x32_bf16 v[80:83], v[176:179], v[200:203], v[80:83]
	v_mfma_f32_16x16x32_bf16 v[68:71], v[168:171], v[212:215], v[68:71]
	v_mfma_f32_16x16x32_bf16 v[64:67], v[176:179], v[212:215], v[64:67]
	v_mfma_f32_16x16x32_bf16 v[116:119], v[172:175], v[188:191], v[116:119]
	v_mfma_f32_16x16x32_bf16 v[112:115], v[180:183], v[188:191], v[112:115]
	v_mfma_f32_16x16x32_bf16 v[100:103], v[172:175], v[196:199], v[100:103]
	v_mfma_f32_16x16x32_bf16 v[96:99], v[180:183], v[196:199], v[96:99]
	v_mfma_f32_16x16x32_bf16 v[84:87], v[172:175], v[208:211], v[84:87]
	v_mfma_f32_16x16x32_bf16 v[80:83], v[180:183], v[208:211], v[80:83]
	v_mfma_f32_16x16x32_bf16 v[68:71], v[172:175], v[216:219], v[68:71]
	v_mfma_f32_16x16x32_bf16 v[64:67], v[180:183], v[216:219], v[64:67]
	s_barrier
	s_add_i32 s56, s48, s35
	s_mov_b32 m0, s56
	ds_read_b128 v[184:187], v153 offset:16384
	ds_read_b128 v[188:191], v153 offset:17408
	ds_read_b128 v[192:195], v153 offset:18432
	ds_read_b128 v[196:199], v153 offset:19456
	ds_read_b128 v[200:203], v153 offset:20480
	ds_read_b128 v[208:211], v153 offset:21504
	ds_read_b128 v[212:215], v153 offset:22528
	ds_read_b128 v[216:219], v153 offset:23552
	global_load_lds_dwordx4 v132, s[26:27]
	s_add_i32 m0, s56, 0x2000
	s_add_u32 s56, s26, 0x40000
	s_mov_b64 s[98:99], s[26:27]
	s_addc_u32 s57, s27, 0
	s_add_i32 s58, s49, s35
	global_load_lds_dwordx4 v128, s[26:27]
	s_mov_b32 m0, s58
	s_mov_b64 s[100:101], s[28:29]
	global_load_lds_dwordx4 v132, s[56:57]
	s_add_i32 m0, s58, 0x2000
	s_nop 0
	global_load_lds_dwordx4 v128, s[56:57]
	s_mov_b32 m0, s38
	s_nop 0
	global_load_lds_dwordx4 v134, s[28:29]
	s_mov_b32 m0, s39
	s_nop 0
	global_load_lds_dwordx4 v130, s[28:29]
	s_waitcnt vmcnt(8)
	s_waitcnt lgkmcnt(0)
	s_barrier
	s_waitcnt lgkmcnt(0)
	s_nop 0
	v_mfma_f32_16x16x32_bf16 v[60:63], v[144:147], v[184:187], v[60:63]
	v_mfma_f32_16x16x32_bf16 v[56:59], v[160:163], v[184:187], v[56:59]
	v_mfma_f32_16x16x32_bf16 v[44:47], v[144:147], v[192:195], v[44:47]
	v_mfma_f32_16x16x32_bf16 v[40:43], v[160:163], v[192:195], v[40:43]
	v_mfma_f32_16x16x32_bf16 v[28:31], v[144:147], v[200:203], v[28:31]
	v_mfma_f32_16x16x32_bf16 v[24:27], v[160:163], v[200:203], v[24:27]
	v_mfma_f32_16x16x32_bf16 v[12:15], v[144:147], v[212:215], v[12:15]
	v_mfma_f32_16x16x32_bf16 v[8:11], v[160:163], v[212:215], v[8:11]
	v_mfma_f32_16x16x32_bf16 v[60:63], v[156:159], v[188:191], v[60:63]
	v_mfma_f32_16x16x32_bf16 v[56:59], v[164:167], v[188:191], v[56:59]
	v_mfma_f32_16x16x32_bf16 v[44:47], v[156:159], v[196:199], v[44:47]
	v_mfma_f32_16x16x32_bf16 v[40:43], v[164:167], v[196:199], v[40:43]
	v_mfma_f32_16x16x32_bf16 v[28:31], v[156:159], v[208:211], v[28:31]
	v_mfma_f32_16x16x32_bf16 v[24:27], v[164:167], v[208:211], v[24:27]
	v_mfma_f32_16x16x32_bf16 v[12:15], v[156:159], v[216:219], v[12:15]
	v_mfma_f32_16x16x32_bf16 v[8:11], v[164:167], v[216:219], v[8:11]
	v_mfma_f32_16x16x32_bf16 v[52:55], v[168:171], v[184:187], v[52:55]
	v_mfma_f32_16x16x32_bf16 v[48:51], v[176:179], v[184:187], v[48:51]
	v_mfma_f32_16x16x32_bf16 v[36:39], v[168:171], v[192:195], v[36:39]
	v_mfma_f32_16x16x32_bf16 v[32:35], v[176:179], v[192:195], v[32:35]
	v_mfma_f32_16x16x32_bf16 v[20:23], v[168:171], v[200:203], v[20:23]
	v_mfma_f32_16x16x32_bf16 v[16:19], v[176:179], v[200:203], v[16:19]
	v_mfma_f32_16x16x32_bf16 v[4:7], v[168:171], v[212:215], v[4:7]
	v_mfma_f32_16x16x32_bf16 v[0:3], v[176:179], v[212:215], v[0:3]
	v_mfma_f32_16x16x32_bf16 v[52:55], v[172:175], v[188:191], v[52:55]
	v_mfma_f32_16x16x32_bf16 v[48:51], v[180:183], v[188:191], v[48:51]
	v_mfma_f32_16x16x32_bf16 v[36:39], v[172:175], v[196:199], v[36:39]
	v_mfma_f32_16x16x32_bf16 v[32:35], v[180:183], v[196:199], v[32:35]
	v_mfma_f32_16x16x32_bf16 v[20:23], v[172:175], v[208:211], v[20:23]
	v_mfma_f32_16x16x32_bf16 v[16:19], v[180:183], v[208:211], v[16:19]
	v_mfma_f32_16x16x32_bf16 v[4:7], v[172:175], v[216:219], v[4:7]
	v_mfma_f32_16x16x32_bf16 v[0:3], v[180:183], v[216:219], v[0:3]
	s_barrier
	s_add_i32 s56, 0, 0x18000
	s_add_i32 s57, 0, 0x1c000
	v_add_u32_e32 v164, s56, v149
	v_add_u32_e32 v180, s57, v149
	ds_read_b128 v[144:147], v164
	ds_read_b128 v[156:159], v164 offset:1024
	ds_read_b128 v[160:163], v164 offset:2048
	ds_read_b128 v[164:167], v164 offset:3072
	ds_read_b128 v[168:171], v180
	ds_read_b128 v[172:175], v180 offset:1024
	ds_read_b128 v[176:179], v180 offset:2048
	ds_read_b128 v[180:183], v180 offset:3072
	s_add_u32 s28, s28, 0x40000
	s_addc_u32 s29, s29, 0
	s_mov_b32 m0, s40
	ds_read_b128 v[184:187], v153 offset:32768
	ds_read_b128 v[188:191], v153 offset:33792
	ds_read_b128 v[192:195], v153 offset:34816
	ds_read_b128 v[196:199], v153 offset:35840
	ds_read_b128 v[200:203], v153 offset:36864
	ds_read_b128 v[208:211], v153 offset:37888
	ds_read_b128 v[212:215], v153 offset:38912
	ds_read_b128 v[216:219], v153 offset:39936
	global_load_lds_dwordx4 v134, s[28:29]
	s_mov_b32 m0, s41
	s_nop 0
	global_load_lds_dwordx4 v130, s[28:29]
	s_waitcnt vmcnt(8)
	s_waitcnt lgkmcnt(0)
	s_barrier
	s_waitcnt lgkmcnt(0)
	s_nop 0
	v_mfma_f32_16x16x32_bf16 v[124:127], v[144:147], v[184:187], v[124:127]
	v_mfma_f32_16x16x32_bf16 v[120:123], v[160:163], v[184:187], v[120:123]
	v_mfma_f32_16x16x32_bf16 v[108:111], v[144:147], v[192:195], v[108:111]
	v_mfma_f32_16x16x32_bf16 v[104:107], v[160:163], v[192:195], v[104:107]
	v_mfma_f32_16x16x32_bf16 v[92:95], v[144:147], v[200:203], v[92:95]
	v_mfma_f32_16x16x32_bf16 v[88:91], v[160:163], v[200:203], v[88:91]
	v_mfma_f32_16x16x32_bf16 v[76:79], v[144:147], v[212:215], v[76:79]
	v_mfma_f32_16x16x32_bf16 v[72:75], v[160:163], v[212:215], v[72:75]
	v_mfma_f32_16x16x32_bf16 v[124:127], v[156:159], v[188:191], v[124:127]
	v_mfma_f32_16x16x32_bf16 v[120:123], v[164:167], v[188:191], v[120:123]
	v_mfma_f32_16x16x32_bf16 v[108:111], v[156:159], v[196:199], v[108:111]
	v_mfma_f32_16x16x32_bf16 v[104:107], v[164:167], v[196:199], v[104:107]
	v_mfma_f32_16x16x32_bf16 v[92:95], v[156:159], v[208:211], v[92:95]
	v_mfma_f32_16x16x32_bf16 v[88:91], v[164:167], v[208:211], v[88:91]
	v_mfma_f32_16x16x32_bf16 v[76:79], v[156:159], v[216:219], v[76:79]
	v_mfma_f32_16x16x32_bf16 v[72:75], v[164:167], v[216:219], v[72:75]
	v_mfma_f32_16x16x32_bf16 v[116:119], v[168:171], v[184:187], v[116:119]
	v_mfma_f32_16x16x32_bf16 v[112:115], v[176:179], v[184:187], v[112:115]
	v_mfma_f32_16x16x32_bf16 v[100:103], v[168:171], v[192:195], v[100:103]
	v_mfma_f32_16x16x32_bf16 v[96:99], v[176:179], v[192:195], v[96:99]
	v_mfma_f32_16x16x32_bf16 v[84:87], v[168:171], v[200:203], v[84:87]
	v_mfma_f32_16x16x32_bf16 v[80:83], v[176:179], v[200:203], v[80:83]
	v_mfma_f32_16x16x32_bf16 v[68:71], v[168:171], v[212:215], v[68:71]
	v_mfma_f32_16x16x32_bf16 v[64:67], v[176:179], v[212:215], v[64:67]
	v_mfma_f32_16x16x32_bf16 v[116:119], v[172:175], v[188:191], v[116:119]
	v_mfma_f32_16x16x32_bf16 v[112:115], v[180:183], v[188:191], v[112:115]
	v_mfma_f32_16x16x32_bf16 v[100:103], v[172:175], v[196:199], v[100:103]
	v_mfma_f32_16x16x32_bf16 v[96:99], v[180:183], v[196:199], v[96:99]
	v_mfma_f32_16x16x32_bf16 v[84:87], v[172:175], v[208:211], v[84:87]
	v_mfma_f32_16x16x32_bf16 v[80:83], v[180:183], v[208:211], v[80:83]
	v_mfma_f32_16x16x32_bf16 v[68:71], v[172:175], v[216:219], v[68:71]
	v_mfma_f32_16x16x32_bf16 v[64:67], v[180:183], v[216:219], v[64:67]
	s_barrier
	s_add_i32 s28, s56, s35
	s_mov_b32 m0, s28
	ds_read_b128 v[184:187], v153 offset:49152
	ds_read_b128 v[188:191], v153 offset:50176
	ds_read_b128 v[192:195], v153 offset:51200
	ds_read_b128 v[196:199], v153 offset:52224
	ds_read_b128 v[200:203], v153 offset:53248
	ds_read_b128 v[208:211], v153 offset:54272
	ds_read_b128 v[212:215], v153 offset:55296
	ds_read_b128 v[216:219], v153 offset:56320
	global_load_lds_dwordx4 v220, s[26:27]
	s_add_i32 m0, s28, 0x2000
	s_add_u32 s26, s26, 0x40080
	s_addc_u32 s27, s27, 0
	s_add_i32 s28, s57, s35
	global_load_lds_dwordx4 v204, s[98:99]
	s_mov_b32 m0, s28
	s_nop 0
	global_load_lds_dwordx4 v132, s[26:27]
	s_add_i32 m0, s28, 0x2000
	s_nop 0
	global_load_lds_dwordx4 v128, s[26:27]
	s_mov_b32 m0, s45
	s_nop 0
	global_load_lds_dwordx4 v221, s[100:101]
	s_mov_b32 m0, s46
	s_nop 0
	global_load_lds_dwordx4 v205, s[100:101]
	s_waitcnt vmcnt(8)
	s_waitcnt lgkmcnt(0)
	s_barrier
	s_waitcnt lgkmcnt(0)
	v_mfma_f32_16x16x32_bf16 v[60:63], v[144:147], v[184:187], v[60:63]
	v_mfma_f32_16x16x32_bf16 v[56:59], v[160:163], v[184:187], v[56:59]
	v_mfma_f32_16x16x32_bf16 v[44:47], v[144:147], v[192:195], v[44:47]
	v_mfma_f32_16x16x32_bf16 v[40:43], v[160:163], v[192:195], v[40:43]
	v_mfma_f32_16x16x32_bf16 v[28:31], v[144:147], v[200:203], v[28:31]
	v_mfma_f32_16x16x32_bf16 v[24:27], v[160:163], v[200:203], v[24:27]
	v_mfma_f32_16x16x32_bf16 v[12:15], v[144:147], v[212:215], v[12:15]
	v_mfma_f32_16x16x32_bf16 v[8:11], v[160:163], v[212:215], v[8:11]
	v_mfma_f32_16x16x32_bf16 v[60:63], v[156:159], v[188:191], v[60:63]
	v_mfma_f32_16x16x32_bf16 v[56:59], v[164:167], v[188:191], v[56:59]
	v_mfma_f32_16x16x32_bf16 v[44:47], v[156:159], v[196:199], v[44:47]
	v_mfma_f32_16x16x32_bf16 v[40:43], v[164:167], v[196:199], v[40:43]
	v_mfma_f32_16x16x32_bf16 v[28:31], v[156:159], v[208:211], v[28:31]
	v_mfma_f32_16x16x32_bf16 v[24:27], v[164:167], v[208:211], v[24:27]
	v_mfma_f32_16x16x32_bf16 v[12:15], v[156:159], v[216:219], v[12:15]
	v_mfma_f32_16x16x32_bf16 v[8:11], v[164:167], v[216:219], v[8:11]
	v_mfma_f32_16x16x32_bf16 v[52:55], v[168:171], v[184:187], v[52:55]
	v_mfma_f32_16x16x32_bf16 v[48:51], v[176:179], v[184:187], v[48:51]
	v_mfma_f32_16x16x32_bf16 v[36:39], v[168:171], v[192:195], v[36:39]
	v_mfma_f32_16x16x32_bf16 v[32:35], v[176:179], v[192:195], v[32:35]
	v_mfma_f32_16x16x32_bf16 v[20:23], v[168:171], v[200:203], v[20:23]
	v_mfma_f32_16x16x32_bf16 v[16:19], v[176:179], v[200:203], v[16:19]
	v_mfma_f32_16x16x32_bf16 v[4:7], v[168:171], v[212:215], v[4:7]
	v_mfma_f32_16x16x32_bf16 v[0:3], v[176:179], v[212:215], v[0:3]
	v_mfma_f32_16x16x32_bf16 v[52:55], v[172:175], v[188:191], v[52:55]
	v_mfma_f32_16x16x32_bf16 v[48:51], v[180:183], v[188:191], v[48:51]
	v_mfma_f32_16x16x32_bf16 v[36:39], v[172:175], v[196:199], v[36:39]
	v_mfma_f32_16x16x32_bf16 v[32:35], v[180:183], v[196:199], v[32:35]
	v_mfma_f32_16x16x32_bf16 v[20:23], v[172:175], v[208:211], v[20:23]
	v_mfma_f32_16x16x32_bf16 v[16:19], v[180:183], v[208:211], v[16:19]
	v_mfma_f32_16x16x32_bf16 v[4:7], v[172:175], v[216:219], v[4:7]
	v_mfma_f32_16x16x32_bf16 v[0:3], v[180:183], v[216:219], v[0:3]
	s_barrier
	s_add_i32 s55, s55, 2
	s_add_u32 s53, s53, 0x100
	s_addc_u32 s54, s54, 0
	s_add_u32 s24, s24, 0x100
	s_addc_u32 s25, s25, 0
	s_cmp_gt_u32 s55, 13
	s_cbranch_scc0 .LBB0_163
	s_and_b64 vcc, exec, s[14:15]
	s_cbranch_vccz .LBB0_166
	s_barrier

.LBB0_606:
	ds_read_b128 v[140:143], v147
	ds_read_b128 v[150:153], v147 offset:1024
	ds_read_b128 v[154:157], v147 offset:2048
	ds_read_b128 v[158:161], v147 offset:3072
	ds_read_b128 v[162:165], v148
	ds_read_b128 v[166:169], v148 offset:1024
	ds_read_b128 v[170:173], v148 offset:2048
	ds_read_b128 v[174:177], v148 offset:3072
	s_add_u32 s30, s28, 0x100
	s_addc_u32 s31, s29, 0
	s_cmp_eq_u32 s58, 12
	s_cselect_b32 s37, s21, s31
	s_cselect_b32 s36, s27, s30
	s_cselect_b32 s35, s19, s57
	s_cselect_b32 s34, s55, s56
	s_add_i32 m0, s44, 0xc000
	ds_read_b128 v[178:181], v149
	ds_read_b128 v[182:185], v149 offset:1024
	ds_read_b128 v[186:189], v149 offset:2048
	ds_read_b128 v[190:193], v149 offset:3072
	ds_read_b128 v[194:197], v149 offset:4096
	ds_read_b128 v[198:201], v149 offset:5120
	ds_read_b128 v[202:205], v149 offset:6144
	ds_read_b128 v[208:211], v149 offset:7168
	global_load_lds_dwordx4 v134, s[28:29]
	s_add_i32 m0, s44, 0xe000
	s_nop 0
	global_load_lds_dwordx4 v132, s[28:29]
	s_waitcnt vmcnt(8)
	s_waitcnt lgkmcnt(0)
	s_barrier
	s_waitcnt lgkmcnt(0)
	s_nop 0
	v_mfma_f32_16x16x32_bf16 v[124:127], v[140:143], v[178:181], v[124:127]
	v_mfma_f32_16x16x32_bf16 v[120:123], v[154:157], v[178:181], v[120:123]
	v_mfma_f32_16x16x32_bf16 v[108:111], v[140:143], v[186:189], v[108:111]
	v_mfma_f32_16x16x32_bf16 v[104:107], v[154:157], v[186:189], v[104:107]
	v_mfma_f32_16x16x32_bf16 v[92:95], v[140:143], v[194:197], v[92:95]
	v_mfma_f32_16x16x32_bf16 v[88:91], v[154:157], v[194:197], v[88:91]
	v_mfma_f32_16x16x32_bf16 v[76:79], v[140:143], v[202:205], v[76:79]
	v_mfma_f32_16x16x32_bf16 v[72:75], v[154:157], v[202:205], v[72:75]
	v_mfma_f32_16x16x32_bf16 v[124:127], v[150:153], v[182:185], v[124:127]
	v_mfma_f32_16x16x32_bf16 v[120:123], v[158:161], v[182:185], v[120:123]
	v_mfma_f32_16x16x32_bf16 v[108:111], v[150:153], v[190:193], v[108:111]
	v_mfma_f32_16x16x32_bf16 v[104:107], v[158:161], v[190:193], v[104:107]
	v_mfma_f32_16x16x32_bf16 v[92:95], v[150:153], v[198:201], v[92:95]
	v_mfma_f32_16x16x32_bf16 v[88:91], v[158:161], v[198:201], v[88:91]
	v_mfma_f32_16x16x32_bf16 v[76:79], v[150:153], v[208:211], v[76:79]
	v_mfma_f32_16x16x32_bf16 v[72:75], v[158:161], v[208:211], v[72:75]
	v_mfma_f32_16x16x32_bf16 v[116:119], v[162:165], v[178:181], v[116:119]
	v_mfma_f32_16x16x32_bf16 v[112:115], v[170:173], v[178:181], v[112:115]
	v_mfma_f32_16x16x32_bf16 v[100:103], v[162:165], v[186:189], v[100:103]
	v_mfma_f32_16x16x32_bf16 v[96:99], v[170:173], v[186:189], v[96:99]
	v_mfma_f32_16x16x32_bf16 v[84:87], v[162:165], v[194:197], v[84:87]
	v_mfma_f32_16x16x32_bf16 v[80:83], v[170:173], v[194:197], v[80:83]
	v_mfma_f32_16x16x32_bf16 v[68:71], v[162:165], v[202:205], v[68:71]
	v_mfma_f32_16x16x32_bf16 v[64:67], v[170:173], v[202:205], v[64:67]
	v_mfma_f32_16x16x32_bf16 v[116:119], v[166:169], v[182:185], v[116:119]
	v_mfma_f32_16x16x32_bf16 v[112:115], v[174:177], v[182:185], v[112:115]
	v_mfma_f32_16x16x32_bf16 v[100:103], v[166:169], v[190:193], v[100:103]
	v_mfma_f32_16x16x32_bf16 v[96:99], v[174:177], v[190:193], v[96:99]
	v_mfma_f32_16x16x32_bf16 v[84:87], v[166:169], v[198:201], v[84:87]
	v_mfma_f32_16x16x32_bf16 v[80:83], v[174:177], v[198:201], v[80:83]
	v_mfma_f32_16x16x32_bf16 v[68:71], v[166:169], v[208:211], v[68:71]
	v_mfma_f32_16x16x32_bf16 v[64:67], v[174:177], v[208:211], v[64:67]
	s_barrier
	s_add_i32 s28, s52, s43
	s_mov_b32 m0, s28
	ds_read_b128 v[178:181], v149 offset:16384
	ds_read_b128 v[182:185], v149 offset:17408
	ds_read_b128 v[186:189], v149 offset:18432
	ds_read_b128 v[190:193], v149 offset:19456
	ds_read_b128 v[194:197], v149 offset:20480
	ds_read_b128 v[198:201], v149 offset:21504
	ds_read_b128 v[202:205], v149 offset:22528
	ds_read_b128 v[208:211], v149 offset:23552
	global_load_lds_dwordx4 v128, s[34:35]
	s_add_i32 m0, s28, 0x2000
	s_add_u32 s28, s34, 0x40000
	s_mov_b64 s[98:99], s[34:35]
	s_addc_u32 s29, s35, 0
	s_add_i32 s59, s53, s43
	global_load_lds_dwordx4 v130, s[34:35]
	s_mov_b32 m0, s59
	s_nop 0
	global_load_lds_dwordx4 v128, s[28:29]
	s_add_i32 m0, s59, 0x2000
	s_nop 0
	global_load_lds_dwordx4 v130, s[28:29]
	s_mov_b32 m0, s44
	s_nop 0
	global_load_lds_dwordx4 v128, s[36:37]
	s_mov_b32 m0, s45
	s_nop 0
	global_load_lds_dwordx4 v130, s[36:37]
	s_waitcnt vmcnt(8)
	s_waitcnt lgkmcnt(0)
	s_barrier
	s_waitcnt lgkmcnt(0)
	s_nop 0
	v_mfma_f32_16x16x32_bf16 v[60:63], v[140:143], v[178:181], v[60:63]
	v_mfma_f32_16x16x32_bf16 v[56:59], v[154:157], v[178:181], v[56:59]
	v_mfma_f32_16x16x32_bf16 v[44:47], v[140:143], v[186:189], v[44:47]
	v_mfma_f32_16x16x32_bf16 v[40:43], v[154:157], v[186:189], v[40:43]
	v_mfma_f32_16x16x32_bf16 v[28:31], v[140:143], v[194:197], v[28:31]
	v_mfma_f32_16x16x32_bf16 v[24:27], v[154:157], v[194:197], v[24:27]
	v_mfma_f32_16x16x32_bf16 v[12:15], v[140:143], v[202:205], v[12:15]
	v_mfma_f32_16x16x32_bf16 v[8:11], v[154:157], v[202:205], v[8:11]
	v_mfma_f32_16x16x32_bf16 v[60:63], v[150:153], v[182:185], v[60:63]
	v_mfma_f32_16x16x32_bf16 v[56:59], v[158:161], v[182:185], v[56:59]
	v_mfma_f32_16x16x32_bf16 v[44:47], v[150:153], v[190:193], v[44:47]
	v_mfma_f32_16x16x32_bf16 v[40:43], v[158:161], v[190:193], v[40:43]
	v_mfma_f32_16x16x32_bf16 v[28:31], v[150:153], v[198:201], v[28:31]
	v_mfma_f32_16x16x32_bf16 v[24:27], v[158:161], v[198:201], v[24:27]
	v_mfma_f32_16x16x32_bf16 v[12:15], v[150:153], v[208:211], v[12:15]
	v_mfma_f32_16x16x32_bf16 v[8:11], v[158:161], v[208:211], v[8:11]
	v_mfma_f32_16x16x32_bf16 v[52:55], v[162:165], v[178:181], v[52:55]
	v_mfma_f32_16x16x32_bf16 v[48:51], v[170:173], v[178:181], v[48:51]
	v_mfma_f32_16x16x32_bf16 v[36:39], v[162:165], v[186:189], v[36:39]
	v_mfma_f32_16x16x32_bf16 v[32:35], v[170:173], v[186:189], v[32:35]
	v_mfma_f32_16x16x32_bf16 v[20:23], v[162:165], v[194:197], v[20:23]
	v_mfma_f32_16x16x32_bf16 v[16:19], v[170:173], v[194:197], v[16:19]
	v_mfma_f32_16x16x32_bf16 v[4:7], v[162:165], v[202:205], v[4:7]
	v_mfma_f32_16x16x32_bf16 v[0:3], v[170:173], v[202:205], v[0:3]
	v_mfma_f32_16x16x32_bf16 v[52:55], v[166:169], v[182:185], v[52:55]
	v_mfma_f32_16x16x32_bf16 v[48:51], v[174:177], v[182:185], v[48:51]
	v_mfma_f32_16x16x32_bf16 v[36:39], v[166:169], v[190:193], v[36:39]
	v_mfma_f32_16x16x32_bf16 v[32:35], v[174:177], v[190:193], v[32:35]
	v_mfma_f32_16x16x32_bf16 v[20:23], v[166:169], v[198:201], v[20:23]
	v_mfma_f32_16x16x32_bf16 v[16:19], v[174:177], v[198:201], v[16:19]
	v_mfma_f32_16x16x32_bf16 v[4:7], v[166:169], v[208:211], v[4:7]
	v_mfma_f32_16x16x32_bf16 v[0:3], v[174:177], v[208:211], v[0:3]
	s_barrier
	s_add_i32 s59, 0, 0x18000
	s_add_i32 s60, 0, 0x1c000
	v_add_u32_e32 v158, s59, v145
	v_add_u32_e32 v174, s60, v145
	ds_read_b128 v[140:143], v158
	ds_read_b128 v[150:153], v158 offset:1024
	ds_read_b128 v[154:157], v158 offset:2048
	ds_read_b128 v[158:161], v158 offset:3072
	ds_read_b128 v[162:165], v174
	ds_read_b128 v[166:169], v174 offset:1024
	ds_read_b128 v[170:173], v174 offset:2048
	ds_read_b128 v[174:177], v174 offset:3072
	s_add_u32 s28, s36, 0x40000
	s_addc_u32 s29, s37, 0
	s_mov_b32 m0, s46
	ds_read_b128 v[178:181], v149 offset:32768
	ds_read_b128 v[182:185], v149 offset:33792
	ds_read_b128 v[186:189], v149 offset:34816
	ds_read_b128 v[190:193], v149 offset:35840
	ds_read_b128 v[194:197], v149 offset:36864
	ds_read_b128 v[198:201], v149 offset:37888
	ds_read_b128 v[202:205], v149 offset:38912
	ds_read_b128 v[208:211], v149 offset:39936
	global_load_lds_dwordx4 v128, s[28:29]
	s_mov_b32 m0, s47
	s_nop 0
	global_load_lds_dwordx4 v130, s[28:29]
	s_waitcnt vmcnt(8)
	s_waitcnt lgkmcnt(0)
	s_barrier
	s_waitcnt lgkmcnt(0)
	s_nop 0
	v_mfma_f32_16x16x32_bf16 v[124:127], v[140:143], v[178:181], v[124:127]
	v_mfma_f32_16x16x32_bf16 v[120:123], v[154:157], v[178:181], v[120:123]
	v_mfma_f32_16x16x32_bf16 v[108:111], v[140:143], v[186:189], v[108:111]
	v_mfma_f32_16x16x32_bf16 v[104:107], v[154:157], v[186:189], v[104:107]
	v_mfma_f32_16x16x32_bf16 v[92:95], v[140:143], v[194:197], v[92:95]
	v_mfma_f32_16x16x32_bf16 v[88:91], v[154:157], v[194:197], v[88:91]
	v_mfma_f32_16x16x32_bf16 v[76:79], v[140:143], v[202:205], v[76:79]
	v_mfma_f32_16x16x32_bf16 v[72:75], v[154:157], v[202:205], v[72:75]
	v_mfma_f32_16x16x32_bf16 v[124:127], v[150:153], v[182:185], v[124:127]
	v_mfma_f32_16x16x32_bf16 v[120:123], v[158:161], v[182:185], v[120:123]
	v_mfma_f32_16x16x32_bf16 v[108:111], v[150:153], v[190:193], v[108:111]
	v_mfma_f32_16x16x32_bf16 v[104:107], v[158:161], v[190:193], v[104:107]
	v_mfma_f32_16x16x32_bf16 v[92:95], v[150:153], v[198:201], v[92:95]
	v_mfma_f32_16x16x32_bf16 v[88:91], v[158:161], v[198:201], v[88:91]
	v_mfma_f32_16x16x32_bf16 v[76:79], v[150:153], v[208:211], v[76:79]
	v_mfma_f32_16x16x32_bf16 v[72:75], v[158:161], v[208:211], v[72:75]
	v_mfma_f32_16x16x32_bf16 v[116:119], v[162:165], v[178:181], v[116:119]
	v_mfma_f32_16x16x32_bf16 v[112:115], v[170:173], v[178:181], v[112:115]
	v_mfma_f32_16x16x32_bf16 v[100:103], v[162:165], v[186:189], v[100:103]
	v_mfma_f32_16x16x32_bf16 v[96:99], v[170:173], v[186:189], v[96:99]
	v_mfma_f32_16x16x32_bf16 v[84:87], v[162:165], v[194:197], v[84:87]
	v_mfma_f32_16x16x32_bf16 v[80:83], v[170:173], v[194:197], v[80:83]
	v_mfma_f32_16x16x32_bf16 v[68:71], v[162:165], v[202:205], v[68:71]
	v_mfma_f32_16x16x32_bf16 v[64:67], v[170:173], v[202:205], v[64:67]
	v_mfma_f32_16x16x32_bf16 v[116:119], v[166:169], v[182:185], v[116:119]
	v_mfma_f32_16x16x32_bf16 v[112:115], v[174:177], v[182:185], v[112:115]
	v_mfma_f32_16x16x32_bf16 v[100:103], v[166:169], v[190:193], v[100:103]
	v_mfma_f32_16x16x32_bf16 v[96:99], v[174:177], v[190:193], v[96:99]
	v_mfma_f32_16x16x32_bf16 v[84:87], v[166:169], v[198:201], v[84:87]
	v_mfma_f32_16x16x32_bf16 v[80:83], v[174:177], v[198:201], v[80:83]
	v_mfma_f32_16x16x32_bf16 v[68:71], v[166:169], v[208:211], v[68:71]
	v_mfma_f32_16x16x32_bf16 v[64:67], v[174:177], v[208:211], v[64:67]
	s_barrier
	s_add_i32 s28, s59, s43
	s_mov_b32 m0, s28
	ds_read_b128 v[178:181], v149 offset:49152
	ds_read_b128 v[182:185], v149 offset:50176
	ds_read_b128 v[186:189], v149 offset:51200
	ds_read_b128 v[190:193], v149 offset:52224
	ds_read_b128 v[194:197], v149 offset:53248
	ds_read_b128 v[198:201], v149 offset:54272
	ds_read_b128 v[202:205], v149 offset:55296
	ds_read_b128 v[208:211], v149 offset:56320
	global_load_lds_dwordx4 v212, s[34:35]
	s_add_i32 m0, s28, 0x2000
	s_add_u32 s28, s34, 0x40080
	s_addc_u32 s29, s35, 0
	s_add_i32 s34, s60, s43
	global_load_lds_dwordx4 v213, s[98:99]
	s_mov_b32 m0, s34
	s_nop 0
	global_load_lds_dwordx4 v128, s[28:29]
	s_add_i32 m0, s34, 0x2000
	s_nop 0
	global_load_lds_dwordx4 v130, s[28:29]
	s_mov_b32 m0, s49
	s_nop 0
	global_load_lds_dwordx4 v212, s[36:37]
	s_mov_b32 m0, s50
	s_nop 0
	global_load_lds_dwordx4 v213, s[36:37]
	s_waitcnt vmcnt(8)
	s_waitcnt lgkmcnt(0)
	s_barrier
	s_waitcnt lgkmcnt(0)
	v_mfma_f32_16x16x32_bf16 v[60:63], v[140:143], v[178:181], v[60:63]
	v_mfma_f32_16x16x32_bf16 v[56:59], v[154:157], v[178:181], v[56:59]
	v_mfma_f32_16x16x32_bf16 v[44:47], v[140:143], v[186:189], v[44:47]
	v_mfma_f32_16x16x32_bf16 v[40:43], v[154:157], v[186:189], v[40:43]
	v_mfma_f32_16x16x32_bf16 v[28:31], v[140:143], v[194:197], v[28:31]
	v_mfma_f32_16x16x32_bf16 v[24:27], v[154:157], v[194:197], v[24:27]
	v_mfma_f32_16x16x32_bf16 v[12:15], v[140:143], v[202:205], v[12:15]
	v_mfma_f32_16x16x32_bf16 v[8:11], v[154:157], v[202:205], v[8:11]
	v_mfma_f32_16x16x32_bf16 v[60:63], v[150:153], v[182:185], v[60:63]
	v_mfma_f32_16x16x32_bf16 v[56:59], v[158:161], v[182:185], v[56:59]
	v_mfma_f32_16x16x32_bf16 v[44:47], v[150:153], v[190:193], v[44:47]
	v_mfma_f32_16x16x32_bf16 v[40:43], v[158:161], v[190:193], v[40:43]
	v_mfma_f32_16x16x32_bf16 v[28:31], v[150:153], v[198:201], v[28:31]
	v_mfma_f32_16x16x32_bf16 v[24:27], v[158:161], v[198:201], v[24:27]
	v_mfma_f32_16x16x32_bf16 v[12:15], v[150:153], v[208:211], v[12:15]
	v_mfma_f32_16x16x32_bf16 v[8:11], v[158:161], v[208:211], v[8:11]
	v_mfma_f32_16x16x32_bf16 v[52:55], v[162:165], v[178:181], v[52:55]
	v_mfma_f32_16x16x32_bf16 v[48:51], v[170:173], v[178:181], v[48:51]
	v_mfma_f32_16x16x32_bf16 v[36:39], v[162:165], v[186:189], v[36:39]
	v_mfma_f32_16x16x32_bf16 v[32:35], v[170:173], v[186:189], v[32:35]
	v_mfma_f32_16x16x32_bf16 v[20:23], v[162:165], v[194:197], v[20:23]
	v_mfma_f32_16x16x32_bf16 v[16:19], v[170:173], v[194:197], v[16:19]
	v_mfma_f32_16x16x32_bf16 v[4:7], v[162:165], v[202:205], v[4:7]
	v_mfma_f32_16x16x32_bf16 v[0:3], v[170:173], v[202:205], v[0:3]
	v_mfma_f32_16x16x32_bf16 v[52:55], v[166:169], v[182:185], v[52:55]
	v_mfma_f32_16x16x32_bf16 v[48:51], v[174:177], v[182:185], v[48:51]
	v_mfma_f32_16x16x32_bf16 v[36:39], v[166:169], v[190:193], v[36:39]
	v_mfma_f32_16x16x32_bf16 v[32:35], v[174:177], v[190:193], v[32:35]
	v_mfma_f32_16x16x32_bf16 v[20:23], v[166:169], v[198:201], v[20:23]
	v_mfma_f32_16x16x32_bf16 v[16:19], v[174:177], v[198:201], v[16:19]
	v_mfma_f32_16x16x32_bf16 v[4:7], v[166:169], v[208:211], v[4:7]
	v_mfma_f32_16x16x32_bf16 v[0:3], v[174:177], v[208:211], v[0:3]
	s_barrier
	s_add_i32 s58, s58, 2
	s_add_u32 s56, s56, 0x100
	s_addc_u32 s57, s57, 0
	s_cmp_gt_u32 s58, 13
	s_mov_b64 s[28:29], s[30:31]
	s_cbranch_scc0 .LBB0_606
	s_and_b64 vcc, exec, s[16:17]
	s_cbranch_vccz .LBB0_609
	s_barrier

.LBB0_699:
	ds_read_b128 v[144:147], v151
	ds_read_b128 v[156:159], v151 offset:1024
	ds_read_b128 v[160:163], v151 offset:2048
	ds_read_b128 v[164:167], v151 offset:3072
	ds_read_b128 v[168:171], v152
	ds_read_b128 v[172:175], v152 offset:1024
	ds_read_b128 v[176:179], v152 offset:2048
	ds_read_b128 v[180:183], v152 offset:3072
	s_add_u32 s28, s26, 0xfffc0080
	s_addc_u32 s29, s27, -1
	s_cmp_eq_u32 s53, 12
	s_cselect_b32 s31, s21, s29
	s_cselect_b32 s30, s49, s28
	s_cselect_b32 s29, s19, s52
	s_cselect_b32 s28, s50, s51
	s_add_i32 m0, s39, 0xc000
	ds_read_b128 v[184:187], v153
	ds_read_b128 v[188:191], v153 offset:1024
	ds_read_b128 v[192:195], v153 offset:2048
	ds_read_b128 v[196:199], v153 offset:3072
	ds_read_b128 v[200:203], v153 offset:4096
	ds_read_b128 v[208:211], v153 offset:5120
	ds_read_b128 v[212:215], v153 offset:6144
	ds_read_b128 v[216:219], v153 offset:7168
	global_load_lds_dwordx4 v138, s[26:27]
	s_add_i32 m0, s39, 0xe000
	s_nop 0
	global_load_lds_dwordx4 v136, s[26:27]
	s_waitcnt vmcnt(8)
	s_waitcnt lgkmcnt(0)
	s_barrier
	s_waitcnt lgkmcnt(0)
	v_mfma_f32_16x16x32_bf16 v[124:127], v[144:147], v[184:187], v[124:127]
	v_mfma_f32_16x16x32_bf16 v[120:123], v[160:163], v[184:187], v[120:123]
	v_mfma_f32_16x16x32_bf16 v[108:111], v[144:147], v[192:195], v[108:111]
	v_mfma_f32_16x16x32_bf16 v[104:107], v[160:163], v[192:195], v[104:107]
	v_mfma_f32_16x16x32_bf16 v[92:95], v[144:147], v[200:203], v[92:95]
	v_mfma_f32_16x16x32_bf16 v[88:91], v[160:163], v[200:203], v[88:91]
	v_mfma_f32_16x16x32_bf16 v[76:79], v[144:147], v[212:215], v[76:79]
	v_mfma_f32_16x16x32_bf16 v[72:75], v[160:163], v[212:215], v[72:75]
	v_mfma_f32_16x16x32_bf16 v[124:127], v[156:159], v[188:191], v[124:127]
	v_mfma_f32_16x16x32_bf16 v[120:123], v[164:167], v[188:191], v[120:123]
	v_mfma_f32_16x16x32_bf16 v[108:111], v[156:159], v[196:199], v[108:111]
	v_mfma_f32_16x16x32_bf16 v[104:107], v[164:167], v[196:199], v[104:107]
	v_mfma_f32_16x16x32_bf16 v[92:95], v[156:159], v[208:211], v[92:95]
	v_mfma_f32_16x16x32_bf16 v[88:91], v[164:167], v[208:211], v[88:91]
	v_mfma_f32_16x16x32_bf16 v[76:79], v[156:159], v[216:219], v[76:79]
	v_mfma_f32_16x16x32_bf16 v[72:75], v[164:167], v[216:219], v[72:75]
	v_mfma_f32_16x16x32_bf16 v[116:119], v[168:171], v[184:187], v[116:119]
	v_mfma_f32_16x16x32_bf16 v[112:115], v[176:179], v[184:187], v[112:115]
	v_mfma_f32_16x16x32_bf16 v[100:103], v[168:171], v[192:195], v[100:103]
	v_mfma_f32_16x16x32_bf16 v[96:99], v[176:179], v[192:195], v[96:99]
	v_mfma_f32_16x16x32_bf16 v[84:87], v[168:171], v[200:203], v[84:87]
	v_mfma_f32_16x16x32_bf16 v[80:83], v[176:179], v[200:203], v[80:83]
	v_mfma_f32_16x16x32_bf16 v[68:71], v[168:171], v[212:215], v[68:71]
	v_mfma_f32_16x16x32_bf16 v[64:67], v[176:179], v[212:215], v[64:67]
	v_mfma_f32_16x16x32_bf16 v[116:119], v[172:175], v[188:191], v[116:119]
	v_mfma_f32_16x16x32_bf16 v[112:115], v[180:183], v[188:191], v[112:115]
	v_mfma_f32_16x16x32_bf16 v[100:103], v[172:175], v[196:199], v[100:103]
	v_mfma_f32_16x16x32_bf16 v[96:99], v[180:183], v[196:199], v[96:99]
	v_mfma_f32_16x16x32_bf16 v[84:87], v[172:175], v[208:211], v[84:87]
	v_mfma_f32_16x16x32_bf16 v[80:83], v[180:183], v[208:211], v[80:83]
	v_mfma_f32_16x16x32_bf16 v[68:71], v[172:175], v[216:219], v[68:71]
	v_mfma_f32_16x16x32_bf16 v[64:67], v[180:183], v[216:219], v[64:67]
	s_barrier
	s_add_i32 s54, s46, s38
	s_mov_b32 m0, s54
	ds_read_b128 v[184:187], v153 offset:16384
	ds_read_b128 v[188:191], v153 offset:17408
	ds_read_b128 v[192:195], v153 offset:18432
	ds_read_b128 v[196:199], v153 offset:19456
	ds_read_b128 v[200:203], v153 offset:20480
	ds_read_b128 v[208:211], v153 offset:21504
	ds_read_b128 v[212:215], v153 offset:22528
	ds_read_b128 v[216:219], v153 offset:23552
	global_load_lds_dwordx4 v130, s[28:29]
	s_add_i32 m0, s54, 0x2000
	s_add_u32 s54, s28, 0x40000
	s_mov_b64 s[98:99], s[28:29]
	s_addc_u32 s55, s29, 0
	s_add_i32 s56, s47, s38
	global_load_lds_dwordx4 v134, s[28:29]
	s_mov_b32 m0, s56
	s_mov_b64 s[100:101], s[30:31]
	global_load_lds_dwordx4 v130, s[54:55]
	s_add_i32 m0, s56, 0x2000
	s_nop 0
	global_load_lds_dwordx4 v134, s[54:55]
	s_mov_b32 m0, s39
	s_nop 0
	global_load_lds_dwordx4 v128, s[30:31]
	s_mov_b32 m0, s40
	s_nop 0
	global_load_lds_dwordx4 v132, s[30:31]
	s_waitcnt vmcnt(8)
	s_waitcnt lgkmcnt(0)
	s_barrier
	s_waitcnt lgkmcnt(0)
	s_nop 0
	v_mfma_f32_16x16x32_bf16 v[60:63], v[144:147], v[184:187], v[60:63]
	v_mfma_f32_16x16x32_bf16 v[56:59], v[160:163], v[184:187], v[56:59]
	v_mfma_f32_16x16x32_bf16 v[44:47], v[144:147], v[192:195], v[44:47]
	v_mfma_f32_16x16x32_bf16 v[40:43], v[160:163], v[192:195], v[40:43]
	v_mfma_f32_16x16x32_bf16 v[28:31], v[144:147], v[200:203], v[28:31]
	v_mfma_f32_16x16x32_bf16 v[24:27], v[160:163], v[200:203], v[24:27]
	v_mfma_f32_16x16x32_bf16 v[12:15], v[144:147], v[212:215], v[12:15]
	v_mfma_f32_16x16x32_bf16 v[8:11], v[160:163], v[212:215], v[8:11]
	v_mfma_f32_16x16x32_bf16 v[60:63], v[156:159], v[188:191], v[60:63]
	v_mfma_f32_16x16x32_bf16 v[56:59], v[164:167], v[188:191], v[56:59]
	v_mfma_f32_16x16x32_bf16 v[44:47], v[156:159], v[196:199], v[44:47]
	v_mfma_f32_16x16x32_bf16 v[40:43], v[164:167], v[196:199], v[40:43]
	v_mfma_f32_16x16x32_bf16 v[28:31], v[156:159], v[208:211], v[28:31]
	v_mfma_f32_16x16x32_bf16 v[24:27], v[164:167], v[208:211], v[24:27]
	v_mfma_f32_16x16x32_bf16 v[12:15], v[156:159], v[216:219], v[12:15]
	v_mfma_f32_16x16x32_bf16 v[8:11], v[164:167], v[216:219], v[8:11]
	v_mfma_f32_16x16x32_bf16 v[52:55], v[168:171], v[184:187], v[52:55]
	v_mfma_f32_16x16x32_bf16 v[48:51], v[176:179], v[184:187], v[48:51]
	v_mfma_f32_16x16x32_bf16 v[36:39], v[168:171], v[192:195], v[36:39]
	v_mfma_f32_16x16x32_bf16 v[32:35], v[176:179], v[192:195], v[32:35]
	v_mfma_f32_16x16x32_bf16 v[20:23], v[168:171], v[200:203], v[20:23]
	v_mfma_f32_16x16x32_bf16 v[16:19], v[176:179], v[200:203], v[16:19]
	v_mfma_f32_16x16x32_bf16 v[4:7], v[168:171], v[212:215], v[4:7]
	v_mfma_f32_16x16x32_bf16 v[0:3], v[176:179], v[212:215], v[0:3]
	v_mfma_f32_16x16x32_bf16 v[52:55], v[172:175], v[188:191], v[52:55]
	v_mfma_f32_16x16x32_bf16 v[48:51], v[180:183], v[188:191], v[48:51]
	v_mfma_f32_16x16x32_bf16 v[36:39], v[172:175], v[196:199], v[36:39]
	v_mfma_f32_16x16x32_bf16 v[32:35], v[180:183], v[196:199], v[32:35]
	v_mfma_f32_16x16x32_bf16 v[20:23], v[172:175], v[208:211], v[20:23]
	v_mfma_f32_16x16x32_bf16 v[16:19], v[180:183], v[208:211], v[16:19]
	v_mfma_f32_16x16x32_bf16 v[4:7], v[172:175], v[216:219], v[4:7]
	v_mfma_f32_16x16x32_bf16 v[0:3], v[180:183], v[216:219], v[0:3]
	s_barrier
	s_add_i32 s54, 0, 0x18000
	v_add_u32_e32 v155, s54, v149
	s_add_i32 s55, 0, 0x1c000
	ds_read_b128 v[144:147], v155
	ds_read_b128 v[156:159], v155 offset:1024
	ds_read_b128 v[160:163], v155 offset:2048
	ds_read_b128 v[164:167], v155 offset:3072
	v_add_u32_e32 v155, s55, v149
	ds_read_b128 v[168:171], v155
	ds_read_b128 v[172:175], v155 offset:1024
	ds_read_b128 v[176:179], v155 offset:2048
	ds_read_b128 v[180:183], v155 offset:3072
	s_add_u32 s30, s30, 0x40000
	s_addc_u32 s31, s31, 0
	s_mov_b32 m0, s41
	ds_read_b128 v[184:187], v153 offset:32768
	ds_read_b128 v[188:191], v153 offset:33792
	ds_read_b128 v[192:195], v153 offset:34816
	ds_read_b128 v[196:199], v153 offset:35840
	ds_read_b128 v[200:203], v153 offset:36864
	ds_read_b128 v[208:211], v153 offset:37888
	ds_read_b128 v[212:215], v153 offset:38912
	ds_read_b128 v[216:219], v153 offset:39936
	global_load_lds_dwordx4 v128, s[30:31]
	s_mov_b32 m0, s42
	s_nop 0
	global_load_lds_dwordx4 v132, s[30:31]
	s_waitcnt vmcnt(8)
	s_waitcnt lgkmcnt(0)
	s_barrier
	s_waitcnt lgkmcnt(0)
	s_nop 0
	v_mfma_f32_16x16x32_bf16 v[124:127], v[144:147], v[184:187], v[124:127]
	v_mfma_f32_16x16x32_bf16 v[120:123], v[160:163], v[184:187], v[120:123]
	v_mfma_f32_16x16x32_bf16 v[108:111], v[144:147], v[192:195], v[108:111]
	v_mfma_f32_16x16x32_bf16 v[104:107], v[160:163], v[192:195], v[104:107]
	v_mfma_f32_16x16x32_bf16 v[92:95], v[144:147], v[200:203], v[92:95]
	v_mfma_f32_16x16x32_bf16 v[88:91], v[160:163], v[200:203], v[88:91]
	v_mfma_f32_16x16x32_bf16 v[76:79], v[144:147], v[212:215], v[76:79]
	v_mfma_f32_16x16x32_bf16 v[72:75], v[160:163], v[212:215], v[72:75]
	v_mfma_f32_16x16x32_bf16 v[124:127], v[156:159], v[188:191], v[124:127]
	v_mfma_f32_16x16x32_bf16 v[120:123], v[164:167], v[188:191], v[120:123]
	v_mfma_f32_16x16x32_bf16 v[108:111], v[156:159], v[196:199], v[108:111]
	v_mfma_f32_16x16x32_bf16 v[104:107], v[164:167], v[196:199], v[104:107]
	v_mfma_f32_16x16x32_bf16 v[92:95], v[156:159], v[208:211], v[92:95]
	v_mfma_f32_16x16x32_bf16 v[88:91], v[164:167], v[208:211], v[88:91]
	v_mfma_f32_16x16x32_bf16 v[76:79], v[156:159], v[216:219], v[76:79]
	v_mfma_f32_16x16x32_bf16 v[72:75], v[164:167], v[216:219], v[72:75]
	v_mfma_f32_16x16x32_bf16 v[116:119], v[168:171], v[184:187], v[116:119]
	v_mfma_f32_16x16x32_bf16 v[112:115], v[176:179], v[184:187], v[112:115]
	v_mfma_f32_16x16x32_bf16 v[100:103], v[168:171], v[192:195], v[100:103]
	v_mfma_f32_16x16x32_bf16 v[96:99], v[176:179], v[192:195], v[96:99]
	v_mfma_f32_16x16x32_bf16 v[84:87], v[168:171], v[200:203], v[84:87]
	v_mfma_f32_16x16x32_bf16 v[80:83], v[176:179], v[200:203], v[80:83]
	v_mfma_f32_16x16x32_bf16 v[68:71], v[168:171], v[212:215], v[68:71]
	v_mfma_f32_16x16x32_bf16 v[64:67], v[176:179], v[212:215], v[64:67]
	v_mfma_f32_16x16x32_bf16 v[116:119], v[172:175], v[188:191], v[116:119]
	v_mfma_f32_16x16x32_bf16 v[112:115], v[180:183], v[188:191], v[112:115]
	v_mfma_f32_16x16x32_bf16 v[100:103], v[172:175], v[196:199], v[100:103]
	v_mfma_f32_16x16x32_bf16 v[96:99], v[180:183], v[196:199], v[96:99]
	v_mfma_f32_16x16x32_bf16 v[84:87], v[172:175], v[208:211], v[84:87]
	v_mfma_f32_16x16x32_bf16 v[80:83], v[180:183], v[208:211], v[80:83]
	v_mfma_f32_16x16x32_bf16 v[68:71], v[172:175], v[216:219], v[68:71]
	v_mfma_f32_16x16x32_bf16 v[64:67], v[180:183], v[216:219], v[64:67]
	s_barrier
	s_add_i32 s30, s54, s38
	s_mov_b32 m0, s30
	ds_read_b128 v[184:187], v153 offset:49152
	ds_read_b128 v[188:191], v153 offset:50176
	ds_read_b128 v[192:195], v153 offset:51200
	ds_read_b128 v[196:199], v153 offset:52224
	ds_read_b128 v[200:203], v153 offset:53248
	ds_read_b128 v[208:211], v153 offset:54272
	ds_read_b128 v[212:215], v153 offset:55296
	ds_read_b128 v[216:219], v153 offset:56320
	global_load_lds_dwordx4 v205, s[28:29]
	s_add_i32 m0, s30, 0x2000
	s_add_u32 s28, s28, 0x40080
	s_addc_u32 s29, s29, 0
	s_add_i32 s30, s55, s38
	global_load_lds_dwordx4 v221, s[98:99]
	s_mov_b32 m0, s30
	s_nop 0
	global_load_lds_dwordx4 v130, s[28:29]
	s_add_i32 m0, s30, 0x2000
	s_nop 0
	global_load_lds_dwordx4 v134, s[28:29]
	s_mov_b32 m0, s44
	s_nop 0
	global_load_lds_dwordx4 v204, s[100:101]
	s_mov_b32 m0, s45
	s_nop 0
	global_load_lds_dwordx4 v220, s[100:101]
	s_waitcnt vmcnt(8)
	s_waitcnt lgkmcnt(0)
	s_barrier
	s_waitcnt lgkmcnt(0)
	v_mfma_f32_16x16x32_bf16 v[60:63], v[144:147], v[184:187], v[60:63]
	v_mfma_f32_16x16x32_bf16 v[56:59], v[160:163], v[184:187], v[56:59]
	v_mfma_f32_16x16x32_bf16 v[44:47], v[144:147], v[192:195], v[44:47]
	v_mfma_f32_16x16x32_bf16 v[40:43], v[160:163], v[192:195], v[40:43]
	v_mfma_f32_16x16x32_bf16 v[28:31], v[144:147], v[200:203], v[28:31]
	v_mfma_f32_16x16x32_bf16 v[24:27], v[160:163], v[200:203], v[24:27]
	v_mfma_f32_16x16x32_bf16 v[12:15], v[144:147], v[212:215], v[12:15]
	v_mfma_f32_16x16x32_bf16 v[8:11], v[160:163], v[212:215], v[8:11]
	v_mfma_f32_16x16x32_bf16 v[60:63], v[156:159], v[188:191], v[60:63]
	v_mfma_f32_16x16x32_bf16 v[56:59], v[164:167], v[188:191], v[56:59]
	v_mfma_f32_16x16x32_bf16 v[44:47], v[156:159], v[196:199], v[44:47]
	v_mfma_f32_16x16x32_bf16 v[40:43], v[164:167], v[196:199], v[40:43]
	v_mfma_f32_16x16x32_bf16 v[28:31], v[156:159], v[208:211], v[28:31]
	v_mfma_f32_16x16x32_bf16 v[24:27], v[164:167], v[208:211], v[24:27]
	v_mfma_f32_16x16x32_bf16 v[12:15], v[156:159], v[216:219], v[12:15]
	v_mfma_f32_16x16x32_bf16 v[8:11], v[164:167], v[216:219], v[8:11]
	v_mfma_f32_16x16x32_bf16 v[52:55], v[168:171], v[184:187], v[52:55]
	v_mfma_f32_16x16x32_bf16 v[48:51], v[176:179], v[184:187], v[48:51]
	v_mfma_f32_16x16x32_bf16 v[36:39], v[168:171], v[192:195], v[36:39]
	v_mfma_f32_16x16x32_bf16 v[32:35], v[176:179], v[192:195], v[32:35]
	v_mfma_f32_16x16x32_bf16 v[20:23], v[168:171], v[200:203], v[20:23]
	v_mfma_f32_16x16x32_bf16 v[16:19], v[176:179], v[200:203], v[16:19]
	v_mfma_f32_16x16x32_bf16 v[4:7], v[168:171], v[212:215], v[4:7]
	v_mfma_f32_16x16x32_bf16 v[0:3], v[176:179], v[212:215], v[0:3]
	v_mfma_f32_16x16x32_bf16 v[52:55], v[172:175], v[188:191], v[52:55]
	v_mfma_f32_16x16x32_bf16 v[48:51], v[180:183], v[188:191], v[48:51]
	v_mfma_f32_16x16x32_bf16 v[36:39], v[172:175], v[196:199], v[36:39]
	v_mfma_f32_16x16x32_bf16 v[32:35], v[180:183], v[196:199], v[32:35]
	v_mfma_f32_16x16x32_bf16 v[20:23], v[172:175], v[208:211], v[20:23]
	v_mfma_f32_16x16x32_bf16 v[16:19], v[180:183], v[208:211], v[16:19]
	v_mfma_f32_16x16x32_bf16 v[4:7], v[172:175], v[216:219], v[4:7]
	v_mfma_f32_16x16x32_bf16 v[0:3], v[180:183], v[216:219], v[0:3]
	s_barrier
	s_add_i32 s53, s53, 2
	s_add_u32 s51, s51, 0x100
	s_addc_u32 s52, s52, 0
	s_add_u32 s26, s26, 0x100
	s_addc_u32 s27, s27, 0
	s_cmp_gt_u32 s53, 13
	s_cbranch_scc0 .LBB0_699
	s_and_b64 vcc, exec, s[16:17]
	s_cbranch_vccz .LBB0_702
	s_barrier

.LBB0_778:
	ds_read_b128 v[140:143], v147
	ds_read_b128 v[150:153], v147 offset:1024
	ds_read_b128 v[154:157], v147 offset:2048
	ds_read_b128 v[158:161], v147 offset:3072
	ds_read_b128 v[162:165], v148
	ds_read_b128 v[166:169], v148 offset:1024
	ds_read_b128 v[170:173], v148 offset:2048
	ds_read_b128 v[174:177], v148 offset:3072
	s_add_u32 s30, s28, 0x100
	s_addc_u32 s31, s29, 0
	s_cmp_eq_u32 s58, 60
	s_cselect_b32 s37, s21, s31
	s_cselect_b32 s36, s27, s30
	s_cselect_b32 s35, s19, s57
	s_cselect_b32 s34, s55, s56
	s_add_i32 m0, s44, 0xc000
	ds_read_b128 v[178:181], v149
	ds_read_b128 v[182:185], v149 offset:1024
	ds_read_b128 v[186:189], v149 offset:2048
	ds_read_b128 v[190:193], v149 offset:3072
	ds_read_b128 v[194:197], v149 offset:4096
	ds_read_b128 v[198:201], v149 offset:5120
	ds_read_b128 v[202:205], v149 offset:6144
	ds_read_b128 v[208:211], v149 offset:7168
	global_load_lds_dwordx4 v134, s[28:29]
	s_add_i32 m0, s44, 0xe000
	s_nop 0
	global_load_lds_dwordx4 v132, s[28:29]
	s_waitcnt vmcnt(8)
	s_waitcnt lgkmcnt(0)
	s_barrier
	s_waitcnt lgkmcnt(0)
	v_mfma_f32_16x16x32_bf16 v[124:127], v[140:143], v[178:181], v[124:127]
	v_mfma_f32_16x16x32_bf16 v[120:123], v[154:157], v[178:181], v[120:123]
	v_mfma_f32_16x16x32_bf16 v[108:111], v[140:143], v[186:189], v[108:111]
	v_mfma_f32_16x16x32_bf16 v[104:107], v[154:157], v[186:189], v[104:107]
	v_mfma_f32_16x16x32_bf16 v[92:95], v[140:143], v[194:197], v[92:95]
	v_mfma_f32_16x16x32_bf16 v[88:91], v[154:157], v[194:197], v[88:91]
	v_mfma_f32_16x16x32_bf16 v[76:79], v[140:143], v[202:205], v[76:79]
	v_mfma_f32_16x16x32_bf16 v[72:75], v[154:157], v[202:205], v[72:75]
	v_mfma_f32_16x16x32_bf16 v[124:127], v[150:153], v[182:185], v[124:127]
	v_mfma_f32_16x16x32_bf16 v[120:123], v[158:161], v[182:185], v[120:123]
	v_mfma_f32_16x16x32_bf16 v[108:111], v[150:153], v[190:193], v[108:111]
	v_mfma_f32_16x16x32_bf16 v[104:107], v[158:161], v[190:193], v[104:107]
	v_mfma_f32_16x16x32_bf16 v[92:95], v[150:153], v[198:201], v[92:95]
	v_mfma_f32_16x16x32_bf16 v[88:91], v[158:161], v[198:201], v[88:91]
	v_mfma_f32_16x16x32_bf16 v[76:79], v[150:153], v[208:211], v[76:79]
	v_mfma_f32_16x16x32_bf16 v[72:75], v[158:161], v[208:211], v[72:75]
	v_mfma_f32_16x16x32_bf16 v[116:119], v[162:165], v[178:181], v[116:119]
	v_mfma_f32_16x16x32_bf16 v[112:115], v[170:173], v[178:181], v[112:115]
	v_mfma_f32_16x16x32_bf16 v[100:103], v[162:165], v[186:189], v[100:103]
	v_mfma_f32_16x16x32_bf16 v[96:99], v[170:173], v[186:189], v[96:99]
	v_mfma_f32_16x16x32_bf16 v[84:87], v[162:165], v[194:197], v[84:87]
	v_mfma_f32_16x16x32_bf16 v[80:83], v[170:173], v[194:197], v[80:83]
	v_mfma_f32_16x16x32_bf16 v[68:71], v[162:165], v[202:205], v[68:71]
	v_mfma_f32_16x16x32_bf16 v[64:67], v[170:173], v[202:205], v[64:67]
	v_mfma_f32_16x16x32_bf16 v[116:119], v[166:169], v[182:185], v[116:119]
	v_mfma_f32_16x16x32_bf16 v[112:115], v[174:177], v[182:185], v[112:115]
	v_mfma_f32_16x16x32_bf16 v[100:103], v[166:169], v[190:193], v[100:103]
	v_mfma_f32_16x16x32_bf16 v[96:99], v[174:177], v[190:193], v[96:99]
	v_mfma_f32_16x16x32_bf16 v[84:87], v[166:169], v[198:201], v[84:87]
	v_mfma_f32_16x16x32_bf16 v[80:83], v[174:177], v[198:201], v[80:83]
	v_mfma_f32_16x16x32_bf16 v[68:71], v[166:169], v[208:211], v[68:71]
	v_mfma_f32_16x16x32_bf16 v[64:67], v[174:177], v[208:211], v[64:67]
	s_barrier
	s_add_i32 s28, s52, s43
	s_mov_b32 m0, s28
	ds_read_b128 v[178:181], v149 offset:16384
	ds_read_b128 v[182:185], v149 offset:17408
	ds_read_b128 v[186:189], v149 offset:18432
	ds_read_b128 v[190:193], v149 offset:19456
	ds_read_b128 v[194:197], v149 offset:20480
	ds_read_b128 v[198:201], v149 offset:21504
	ds_read_b128 v[202:205], v149 offset:22528
	ds_read_b128 v[208:211], v149 offset:23552
	global_load_lds_dwordx4 v128, s[34:35]
	s_add_i32 m0, s28, 0x2000
	s_add_u32 s28, s34, 0x100000
	s_mov_b64 s[98:99], s[34:35]
	s_addc_u32 s29, s35, 0
	s_add_i32 s59, s53, s43
	global_load_lds_dwordx4 v130, s[34:35]
	s_mov_b32 m0, s59
	s_nop 0
	global_load_lds_dwordx4 v128, s[28:29]
	s_add_i32 m0, s59, 0x2000
	s_nop 0
	global_load_lds_dwordx4 v130, s[28:29]
	s_mov_b32 m0, s44
	s_nop 0
	global_load_lds_dwordx4 v128, s[36:37]
	s_mov_b32 m0, s45
	s_nop 0
	global_load_lds_dwordx4 v130, s[36:37]
	s_waitcnt vmcnt(8)
	s_waitcnt lgkmcnt(0)
	s_barrier
	s_waitcnt lgkmcnt(0)
	s_nop 0
	v_mfma_f32_16x16x32_bf16 v[60:63], v[140:143], v[178:181], v[60:63]
	v_mfma_f32_16x16x32_bf16 v[56:59], v[154:157], v[178:181], v[56:59]
	v_mfma_f32_16x16x32_bf16 v[44:47], v[140:143], v[186:189], v[44:47]
	v_mfma_f32_16x16x32_bf16 v[40:43], v[154:157], v[186:189], v[40:43]
	v_mfma_f32_16x16x32_bf16 v[28:31], v[140:143], v[194:197], v[28:31]
	v_mfma_f32_16x16x32_bf16 v[24:27], v[154:157], v[194:197], v[24:27]
	v_mfma_f32_16x16x32_bf16 v[12:15], v[140:143], v[202:205], v[12:15]
	v_mfma_f32_16x16x32_bf16 v[8:11], v[154:157], v[202:205], v[8:11]
	v_mfma_f32_16x16x32_bf16 v[60:63], v[150:153], v[182:185], v[60:63]
	v_mfma_f32_16x16x32_bf16 v[56:59], v[158:161], v[182:185], v[56:59]
	v_mfma_f32_16x16x32_bf16 v[44:47], v[150:153], v[190:193], v[44:47]
	v_mfma_f32_16x16x32_bf16 v[40:43], v[158:161], v[190:193], v[40:43]
	v_mfma_f32_16x16x32_bf16 v[28:31], v[150:153], v[198:201], v[28:31]
	v_mfma_f32_16x16x32_bf16 v[24:27], v[158:161], v[198:201], v[24:27]
	v_mfma_f32_16x16x32_bf16 v[12:15], v[150:153], v[208:211], v[12:15]
	v_mfma_f32_16x16x32_bf16 v[8:11], v[158:161], v[208:211], v[8:11]
	v_mfma_f32_16x16x32_bf16 v[52:55], v[162:165], v[178:181], v[52:55]
	v_mfma_f32_16x16x32_bf16 v[48:51], v[170:173], v[178:181], v[48:51]
	v_mfma_f32_16x16x32_bf16 v[36:39], v[162:165], v[186:189], v[36:39]
	v_mfma_f32_16x16x32_bf16 v[32:35], v[170:173], v[186:189], v[32:35]
	v_mfma_f32_16x16x32_bf16 v[20:23], v[162:165], v[194:197], v[20:23]
	v_mfma_f32_16x16x32_bf16 v[16:19], v[170:173], v[194:197], v[16:19]
	v_mfma_f32_16x16x32_bf16 v[4:7], v[162:165], v[202:205], v[4:7]
	v_mfma_f32_16x16x32_bf16 v[0:3], v[170:173], v[202:205], v[0:3]
	v_mfma_f32_16x16x32_bf16 v[52:55], v[166:169], v[182:185], v[52:55]
	v_mfma_f32_16x16x32_bf16 v[48:51], v[174:177], v[182:185], v[48:51]
	v_mfma_f32_16x16x32_bf16 v[36:39], v[166:169], v[190:193], v[36:39]
	v_mfma_f32_16x16x32_bf16 v[32:35], v[174:177], v[190:193], v[32:35]
	v_mfma_f32_16x16x32_bf16 v[20:23], v[166:169], v[198:201], v[20:23]
	v_mfma_f32_16x16x32_bf16 v[16:19], v[174:177], v[198:201], v[16:19]
	v_mfma_f32_16x16x32_bf16 v[4:7], v[166:169], v[208:211], v[4:7]
	v_mfma_f32_16x16x32_bf16 v[0:3], v[174:177], v[208:211], v[0:3]
	s_barrier
	s_add_i32 s59, 0, 0x18000
	s_add_i32 s60, 0, 0x1c000
	v_add_u32_e32 v158, s59, v145
	v_add_u32_e32 v174, s60, v145
	ds_read_b128 v[140:143], v158
	ds_read_b128 v[150:153], v158 offset:1024
	ds_read_b128 v[154:157], v158 offset:2048
	ds_read_b128 v[158:161], v158 offset:3072
	ds_read_b128 v[162:165], v174
	ds_read_b128 v[166:169], v174 offset:1024
	ds_read_b128 v[170:173], v174 offset:2048
	ds_read_b128 v[174:177], v174 offset:3072
	s_add_u32 s28, s36, 0x100000
	s_addc_u32 s29, s37, 0
	s_mov_b32 m0, s46
	ds_read_b128 v[178:181], v149 offset:32768
	ds_read_b128 v[182:185], v149 offset:33792
	ds_read_b128 v[186:189], v149 offset:34816
	ds_read_b128 v[190:193], v149 offset:35840
	ds_read_b128 v[194:197], v149 offset:36864
	ds_read_b128 v[198:201], v149 offset:37888
	ds_read_b128 v[202:205], v149 offset:38912
	ds_read_b128 v[208:211], v149 offset:39936
	global_load_lds_dwordx4 v128, s[28:29]
	s_mov_b32 m0, s47
	s_nop 0
	global_load_lds_dwordx4 v130, s[28:29]
	s_waitcnt vmcnt(8)
	s_waitcnt lgkmcnt(0)
	s_barrier
	s_waitcnt lgkmcnt(0)
	s_nop 0
	v_mfma_f32_16x16x32_bf16 v[124:127], v[140:143], v[178:181], v[124:127]
	v_mfma_f32_16x16x32_bf16 v[120:123], v[154:157], v[178:181], v[120:123]
	v_mfma_f32_16x16x32_bf16 v[108:111], v[140:143], v[186:189], v[108:111]
	v_mfma_f32_16x16x32_bf16 v[104:107], v[154:157], v[186:189], v[104:107]
	v_mfma_f32_16x16x32_bf16 v[92:95], v[140:143], v[194:197], v[92:95]
	v_mfma_f32_16x16x32_bf16 v[88:91], v[154:157], v[194:197], v[88:91]
	v_mfma_f32_16x16x32_bf16 v[76:79], v[140:143], v[202:205], v[76:79]
	v_mfma_f32_16x16x32_bf16 v[72:75], v[154:157], v[202:205], v[72:75]
	v_mfma_f32_16x16x32_bf16 v[124:127], v[150:153], v[182:185], v[124:127]
	v_mfma_f32_16x16x32_bf16 v[120:123], v[158:161], v[182:185], v[120:123]
	v_mfma_f32_16x16x32_bf16 v[108:111], v[150:153], v[190:193], v[108:111]
	v_mfma_f32_16x16x32_bf16 v[104:107], v[158:161], v[190:193], v[104:107]
	v_mfma_f32_16x16x32_bf16 v[92:95], v[150:153], v[198:201], v[92:95]
	v_mfma_f32_16x16x32_bf16 v[88:91], v[158:161], v[198:201], v[88:91]
	v_mfma_f32_16x16x32_bf16 v[76:79], v[150:153], v[208:211], v[76:79]
	v_mfma_f32_16x16x32_bf16 v[72:75], v[158:161], v[208:211], v[72:75]
	v_mfma_f32_16x16x32_bf16 v[116:119], v[162:165], v[178:181], v[116:119]
	v_mfma_f32_16x16x32_bf16 v[112:115], v[170:173], v[178:181], v[112:115]
	v_mfma_f32_16x16x32_bf16 v[100:103], v[162:165], v[186:189], v[100:103]
	v_mfma_f32_16x16x32_bf16 v[96:99], v[170:173], v[186:189], v[96:99]
	v_mfma_f32_16x16x32_bf16 v[84:87], v[162:165], v[194:197], v[84:87]
	v_mfma_f32_16x16x32_bf16 v[80:83], v[170:173], v[194:197], v[80:83]
	v_mfma_f32_16x16x32_bf16 v[68:71], v[162:165], v[202:205], v[68:71]
	v_mfma_f32_16x16x32_bf16 v[64:67], v[170:173], v[202:205], v[64:67]
	v_mfma_f32_16x16x32_bf16 v[116:119], v[166:169], v[182:185], v[116:119]
	v_mfma_f32_16x16x32_bf16 v[112:115], v[174:177], v[182:185], v[112:115]
	v_mfma_f32_16x16x32_bf16 v[100:103], v[166:169], v[190:193], v[100:103]
	v_mfma_f32_16x16x32_bf16 v[96:99], v[174:177], v[190:193], v[96:99]
	v_mfma_f32_16x16x32_bf16 v[84:87], v[166:169], v[198:201], v[84:87]
	v_mfma_f32_16x16x32_bf16 v[80:83], v[174:177], v[198:201], v[80:83]
	v_mfma_f32_16x16x32_bf16 v[68:71], v[166:169], v[208:211], v[68:71]
	v_mfma_f32_16x16x32_bf16 v[64:67], v[174:177], v[208:211], v[64:67]
	s_barrier
	s_add_i32 s28, s59, s43
	s_mov_b32 m0, s28
	ds_read_b128 v[178:181], v149 offset:49152
	ds_read_b128 v[182:185], v149 offset:50176
	ds_read_b128 v[186:189], v149 offset:51200
	ds_read_b128 v[190:193], v149 offset:52224
	ds_read_b128 v[194:197], v149 offset:53248
	ds_read_b128 v[198:201], v149 offset:54272
	ds_read_b128 v[202:205], v149 offset:55296
	ds_read_b128 v[208:211], v149 offset:56320
	global_load_lds_dwordx4 v212, s[34:35]
	s_add_i32 m0, s28, 0x2000
	s_add_u32 s28, s34, 0x100080
	s_addc_u32 s29, s35, 0
	s_add_i32 s34, s60, s43
	global_load_lds_dwordx4 v213, s[98:99]
	s_mov_b32 m0, s34
	s_nop 0
	global_load_lds_dwordx4 v128, s[28:29]
	s_add_i32 m0, s34, 0x2000
	s_nop 0
	global_load_lds_dwordx4 v130, s[28:29]
	s_mov_b32 m0, s49
	s_nop 0
	global_load_lds_dwordx4 v212, s[36:37]
	s_mov_b32 m0, s50
	s_nop 0
	global_load_lds_dwordx4 v213, s[36:37]
	s_waitcnt vmcnt(8)
	s_waitcnt lgkmcnt(0)
	s_barrier
	s_waitcnt lgkmcnt(0)
	v_mfma_f32_16x16x32_bf16 v[60:63], v[140:143], v[178:181], v[60:63]
	v_mfma_f32_16x16x32_bf16 v[56:59], v[154:157], v[178:181], v[56:59]
	v_mfma_f32_16x16x32_bf16 v[44:47], v[140:143], v[186:189], v[44:47]
	v_mfma_f32_16x16x32_bf16 v[40:43], v[154:157], v[186:189], v[40:43]
	v_mfma_f32_16x16x32_bf16 v[28:31], v[140:143], v[194:197], v[28:31]
	v_mfma_f32_16x16x32_bf16 v[24:27], v[154:157], v[194:197], v[24:27]
	v_mfma_f32_16x16x32_bf16 v[12:15], v[140:143], v[202:205], v[12:15]
	v_mfma_f32_16x16x32_bf16 v[8:11], v[154:157], v[202:205], v[8:11]
	v_mfma_f32_16x16x32_bf16 v[60:63], v[150:153], v[182:185], v[60:63]
	v_mfma_f32_16x16x32_bf16 v[56:59], v[158:161], v[182:185], v[56:59]
	v_mfma_f32_16x16x32_bf16 v[44:47], v[150:153], v[190:193], v[44:47]
	v_mfma_f32_16x16x32_bf16 v[40:43], v[158:161], v[190:193], v[40:43]
	v_mfma_f32_16x16x32_bf16 v[28:31], v[150:153], v[198:201], v[28:31]
	v_mfma_f32_16x16x32_bf16 v[24:27], v[158:161], v[198:201], v[24:27]
	v_mfma_f32_16x16x32_bf16 v[12:15], v[150:153], v[208:211], v[12:15]
	v_mfma_f32_16x16x32_bf16 v[8:11], v[158:161], v[208:211], v[8:11]
	v_mfma_f32_16x16x32_bf16 v[52:55], v[162:165], v[178:181], v[52:55]
	v_mfma_f32_16x16x32_bf16 v[48:51], v[170:173], v[178:181], v[48:51]
	v_mfma_f32_16x16x32_bf16 v[36:39], v[162:165], v[186:189], v[36:39]
	v_mfma_f32_16x16x32_bf16 v[32:35], v[170:173], v[186:189], v[32:35]
	v_mfma_f32_16x16x32_bf16 v[20:23], v[162:165], v[194:197], v[20:23]
	v_mfma_f32_16x16x32_bf16 v[16:19], v[170:173], v[194:197], v[16:19]
	v_mfma_f32_16x16x32_bf16 v[4:7], v[162:165], v[202:205], v[4:7]
	v_mfma_f32_16x16x32_bf16 v[0:3], v[170:173], v[202:205], v[0:3]
	v_mfma_f32_16x16x32_bf16 v[52:55], v[166:169], v[182:185], v[52:55]
	v_mfma_f32_16x16x32_bf16 v[48:51], v[174:177], v[182:185], v[48:51]
	v_mfma_f32_16x16x32_bf16 v[36:39], v[166:169], v[190:193], v[36:39]
	v_mfma_f32_16x16x32_bf16 v[32:35], v[174:177], v[190:193], v[32:35]
	v_mfma_f32_16x16x32_bf16 v[20:23], v[166:169], v[198:201], v[20:23]
	v_mfma_f32_16x16x32_bf16 v[16:19], v[174:177], v[198:201], v[16:19]
	v_mfma_f32_16x16x32_bf16 v[4:7], v[166:169], v[208:211], v[4:7]
	v_mfma_f32_16x16x32_bf16 v[0:3], v[174:177], v[208:211], v[0:3]
	s_barrier
	s_add_i32 s58, s58, 2
	s_add_u32 s56, s56, 0x100
	s_addc_u32 s57, s57, 0
	s_cmp_gt_u32 s58, 61
	s_mov_b64 s[28:29], s[30:31]
	s_cbranch_scc0 .LBB0_778
	s_and_b64 vcc, exec, s[16:17]
	s_cbranch_vccz .LBB0_781
	s_barrier

.LBB0_817:
	ds_read_b128 v[0:3], v139
	ds_read_b128 v[4:7], v139 offset:1024
	ds_read_b128 v[8:11], v139 offset:2048
	ds_read_b128 v[12:15], v139 offset:3072
	ds_read_b128 v[16:19], v140
	ds_read_b128 v[20:23], v140 offset:1024
	ds_read_b128 v[24:27], v140 offset:2048
	ds_read_b128 v[28:31], v140 offset:3072
	s_ashr_i32 s29, s28, 31
	s_lshl_b64 s[30:31], s[28:29], 17
	s_add_u32 s30, s46, s30
	s_addc_u32 s31, s47, s31
	s_and_b64 s[34:35], s[4:5], exec
	s_cselect_b32 s45, s31, s39
	s_cselect_b32 s44, s30, s38
	s_ashr_i32 s27, s26, 31
	s_lshl_b64 s[34:35], s[26:27], 17
	s_add_u32 s34, s48, s34
	s_addc_u32 s35, s49, s35
	s_and_b64 s[42:43], s[4:5], exec
	s_cselect_b32 s43, s35, s41
	s_cselect_b32 s42, s34, s40
	s_add_u32 s64, s38, 0x10080
	s_addc_u32 s65, s39, 0
	s_add_i32 s67, s37, 0xc000
	v_lshl_add_u64 v[64:65], s[64:65], 0, v[128:129]
	s_mov_b32 m0, s67
	s_add_i32 s27, s37, 0xe000
	ds_read_b128 v[32:35], v141
	ds_read_b128 v[36:39], v141 offset:1024
	ds_read_b128 v[40:43], v141 offset:2048
	ds_read_b128 v[44:47], v141 offset:3072
	ds_read_b128 v[48:51], v141 offset:4096
	ds_read_b128 v[52:55], v141 offset:5120
	ds_read_b128 v[56:59], v141 offset:6144
	ds_read_b128 v[60:63], v141 offset:7168
	global_load_lds_dwordx4 v[64:65], off
	v_lshl_add_u64 v[64:65], s[64:65], 0, v[130:131]
	s_mov_b32 m0, s27
	s_nop 0
	global_load_lds_dwordx4 v[64:65], off
	s_waitcnt vmcnt(8)
	s_waitcnt lgkmcnt(0)
	s_barrier
	s_waitcnt lgkmcnt(0)
	v_mfma_f32_16x16x32_bf16 v[64:67], v[0:3], v[32:35], 0
	v_mfma_f32_16x16x32_bf16 v[68:71], v[8:11], v[32:35], 0
	v_mfma_f32_16x16x32_bf16 v[72:75], v[0:3], v[40:43], 0
	v_mfma_f32_16x16x32_bf16 v[76:79], v[8:11], v[40:43], 0
	v_mfma_f32_16x16x32_bf16 v[80:83], v[0:3], v[48:51], 0
	v_mfma_f32_16x16x32_bf16 v[84:87], v[8:11], v[48:51], 0
	v_mfma_f32_16x16x32_bf16 v[88:91], v[0:3], v[56:59], 0
	v_mfma_f32_16x16x32_bf16 v[92:95], v[8:11], v[56:59], 0
	v_mfma_f32_16x16x32_bf16 v[64:67], v[4:7], v[36:39], v[64:67]
	v_mfma_f32_16x16x32_bf16 v[68:71], v[12:15], v[36:39], v[68:71]
	v_mfma_f32_16x16x32_bf16 v[72:75], v[4:7], v[44:47], v[72:75]
	v_mfma_f32_16x16x32_bf16 v[76:79], v[12:15], v[44:47], v[76:79]
	v_mfma_f32_16x16x32_bf16 v[80:83], v[4:7], v[52:55], v[80:83]
	v_mfma_f32_16x16x32_bf16 v[84:87], v[12:15], v[52:55], v[84:87]
	v_mfma_f32_16x16x32_bf16 v[88:91], v[4:7], v[60:63], v[88:91]
	v_mfma_f32_16x16x32_bf16 v[92:95], v[12:15], v[60:63], v[92:95]
	v_mfma_f32_16x16x32_bf16 v[96:99], v[16:19], v[32:35], 0
	v_mfma_f32_16x16x32_bf16 v[32:35], v[24:27], v[32:35], 0
	v_mfma_f32_16x16x32_bf16 v[96:99], v[20:23], v[36:39], v[96:99]
	v_mfma_f32_16x16x32_bf16 v[32:35], v[28:31], v[36:39], v[32:35]
	v_mfma_f32_16x16x32_bf16 v[36:39], v[16:19], v[40:43], 0
	v_mfma_f32_16x16x32_bf16 v[40:43], v[24:27], v[40:43], 0
	v_mfma_f32_16x16x32_bf16 v[36:39], v[20:23], v[44:47], v[36:39]
	v_mfma_f32_16x16x32_bf16 v[40:43], v[28:31], v[44:47], v[40:43]
	v_mfma_f32_16x16x32_bf16 v[44:47], v[16:19], v[48:51], 0
	v_mfma_f32_16x16x32_bf16 v[48:51], v[24:27], v[48:51], 0
	v_mfma_f32_16x16x32_bf16 v[44:47], v[20:23], v[52:55], v[44:47]
	v_mfma_f32_16x16x32_bf16 v[48:51], v[28:31], v[52:55], v[48:51]
	v_mfma_f32_16x16x32_bf16 v[52:55], v[16:19], v[56:59], 0
	v_mfma_f32_16x16x32_bf16 v[56:59], v[24:27], v[56:59], 0
	v_mfma_f32_16x16x32_bf16 v[52:55], v[20:23], v[60:63], v[52:55]
	v_mfma_f32_16x16x32_bf16 v[56:59], v[28:31], v[60:63], v[56:59]
	s_barrier
	s_add_i32 s65, s56, s50
	v_lshl_add_u64 v[208:209], s[40:41], 0, v[128:129]
	s_add_i32 s29, s65, 0x2000
	v_lshl_add_u64 v[142:143], v[208:209], 0, s[14:15]
	s_mov_b32 m0, s65
	v_lshl_add_u64 v[210:211], s[40:41], 0, v[130:131]
	s_add_u32 s68, s40, 0x10100
	ds_read_b128 v[60:63], v141 offset:16384
	ds_read_b128 v[100:103], v141 offset:17408
	ds_read_b128 v[104:107], v141 offset:18432
	ds_read_b128 v[108:111], v141 offset:19456
	ds_read_b128 v[112:115], v141 offset:20480
	ds_read_b128 v[116:119], v141 offset:21504
	ds_read_b128 v[120:123], v141 offset:22528
	ds_read_b128 v[124:127], v141 offset:23552
	global_load_lds_dwordx4 v[142:143], off
	v_lshl_add_u64 v[142:143], v[210:211], 0, s[14:15]
	s_mov_b32 m0, s29
	s_addc_u32 s69, s41, 0
	s_add_i32 s63, s57, s50
	global_load_lds_dwordx4 v[142:143], off
	v_lshl_add_u64 v[142:143], s[68:69], 0, v[128:129]
	s_mov_b32 m0, s63
	s_add_i32 s64, s63, 0x2000
	global_load_lds_dwordx4 v[142:143], off
	v_lshl_add_u64 v[142:143], s[68:69], 0, v[130:131]
	s_mov_b32 m0, s64
	v_lshl_add_u64 v[212:213], s[38:39], 0, v[128:129]
	global_load_lds_dwordx4 v[142:143], off
	v_lshl_add_u64 v[142:143], v[212:213], 0, s[14:15]
	s_mov_b32 m0, s37
	v_lshl_add_u64 v[214:215], s[38:39], 0, v[130:131]
	global_load_lds_dwordx4 v[142:143], off
	v_lshl_add_u64 v[142:143], v[214:215], 0, s[14:15]
	s_mov_b32 m0, s51
	s_nop 0
	global_load_lds_dwordx4 v[142:143], off
	s_waitcnt vmcnt(8)
	s_waitcnt lgkmcnt(0)
	s_barrier
	s_waitcnt lgkmcnt(0)
	s_nop 0
	v_mfma_f32_16x16x32_bf16 v[142:145], v[0:3], v[60:63], 0
	v_mfma_f32_16x16x32_bf16 v[150:153], v[0:3], v[104:107], 0
	v_mfma_f32_16x16x32_bf16 v[158:161], v[0:3], v[112:115], 0
	v_mfma_f32_16x16x32_bf16 v[0:3], v[0:3], v[120:123], 0
	v_mfma_f32_16x16x32_bf16 v[142:145], v[4:7], v[100:103], v[142:145]
	v_mfma_f32_16x16x32_bf16 v[150:153], v[4:7], v[108:111], v[150:153]
	v_mfma_f32_16x16x32_bf16 v[158:161], v[4:7], v[116:119], v[158:161]
	v_mfma_f32_16x16x32_bf16 v[0:3], v[4:7], v[124:127], v[0:3]
	v_mfma_f32_16x16x32_bf16 v[4:7], v[8:11], v[120:123], 0
	v_mfma_f32_16x16x32_bf16 v[146:149], v[8:11], v[60:63], 0
	v_mfma_f32_16x16x32_bf16 v[154:157], v[8:11], v[104:107], 0
	v_mfma_f32_16x16x32_bf16 v[162:165], v[8:11], v[112:115], 0
	v_mfma_f32_16x16x32_bf16 v[4:7], v[12:15], v[124:127], v[4:7]
	v_mfma_f32_16x16x32_bf16 v[146:149], v[12:15], v[100:103], v[146:149]
	v_mfma_f32_16x16x32_bf16 v[154:157], v[12:15], v[108:111], v[154:157]
	v_mfma_f32_16x16x32_bf16 v[162:165], v[12:15], v[116:119], v[162:165]
	v_mfma_f32_16x16x32_bf16 v[8:11], v[16:19], v[60:63], 0
	v_mfma_f32_16x16x32_bf16 v[12:15], v[24:27], v[60:63], 0
	v_mfma_f32_16x16x32_bf16 v[8:11], v[20:23], v[100:103], v[8:11]
	v_mfma_f32_16x16x32_bf16 v[12:15], v[28:31], v[100:103], v[12:15]
	v_mfma_f32_16x16x32_bf16 v[60:63], v[16:19], v[104:107], 0
	v_mfma_f32_16x16x32_bf16 v[100:103], v[24:27], v[104:107], 0
	v_mfma_f32_16x16x32_bf16 v[104:107], v[16:19], v[112:115], 0
	v_mfma_f32_16x16x32_bf16 v[16:19], v[16:19], v[120:123], 0
	v_mfma_f32_16x16x32_bf16 v[60:63], v[20:23], v[108:111], v[60:63]
	v_mfma_f32_16x16x32_bf16 v[100:103], v[28:31], v[108:111], v[100:103]
	v_mfma_f32_16x16x32_bf16 v[104:107], v[20:23], v[116:119], v[104:107]
	v_mfma_f32_16x16x32_bf16 v[108:111], v[24:27], v[112:115], 0
	v_mfma_f32_16x16x32_bf16 v[16:19], v[20:23], v[124:127], v[16:19]
	v_mfma_f32_16x16x32_bf16 v[20:23], v[24:27], v[120:123], 0
	v_mfma_f32_16x16x32_bf16 v[108:111], v[28:31], v[116:119], v[108:111]
	v_mfma_f32_16x16x32_bf16 v[20:23], v[28:31], v[124:127], v[20:23]
	s_barrier
	s_add_i32 s66, 0, 0x18000
	s_add_i32 s72, 0, 0x1c000
	v_add_u32_e32 v207, s66, v137
	v_add_u32_e32 v228, s72, v137
	ds_read_b128 v[24:27], v207
	ds_read_b128 v[28:31], v207 offset:1024
	ds_read_b128 v[112:115], v207 offset:2048
	ds_read_b128 v[116:119], v207 offset:3072
	ds_read_b128 v[120:123], v228
	ds_read_b128 v[124:127], v228 offset:1024
	ds_read_b128 v[166:169], v228 offset:2048
	ds_read_b128 v[170:173], v228 offset:3072
	s_add_u32 s68, s38, 0x10100
	s_addc_u32 s69, s39, 0
	s_mov_b32 m0, s52
	v_lshl_add_u64 v[216:217], s[68:69], 0, v[128:129]
	ds_read_b128 v[174:177], v141 offset:32768
	ds_read_b128 v[178:181], v141 offset:33792
	ds_read_b128 v[182:185], v141 offset:34816
	ds_read_b128 v[186:189], v141 offset:35840
	ds_read_b128 v[190:193], v141 offset:36864
	ds_read_b128 v[194:197], v141 offset:37888
	ds_read_b128 v[198:201], v141 offset:38912
	ds_read_b128 v[202:205], v141 offset:39936
	global_load_lds_dwordx4 v[216:217], off
	v_lshl_add_u64 v[216:217], s[68:69], 0, v[130:131]
	s_mov_b32 m0, s53
	s_nop 0
	global_load_lds_dwordx4 v[216:217], off
	s_waitcnt vmcnt(8)
	s_waitcnt lgkmcnt(0)
	s_barrier
	s_waitcnt lgkmcnt(0)
	s_nop 0
	v_mfma_f32_16x16x32_bf16 v[64:67], v[24:27], v[174:177], v[64:67]
	v_mfma_f32_16x16x32_bf16 v[68:71], v[112:115], v[174:177], v[68:71]
	v_mfma_f32_16x16x32_bf16 v[72:75], v[24:27], v[182:185], v[72:75]
	v_mfma_f32_16x16x32_bf16 v[76:79], v[112:115], v[182:185], v[76:79]
	v_mfma_f32_16x16x32_bf16 v[80:83], v[24:27], v[190:193], v[80:83]
	v_mfma_f32_16x16x32_bf16 v[84:87], v[112:115], v[190:193], v[84:87]
	v_mfma_f32_16x16x32_bf16 v[88:91], v[24:27], v[198:201], v[88:91]
	v_mfma_f32_16x16x32_bf16 v[92:95], v[112:115], v[198:201], v[92:95]
	v_mfma_f32_16x16x32_bf16 v[64:67], v[28:31], v[178:181], v[64:67]
	v_mfma_f32_16x16x32_bf16 v[68:71], v[116:119], v[178:181], v[68:71]
	v_mfma_f32_16x16x32_bf16 v[72:75], v[28:31], v[186:189], v[72:75]
	v_mfma_f32_16x16x32_bf16 v[76:79], v[116:119], v[186:189], v[76:79]
	v_mfma_f32_16x16x32_bf16 v[80:83], v[28:31], v[194:197], v[80:83]
	v_mfma_f32_16x16x32_bf16 v[84:87], v[116:119], v[194:197], v[84:87]
	v_mfma_f32_16x16x32_bf16 v[88:91], v[28:31], v[202:205], v[88:91]
	v_mfma_f32_16x16x32_bf16 v[92:95], v[116:119], v[202:205], v[92:95]
	v_mfma_f32_16x16x32_bf16 v[96:99], v[120:123], v[174:177], v[96:99]
	v_mfma_f32_16x16x32_bf16 v[32:35], v[166:169], v[174:177], v[32:35]
	v_mfma_f32_16x16x32_bf16 v[36:39], v[120:123], v[182:185], v[36:39]
	v_mfma_f32_16x16x32_bf16 v[40:43], v[166:169], v[182:185], v[40:43]
	v_mfma_f32_16x16x32_bf16 v[44:47], v[120:123], v[190:193], v[44:47]
	v_mfma_f32_16x16x32_bf16 v[48:51], v[166:169], v[190:193], v[48:51]
	v_mfma_f32_16x16x32_bf16 v[52:55], v[120:123], v[198:201], v[52:55]
	v_mfma_f32_16x16x32_bf16 v[56:59], v[166:169], v[198:201], v[56:59]
	v_mfma_f32_16x16x32_bf16 v[96:99], v[124:127], v[178:181], v[96:99]
	v_mfma_f32_16x16x32_bf16 v[32:35], v[170:173], v[178:181], v[32:35]
	v_mfma_f32_16x16x32_bf16 v[36:39], v[124:127], v[186:189], v[36:39]
	v_mfma_f32_16x16x32_bf16 v[40:43], v[170:173], v[186:189], v[40:43]
	v_mfma_f32_16x16x32_bf16 v[44:47], v[124:127], v[194:197], v[44:47]
	v_mfma_f32_16x16x32_bf16 v[48:51], v[170:173], v[194:197], v[48:51]
	v_mfma_f32_16x16x32_bf16 v[52:55], v[124:127], v[202:205], v[52:55]
	v_mfma_f32_16x16x32_bf16 v[56:59], v[170:173], v[202:205], v[56:59]
	s_barrier
	s_add_i32 s68, s66, s50
	s_add_i32 s66, s68, 0x2000
	v_lshl_add_u64 v[208:209], v[208:209], 0, s[16:17]
	s_mov_b32 m0, s68
	s_add_u32 s70, s40, 0x10180
	ds_read_b128 v[174:177], v141 offset:49152
	ds_read_b128 v[178:181], v141 offset:50176
	ds_read_b128 v[182:185], v141 offset:51200
	ds_read_b128 v[186:189], v141 offset:52224
	ds_read_b128 v[190:193], v141 offset:53248
	ds_read_b128 v[194:197], v141 offset:54272
	ds_read_b128 v[198:201], v141 offset:55296
	ds_read_b128 v[202:205], v141 offset:56320
	global_load_lds_dwordx4 v[208:209], off
	v_lshl_add_u64 v[208:209], v[210:211], 0, s[16:17]
	s_mov_b32 m0, s66
	s_addc_u32 s71, s41, 0
	s_add_i32 s40, s72, s50
	global_load_lds_dwordx4 v[208:209], off
	v_lshl_add_u64 v[208:209], s[70:71], 0, v[128:129]
	s_mov_b32 m0, s40
	s_add_i32 s41, s40, 0x2000
	global_load_lds_dwordx4 v[208:209], off
	v_lshl_add_u64 v[208:209], s[70:71], 0, v[130:131]
	s_mov_b32 m0, s41
	s_nop 0
	global_load_lds_dwordx4 v[208:209], off
	v_lshl_add_u64 v[208:209], v[212:213], 0, s[16:17]
	s_mov_b32 m0, s54
	s_nop 0
	global_load_lds_dwordx4 v[208:209], off
	v_lshl_add_u64 v[208:209], v[214:215], 0, s[16:17]
	s_mov_b32 m0, s55
	s_nop 0
	global_load_lds_dwordx4 v[208:209], off
	s_waitcnt vmcnt(8)
	s_waitcnt lgkmcnt(0)
	s_barrier
	s_waitcnt lgkmcnt(0)
	s_nop 0
	v_mfma_f32_16x16x32_bf16 v[0:3], v[24:27], v[198:201], v[0:3]
	v_mfma_f32_16x16x32_bf16 v[4:7], v[112:115], v[198:201], v[4:7]
	v_mfma_f32_16x16x32_bf16 v[142:145], v[24:27], v[174:177], v[142:145]
	v_mfma_f32_16x16x32_bf16 v[146:149], v[112:115], v[174:177], v[146:149]
	v_mfma_f32_16x16x32_bf16 v[150:153], v[24:27], v[182:185], v[150:153]
	v_mfma_f32_16x16x32_bf16 v[154:157], v[112:115], v[182:185], v[154:157]
	v_mfma_f32_16x16x32_bf16 v[158:161], v[24:27], v[190:193], v[158:161]
	v_mfma_f32_16x16x32_bf16 v[162:165], v[112:115], v[190:193], v[162:165]
	v_mfma_f32_16x16x32_bf16 v[0:3], v[28:31], v[202:205], v[0:3]
	v_mfma_f32_16x16x32_bf16 v[4:7], v[116:119], v[202:205], v[4:7]
	v_mfma_f32_16x16x32_bf16 v[142:145], v[28:31], v[178:181], v[142:145]
	v_mfma_f32_16x16x32_bf16 v[146:149], v[116:119], v[178:181], v[146:149]
	v_mfma_f32_16x16x32_bf16 v[150:153], v[28:31], v[186:189], v[150:153]
	v_mfma_f32_16x16x32_bf16 v[154:157], v[116:119], v[186:189], v[154:157]
	v_mfma_f32_16x16x32_bf16 v[158:161], v[28:31], v[194:197], v[158:161]
	v_mfma_f32_16x16x32_bf16 v[162:165], v[116:119], v[194:197], v[162:165]
	v_mfma_f32_16x16x32_bf16 v[8:11], v[120:123], v[174:177], v[8:11]
	v_mfma_f32_16x16x32_bf16 v[12:15], v[166:169], v[174:177], v[12:15]
	v_mfma_f32_16x16x32_bf16 v[24:27], v[120:123], v[182:185], v[60:63]
	v_mfma_f32_16x16x32_bf16 v[28:31], v[166:169], v[182:185], v[100:103]
	v_mfma_f32_16x16x32_bf16 v[60:63], v[120:123], v[190:193], v[104:107]
	v_mfma_f32_16x16x32_bf16 v[100:103], v[166:169], v[190:193], v[108:111]
	v_mfma_f32_16x16x32_bf16 v[16:19], v[120:123], v[198:201], v[16:19]
	v_mfma_f32_16x16x32_bf16 v[20:23], v[166:169], v[198:201], v[20:23]
	v_mfma_f32_16x16x32_bf16 v[8:11], v[124:127], v[178:181], v[8:11]
	v_mfma_f32_16x16x32_bf16 v[12:15], v[170:173], v[178:181], v[12:15]
	v_mfma_f32_16x16x32_bf16 v[24:27], v[124:127], v[186:189], v[24:27]
	v_mfma_f32_16x16x32_bf16 v[28:31], v[170:173], v[186:189], v[28:31]
	v_mfma_f32_16x16x32_bf16 v[60:63], v[124:127], v[194:197], v[60:63]
	v_mfma_f32_16x16x32_bf16 v[100:103], v[170:173], v[194:197], v[100:103]
	v_mfma_f32_16x16x32_bf16 v[16:19], v[124:127], v[202:205], v[16:19]
	v_mfma_f32_16x16x32_bf16 v[20:23], v[170:173], v[202:205], v[20:23]
	s_barrier
	ds_read_b128 v[104:107], v139
	ds_read_b128 v[108:111], v139 offset:1024
	ds_read_b128 v[112:115], v139 offset:2048
	ds_read_b128 v[116:119], v139 offset:3072
	ds_read_b128 v[120:123], v140
	ds_read_b128 v[124:127], v140 offset:1024
	ds_read_b128 v[166:169], v140 offset:2048
	ds_read_b128 v[170:173], v140 offset:3072
	s_add_u32 s38, s38, 0x10180
	s_addc_u32 s39, s39, 0
	s_mov_b32 m0, s67
	v_lshl_add_u64 v[208:209], s[38:39], 0, v[128:129]
	ds_read_b128 v[174:177], v141
	ds_read_b128 v[178:181], v141 offset:1024
	ds_read_b128 v[182:185], v141 offset:2048
	ds_read_b128 v[186:189], v141 offset:3072
	ds_read_b128 v[190:193], v141 offset:4096
	ds_read_b128 v[194:197], v141 offset:5120
	ds_read_b128 v[198:201], v141 offset:6144
	ds_read_b128 v[202:205], v141 offset:7168
	global_load_lds_dwordx4 v[208:209], off
	v_lshl_add_u64 v[208:209], s[38:39], 0, v[130:131]
	s_mov_b32 m0, s27
	s_nop 0
	global_load_lds_dwordx4 v[208:209], off
	s_waitcnt vmcnt(8)
	s_waitcnt lgkmcnt(0)
	s_barrier
	s_waitcnt lgkmcnt(0)
	s_nop 0
	v_mfma_f32_16x16x32_bf16 v[64:67], v[104:107], v[174:177], v[64:67]
	v_mfma_f32_16x16x32_bf16 v[68:71], v[112:115], v[174:177], v[68:71]
	v_mfma_f32_16x16x32_bf16 v[72:75], v[104:107], v[182:185], v[72:75]
	v_mfma_f32_16x16x32_bf16 v[76:79], v[112:115], v[182:185], v[76:79]
	v_mfma_f32_16x16x32_bf16 v[80:83], v[104:107], v[190:193], v[80:83]
	v_mfma_f32_16x16x32_bf16 v[84:87], v[112:115], v[190:193], v[84:87]
	v_mfma_f32_16x16x32_bf16 v[88:91], v[104:107], v[198:201], v[88:91]
	v_mfma_f32_16x16x32_bf16 v[64:67], v[108:111], v[178:181], v[64:67]
	v_mfma_f32_16x16x32_bf16 v[68:71], v[116:119], v[178:181], v[68:71]
	v_mfma_f32_16x16x32_bf16 v[72:75], v[108:111], v[186:189], v[72:75]
	v_mfma_f32_16x16x32_bf16 v[76:79], v[116:119], v[186:189], v[76:79]
	v_mfma_f32_16x16x32_bf16 v[80:83], v[108:111], v[194:197], v[80:83]
	v_mfma_f32_16x16x32_bf16 v[84:87], v[116:119], v[194:197], v[84:87]
	v_mfma_f32_16x16x32_bf16 v[88:91], v[108:111], v[202:205], v[88:91]
	v_mfma_f32_16x16x32_bf16 v[92:95], v[112:115], v[198:201], v[92:95]
	v_mfma_f32_16x16x32_bf16 v[208:211], v[116:119], v[202:205], v[92:95]
	v_mfma_f32_16x16x32_bf16 v[48:51], v[166:169], v[190:193], v[48:51]
	v_mfma_f32_16x16x32_bf16 v[92:95], v[120:123], v[174:177], v[96:99]
	v_mfma_f32_16x16x32_bf16 v[32:35], v[166:169], v[174:177], v[32:35]
	v_mfma_f32_16x16x32_bf16 v[36:39], v[120:123], v[182:185], v[36:39]
	v_mfma_f32_16x16x32_bf16 v[40:43], v[166:169], v[182:185], v[40:43]
	v_mfma_f32_16x16x32_bf16 v[44:47], v[120:123], v[190:193], v[44:47]
	v_mfma_f32_16x16x32_bf16 v[174:177], v[170:173], v[194:197], v[48:51]
	v_mfma_f32_16x16x32_bf16 v[48:51], v[120:123], v[198:201], v[52:55]
	v_mfma_f32_16x16x32_bf16 v[32:35], v[170:173], v[178:181], v[32:35]
	v_mfma_f32_16x16x32_bf16 v[36:39], v[124:127], v[186:189], v[36:39]
	v_mfma_f32_16x16x32_bf16 v[40:43], v[170:173], v[186:189], v[40:43]
	v_mfma_f32_16x16x32_bf16 v[44:47], v[124:127], v[194:197], v[44:47]
	v_mfma_f32_16x16x32_bf16 v[52:55], v[124:127], v[202:205], v[48:51]
	v_mfma_f32_16x16x32_bf16 v[48:51], v[166:169], v[198:201], v[56:59]
	v_mfma_f32_16x16x32_bf16 v[212:215], v[124:127], v[178:181], v[92:95]
	v_mfma_f32_16x16x32_bf16 v[178:181], v[170:173], v[202:205], v[48:51]
	s_barrier
	s_mov_b32 m0, s65
	v_lshl_add_u64 v[248:249], s[42:43], 0, v[128:129]
	s_add_u32 s38, s42, 0x10000
	s_nop 0
	ds_read_b128 v[48:51], v141 offset:16384
	ds_read_b128 v[56:59], v141 offset:17408
	ds_read_b128 v[92:95], v141 offset:18432
	ds_read_b128 v[96:99], v141 offset:19456
	ds_read_b128 v[182:185], v141 offset:20480
	ds_read_b128 v[186:189], v141 offset:21504
	ds_read_b128 v[190:193], v141 offset:22528
	ds_read_b128 v[194:197], v141 offset:23552
	global_load_lds_dwordx4 v[248:249], off
	v_lshl_add_u64 v[250:251], s[42:43], 0, v[130:131]
	s_mov_b32 m0, s29
	s_addc_u32 s39, s43, 0
	global_load_lds_dwordx4 v[250:251], off
	v_lshl_add_u64 v[198:199], s[38:39], 0, v[128:129]
	s_mov_b32 m0, s63
	v_lshl_add_u64 v[252:253], s[44:45], 0, v[128:129]
	global_load_lds_dwordx4 v[198:199], off
	v_lshl_add_u64 v[198:199], s[38:39], 0, v[130:131]
	s_mov_b32 m0, s64
	v_lshl_add_u64 v[132:133], s[44:45], 0, v[130:131]
	global_load_lds_dwordx4 v[198:199], off
	s_mov_b32 m0, s37
	s_nop 0
	global_load_lds_dwordx4 v[252:253], off
	s_mov_b32 m0, s51
	s_nop 0
	global_load_lds_dwordx4 v[132:133], off
	s_waitcnt vmcnt(8)
	s_waitcnt lgkmcnt(0)
	s_barrier
	s_waitcnt lgkmcnt(0)
	s_nop 0
	v_mfma_f32_16x16x32_bf16 v[0:3], v[104:107], v[190:193], v[0:3]
	v_mfma_f32_16x16x32_bf16 v[4:7], v[112:115], v[190:193], v[4:7]
	v_mfma_f32_16x16x32_bf16 v[142:145], v[104:107], v[48:51], v[142:145]
	v_mfma_f32_16x16x32_bf16 v[146:149], v[112:115], v[48:51], v[146:149]
	v_mfma_f32_16x16x32_bf16 v[150:153], v[104:107], v[92:95], v[150:153]
	v_mfma_f32_16x16x32_bf16 v[154:157], v[112:115], v[92:95], v[154:157]
	v_mfma_f32_16x16x32_bf16 v[158:161], v[104:107], v[182:185], v[158:161]
	v_mfma_f32_16x16x32_bf16 v[162:165], v[112:115], v[182:185], v[162:165]
	v_mfma_f32_16x16x32_bf16 v[0:3], v[108:111], v[194:197], v[0:3]
	v_mfma_f32_16x16x32_bf16 v[4:7], v[116:119], v[194:197], v[4:7]
	v_mfma_f32_16x16x32_bf16 v[142:145], v[108:111], v[56:59], v[142:145]
	v_mfma_f32_16x16x32_bf16 v[146:149], v[116:119], v[56:59], v[146:149]
	v_mfma_f32_16x16x32_bf16 v[150:153], v[108:111], v[96:99], v[150:153]
	v_mfma_f32_16x16x32_bf16 v[154:157], v[116:119], v[96:99], v[154:157]
	v_mfma_f32_16x16x32_bf16 v[158:161], v[108:111], v[186:189], v[158:161]
	v_mfma_f32_16x16x32_bf16 v[162:165], v[116:119], v[186:189], v[162:165]
	v_mfma_f32_16x16x32_bf16 v[12:15], v[166:169], v[48:51], v[12:15]
	v_mfma_f32_16x16x32_bf16 v[198:201], v[170:173], v[56:59], v[12:15]
	v_mfma_f32_16x16x32_bf16 v[12:15], v[120:123], v[92:95], v[24:27]
	v_mfma_f32_16x16x32_bf16 v[24:27], v[124:127], v[96:99], v[12:15]
	v_mfma_f32_16x16x32_bf16 v[12:15], v[166:169], v[92:95], v[28:31]
	v_mfma_f32_16x16x32_bf16 v[202:205], v[170:173], v[96:99], v[12:15]
	v_mfma_f32_16x16x32_bf16 v[12:15], v[120:123], v[182:185], v[60:63]
	v_mfma_f32_16x16x32_bf16 v[216:219], v[124:127], v[186:189], v[12:15]
	v_mfma_f32_16x16x32_bf16 v[12:15], v[166:169], v[182:185], v[100:103]
	v_mfma_f32_16x16x32_bf16 v[8:11], v[120:123], v[48:51], v[8:11]
	v_mfma_f32_16x16x32_bf16 v[182:185], v[170:173], v[186:189], v[12:15]
	v_mfma_f32_16x16x32_bf16 v[12:15], v[120:123], v[190:193], v[16:19]
	v_mfma_f32_16x16x32_bf16 v[8:11], v[124:127], v[56:59], v[8:11]
	v_mfma_f32_16x16x32_bf16 v[186:189], v[124:127], v[194:197], v[12:15]
	v_mfma_f32_16x16x32_bf16 v[12:15], v[166:169], v[190:193], v[20:23]
	v_mfma_f32_16x16x32_bf16 v[166:169], v[170:173], v[194:197], v[12:15]
	s_barrier
	s_nop 4
	ds_read_b128 v[12:15], v207
	ds_read_b128 v[20:23], v207 offset:1024
	ds_read_b128 v[170:173], v207 offset:2048
	ds_read_b128 v[190:193], v207 offset:3072
	ds_read_b128 v[194:197], v228
	ds_read_b128 v[220:223], v228 offset:1024
	ds_read_b128 v[224:227], v228 offset:2048
	ds_read_b128 v[228:231], v228 offset:3072
	s_add_u32 s38, s44, 0x10000
	s_addc_u32 s39, s45, 0
	s_mov_b32 m0, s52
	v_lshl_add_u64 v[48:49], s[38:39], 0, v[128:129]
	ds_read_b128 v[16:19], v141 offset:32768
	ds_read_b128 v[28:31], v141 offset:33792
	ds_read_b128 v[56:59], v141 offset:34816
	ds_read_b128 v[100:103], v141 offset:35840
	ds_read_b128 v[232:235], v141 offset:36864
	ds_read_b128 v[236:239], v141 offset:37888
	ds_read_b128 v[240:243], v141 offset:38912
	ds_read_b128 v[244:247], v141 offset:39936
	global_load_lds_dwordx4 v[48:49], off
	v_lshl_add_u64 v[48:49], s[38:39], 0, v[130:131]
	s_mov_b32 m0, s53
	s_nop 0
	global_load_lds_dwordx4 v[48:49], off
	s_waitcnt vmcnt(8)
	s_waitcnt lgkmcnt(0)
	s_barrier
	s_waitcnt lgkmcnt(0)
	v_mfma_f32_16x16x32_bf16 v[48:51], v[12:15], v[16:19], v[64:67]
	v_mfma_f32_16x16x32_bf16 v[124:127], v[20:23], v[28:31], v[48:51]
	v_mfma_f32_16x16x32_bf16 v[48:51], v[170:173], v[16:19], v[68:71]
	v_mfma_f32_16x16x32_bf16 v[112:115], v[190:193], v[28:31], v[48:51]
	v_mfma_f32_16x16x32_bf16 v[48:51], v[12:15], v[56:59], v[72:75]
	v_mfma_f32_16x16x32_bf16 v[108:111], v[20:23], v[100:103], v[48:51]
	v_mfma_f32_16x16x32_bf16 v[48:51], v[170:173], v[56:59], v[76:79]
	v_mfma_f32_16x16x32_bf16 v[96:99], v[190:193], v[100:103], v[48:51]
	v_mfma_f32_16x16x32_bf16 v[48:51], v[12:15], v[232:235], v[80:83]
	v_mfma_f32_16x16x32_bf16 v[92:95], v[20:23], v[236:239], v[48:51]
	v_mfma_f32_16x16x32_bf16 v[48:51], v[170:173], v[232:235], v[84:87]
	v_mfma_f32_16x16x32_bf16 v[80:83], v[190:193], v[236:239], v[48:51]
	v_mfma_f32_16x16x32_bf16 v[48:51], v[12:15], v[240:243], v[88:91]
	v_mfma_f32_16x16x32_bf16 v[60:63], v[20:23], v[244:247], v[48:51]
	v_mfma_f32_16x16x32_bf16 v[48:51], v[170:173], v[240:243], v[208:211]
	v_mfma_f32_16x16x32_bf16 v[48:51], v[190:193], v[244:247], v[48:51]
	v_mfma_f32_16x16x32_bf16 v[64:67], v[194:197], v[16:19], v[212:215]
	v_mfma_f32_16x16x32_bf16 v[16:19], v[224:227], v[16:19], v[32:35]
	v_mfma_f32_16x16x32_bf16 v[116:119], v[228:231], v[28:31], v[16:19]
	v_mfma_f32_16x16x32_bf16 v[16:19], v[194:197], v[56:59], v[36:39]
	v_mfma_f32_16x16x32_bf16 v[104:107], v[220:223], v[100:103], v[16:19]
	v_mfma_f32_16x16x32_bf16 v[16:19], v[224:227], v[56:59], v[40:43]
	v_mfma_f32_16x16x32_bf16 v[100:103], v[228:231], v[100:103], v[16:19]
	v_mfma_f32_16x16x32_bf16 v[16:19], v[194:197], v[232:235], v[44:47]
	v_mfma_f32_16x16x32_bf16 v[88:91], v[220:223], v[236:239], v[16:19]
	v_mfma_f32_16x16x32_bf16 v[16:19], v[224:227], v[232:235], v[174:177]
	v_mfma_f32_16x16x32_bf16 v[84:87], v[228:231], v[236:239], v[16:19]
	v_mfma_f32_16x16x32_bf16 v[16:19], v[194:197], v[240:243], v[52:55]
	v_mfma_f32_16x16x32_bf16 v[56:59], v[220:223], v[244:247], v[16:19]
	v_mfma_f32_16x16x32_bf16 v[16:19], v[224:227], v[240:243], v[178:181]
	v_mfma_f32_16x16x32_bf16 v[120:123], v[220:223], v[28:31], v[64:67]
	v_mfma_f32_16x16x32_bf16 v[52:55], v[228:231], v[244:247], v[16:19]
	s_barrier
	s_mov_b32 m0, s68
	s_nop 2
	v_lshl_add_u64 v[16:17], v[248:249], 0, s[8:9]
	s_add_u32 s38, s42, 0x10080
	ds_read_b128 v[36:39], v141 offset:49152
	ds_read_b128 v[40:43], v141 offset:50176
	ds_read_b128 v[174:177], v141 offset:51200
	ds_read_b128 v[178:181], v141 offset:52224
	ds_read_b128 v[208:211], v141 offset:53248
	ds_read_b128 v[212:215], v141 offset:54272
	ds_read_b128 v[232:235], v141 offset:55296
	ds_read_b128 v[236:239], v141 offset:56320
	global_load_lds_dwordx4 v[16:17], off
	v_lshl_add_u64 v[16:17], v[250:251], 0, s[8:9]
	s_mov_b32 m0, s66
	s_addc_u32 s39, s43, 0
	global_load_lds_dwordx4 v[16:17], off
	v_lshl_add_u64 v[16:17], s[38:39], 0, v[128:129]
	s_mov_b32 m0, s40
	s_nop 0
	global_load_lds_dwordx4 v[16:17], off
	v_lshl_add_u64 v[16:17], s[38:39], 0, v[130:131]
	s_mov_b32 m0, s41
	s_nop 0
	global_load_lds_dwordx4 v[16:17], off
	v_lshl_add_u64 v[16:17], v[252:253], 0, s[8:9]
	s_mov_b32 m0, s54
	s_nop 0
	global_load_lds_dwordx4 v[16:17], off
	v_lshl_add_u64 v[16:17], v[132:133], 0, s[8:9]
	s_mov_b32 m0, s55
	s_nop 0
	global_load_lds_dwordx4 v[16:17], off
	s_waitcnt vmcnt(8)
	s_waitcnt lgkmcnt(0)
	s_barrier
	s_waitcnt lgkmcnt(0)
	s_nop 0
	v_mfma_f32_16x16x32_bf16 v[16:19], v[12:15], v[36:39], v[142:145]
	v_mfma_f32_16x16x32_bf16 v[76:79], v[20:23], v[40:43], v[16:19]
	v_mfma_f32_16x16x32_bf16 v[16:19], v[170:173], v[36:39], v[146:149]
	v_mfma_f32_16x16x32_bf16 v[64:67], v[190:193], v[40:43], v[16:19]
	v_mfma_f32_16x16x32_bf16 v[16:19], v[12:15], v[174:177], v[150:153]
	v_mfma_f32_16x16x32_bf16 v[44:47], v[20:23], v[178:181], v[16:19]
	v_mfma_f32_16x16x32_bf16 v[16:19], v[170:173], v[174:177], v[154:157]
	v_mfma_f32_16x16x32_bf16 v[32:35], v[190:193], v[178:181], v[16:19]
	v_mfma_f32_16x16x32_bf16 v[16:19], v[12:15], v[208:211], v[158:161]
	v_mfma_f32_16x16x32_bf16 v[0:3], v[12:15], v[232:235], v[0:3]
	v_mfma_f32_16x16x32_bf16 v[28:31], v[20:23], v[212:215], v[16:19]
	v_mfma_f32_16x16x32_bf16 v[16:19], v[170:173], v[208:211], v[162:165]
	v_mfma_f32_16x16x32_bf16 v[12:15], v[20:23], v[236:239], v[0:3]
	v_mfma_f32_16x16x32_bf16 v[0:3], v[170:173], v[232:235], v[4:7]
	v_mfma_f32_16x16x32_bf16 v[16:19], v[190:193], v[212:215], v[16:19]
	v_mfma_f32_16x16x32_bf16 v[0:3], v[190:193], v[236:239], v[0:3]
	v_mfma_f32_16x16x32_bf16 v[4:7], v[194:197], v[36:39], v[8:11]
	v_mfma_f32_16x16x32_bf16 v[72:75], v[220:223], v[40:43], v[4:7]
	v_mfma_f32_16x16x32_bf16 v[4:7], v[224:227], v[36:39], v[198:201]
	v_mfma_f32_16x16x32_bf16 v[68:71], v[228:231], v[40:43], v[4:7]
	v_mfma_f32_16x16x32_bf16 v[4:7], v[194:197], v[174:177], v[24:27]
	v_mfma_f32_16x16x32_bf16 v[40:43], v[220:223], v[178:181], v[4:7]
	v_mfma_f32_16x16x32_bf16 v[4:7], v[224:227], v[174:177], v[202:205]
	v_mfma_f32_16x16x32_bf16 v[36:39], v[228:231], v[178:181], v[4:7]
	v_mfma_f32_16x16x32_bf16 v[4:7], v[194:197], v[208:211], v[216:219]
	v_mfma_f32_16x16x32_bf16 v[24:27], v[220:223], v[212:215], v[4:7]
	v_mfma_f32_16x16x32_bf16 v[4:7], v[224:227], v[208:211], v[182:185]
	v_mfma_f32_16x16x32_bf16 v[20:23], v[228:231], v[212:215], v[4:7]
	v_mfma_f32_16x16x32_bf16 v[4:7], v[194:197], v[232:235], v[186:189]
	v_mfma_f32_16x16x32_bf16 v[8:11], v[220:223], v[236:239], v[4:7]
	v_mfma_f32_16x16x32_bf16 v[4:7], v[224:227], v[232:235], v[166:169]
	v_mfma_f32_16x16x32_bf16 v[4:7], v[228:231], v[236:239], v[4:7]
	s_barrier
	s_andn2_b64 vcc, exec, s[10:11]
	s_cbranch_vccnz .LBB0_819
	s_barrier

.LBB0_895:
	ds_read_b128 v[140:143], v153
	ds_read_b128 v[144:147], v153 offset:1024
	ds_read_b128 v[158:161], v153 offset:2048
	ds_read_b128 v[162:165], v153 offset:3072
	ds_read_b128 v[166:169], v154
	ds_read_b128 v[170:173], v154 offset:1024
	ds_read_b128 v[174:177], v154 offset:2048
	ds_read_b128 v[178:181], v154 offset:3072
	s_add_u32 s38, s36, 0xfffc0080
	s_addc_u32 s39, s37, -1
	s_cmp_eq_u32 s61, 12
	s_cselect_b32 s41, s3, s39
	s_cselect_b32 s40, s29, s38
	s_cselect_b32 s39, s27, s60
	s_cselect_b32 s38, s58, s59
	s_add_i32 m0, s46, 0xc000
	ds_read_b128 v[182:185], v155
	ds_read_b128 v[186:189], v155 offset:1024
	ds_read_b128 v[190:193], v155 offset:2048
	ds_read_b128 v[194:197], v155 offset:3072
	ds_read_b128 v[198:201], v155 offset:4096
	ds_read_b128 v[202:205], v155 offset:5120
	ds_read_b128 v[208:211], v155 offset:6144
	ds_read_b128 v[212:215], v155 offset:7168
	global_load_lds_dwordx4 v134, s[36:37]
	s_add_i32 m0, s46, 0xe000
	s_nop 0
	global_load_lds_dwordx4 v132, s[36:37]
	s_waitcnt vmcnt(8)
	s_waitcnt lgkmcnt(0)
	s_barrier
	s_waitcnt lgkmcnt(0)
	s_nop 0
	v_mfma_f32_16x16x32_bf16 v[124:127], v[140:143], v[182:185], v[124:127]
	v_mfma_f32_16x16x32_bf16 v[120:123], v[158:161], v[182:185], v[120:123]
	v_mfma_f32_16x16x32_bf16 v[108:111], v[140:143], v[190:193], v[108:111]
	v_mfma_f32_16x16x32_bf16 v[104:107], v[158:161], v[190:193], v[104:107]
	v_mfma_f32_16x16x32_bf16 v[92:95], v[140:143], v[198:201], v[92:95]
	v_mfma_f32_16x16x32_bf16 v[88:91], v[158:161], v[198:201], v[88:91]
	v_mfma_f32_16x16x32_bf16 v[76:79], v[140:143], v[208:211], v[76:79]
	v_mfma_f32_16x16x32_bf16 v[72:75], v[158:161], v[208:211], v[72:75]
	v_mfma_f32_16x16x32_bf16 v[124:127], v[144:147], v[186:189], v[124:127]
	v_mfma_f32_16x16x32_bf16 v[120:123], v[162:165], v[186:189], v[120:123]
	v_mfma_f32_16x16x32_bf16 v[108:111], v[144:147], v[194:197], v[108:111]
	v_mfma_f32_16x16x32_bf16 v[104:107], v[162:165], v[194:197], v[104:107]
	v_mfma_f32_16x16x32_bf16 v[92:95], v[144:147], v[202:205], v[92:95]
	v_mfma_f32_16x16x32_bf16 v[88:91], v[162:165], v[202:205], v[88:91]
	v_mfma_f32_16x16x32_bf16 v[76:79], v[144:147], v[212:215], v[76:79]
	v_mfma_f32_16x16x32_bf16 v[72:75], v[162:165], v[212:215], v[72:75]
	v_mfma_f32_16x16x32_bf16 v[116:119], v[166:169], v[182:185], v[116:119]
	v_mfma_f32_16x16x32_bf16 v[112:115], v[174:177], v[182:185], v[112:115]
	v_mfma_f32_16x16x32_bf16 v[100:103], v[166:169], v[190:193], v[100:103]
	v_mfma_f32_16x16x32_bf16 v[96:99], v[174:177], v[190:193], v[96:99]
	v_mfma_f32_16x16x32_bf16 v[84:87], v[166:169], v[198:201], v[84:87]
	v_mfma_f32_16x16x32_bf16 v[80:83], v[174:177], v[198:201], v[80:83]
	v_mfma_f32_16x16x32_bf16 v[68:71], v[166:169], v[208:211], v[68:71]
	v_mfma_f32_16x16x32_bf16 v[64:67], v[174:177], v[208:211], v[64:67]
	v_mfma_f32_16x16x32_bf16 v[116:119], v[170:173], v[186:189], v[116:119]
	v_mfma_f32_16x16x32_bf16 v[112:115], v[178:181], v[186:189], v[112:115]
	v_mfma_f32_16x16x32_bf16 v[100:103], v[170:173], v[194:197], v[100:103]
	v_mfma_f32_16x16x32_bf16 v[96:99], v[178:181], v[194:197], v[96:99]
	v_mfma_f32_16x16x32_bf16 v[84:87], v[170:173], v[202:205], v[84:87]
	v_mfma_f32_16x16x32_bf16 v[80:83], v[178:181], v[202:205], v[80:83]
	v_mfma_f32_16x16x32_bf16 v[68:71], v[170:173], v[212:215], v[68:71]
	v_mfma_f32_16x16x32_bf16 v[64:67], v[178:181], v[212:215], v[64:67]
	s_barrier
	s_add_i32 s62, s54, s45
	s_mov_b32 m0, s62
	ds_read_b128 v[182:185], v155 offset:16384
	ds_read_b128 v[186:189], v155 offset:17408
	ds_read_b128 v[190:193], v155 offset:18432
	ds_read_b128 v[194:197], v155 offset:19456
	ds_read_b128 v[198:201], v155 offset:20480
	ds_read_b128 v[202:205], v155 offset:21504
	ds_read_b128 v[208:211], v155 offset:22528
	ds_read_b128 v[212:215], v155 offset:23552
	global_load_lds_dwordx4 v128, s[38:39]
	s_add_i32 m0, s62, 0x2000
	s_add_u32 s62, s38, 0x40000
	s_mov_b64 s[98:99], s[38:39]
	s_addc_u32 s63, s39, 0
	s_add_i32 s64, s55, s45
	global_load_lds_dwordx4 v130, s[38:39]
	s_mov_b32 m0, s64
	s_mov_b64 s[100:101], s[40:41]
	global_load_lds_dwordx4 v128, s[62:63]
	s_add_i32 m0, s64, 0x2000
	s_nop 0
	global_load_lds_dwordx4 v130, s[62:63]
	s_mov_b32 m0, s46
	s_nop 0
	global_load_lds_dwordx4 v128, s[40:41]
	s_mov_b32 m0, s47
	s_nop 0
	global_load_lds_dwordx4 v130, s[40:41]
	s_waitcnt vmcnt(8)
	s_waitcnt lgkmcnt(0)
	s_barrier
	s_waitcnt lgkmcnt(0)
	s_nop 0
	v_mfma_f32_16x16x32_bf16 v[60:63], v[140:143], v[182:185], v[60:63]
	v_mfma_f32_16x16x32_bf16 v[56:59], v[158:161], v[182:185], v[56:59]
	v_mfma_f32_16x16x32_bf16 v[44:47], v[140:143], v[190:193], v[44:47]
	v_mfma_f32_16x16x32_bf16 v[40:43], v[158:161], v[190:193], v[40:43]
	v_mfma_f32_16x16x32_bf16 v[28:31], v[140:143], v[198:201], v[28:31]
	v_mfma_f32_16x16x32_bf16 v[24:27], v[158:161], v[198:201], v[24:27]
	v_mfma_f32_16x16x32_bf16 v[12:15], v[140:143], v[208:211], v[12:15]
	v_mfma_f32_16x16x32_bf16 v[8:11], v[158:161], v[208:211], v[8:11]
	v_mfma_f32_16x16x32_bf16 v[60:63], v[144:147], v[186:189], v[60:63]
	v_mfma_f32_16x16x32_bf16 v[56:59], v[162:165], v[186:189], v[56:59]
	v_mfma_f32_16x16x32_bf16 v[44:47], v[144:147], v[194:197], v[44:47]
	v_mfma_f32_16x16x32_bf16 v[40:43], v[162:165], v[194:197], v[40:43]
	v_mfma_f32_16x16x32_bf16 v[28:31], v[144:147], v[202:205], v[28:31]
	v_mfma_f32_16x16x32_bf16 v[24:27], v[162:165], v[202:205], v[24:27]
	v_mfma_f32_16x16x32_bf16 v[12:15], v[144:147], v[212:215], v[12:15]
	v_mfma_f32_16x16x32_bf16 v[8:11], v[162:165], v[212:215], v[8:11]
	v_mfma_f32_16x16x32_bf16 v[52:55], v[166:169], v[182:185], v[52:55]
	v_mfma_f32_16x16x32_bf16 v[48:51], v[174:177], v[182:185], v[48:51]
	v_mfma_f32_16x16x32_bf16 v[36:39], v[166:169], v[190:193], v[36:39]
	v_mfma_f32_16x16x32_bf16 v[32:35], v[174:177], v[190:193], v[32:35]
	v_mfma_f32_16x16x32_bf16 v[20:23], v[166:169], v[198:201], v[20:23]
	v_mfma_f32_16x16x32_bf16 v[16:19], v[174:177], v[198:201], v[16:19]
	v_mfma_f32_16x16x32_bf16 v[4:7], v[166:169], v[208:211], v[4:7]
	v_mfma_f32_16x16x32_bf16 v[0:3], v[174:177], v[208:211], v[0:3]
	v_mfma_f32_16x16x32_bf16 v[52:55], v[170:173], v[186:189], v[52:55]
	v_mfma_f32_16x16x32_bf16 v[48:51], v[178:181], v[186:189], v[48:51]
	v_mfma_f32_16x16x32_bf16 v[36:39], v[170:173], v[194:197], v[36:39]
	v_mfma_f32_16x16x32_bf16 v[32:35], v[178:181], v[194:197], v[32:35]
	v_mfma_f32_16x16x32_bf16 v[20:23], v[170:173], v[202:205], v[20:23]
	v_mfma_f32_16x16x32_bf16 v[16:19], v[178:181], v[202:205], v[16:19]
	v_mfma_f32_16x16x32_bf16 v[4:7], v[170:173], v[212:215], v[4:7]
	v_mfma_f32_16x16x32_bf16 v[0:3], v[178:181], v[212:215], v[0:3]
	s_barrier
	s_add_i32 s62, 0, 0x18000
	v_add_u32_e32 v157, s62, v151
	s_add_i32 s63, 0, 0x1c000
	ds_read_b128 v[140:143], v157
	ds_read_b128 v[144:147], v157 offset:1024
	ds_read_b128 v[158:161], v157 offset:2048
	ds_read_b128 v[162:165], v157 offset:3072
	v_add_u32_e32 v157, s63, v151
	ds_read_b128 v[166:169], v157
	ds_read_b128 v[170:173], v157 offset:1024
	ds_read_b128 v[174:177], v157 offset:2048
	ds_read_b128 v[178:181], v157 offset:3072
	s_add_u32 s40, s40, 0x40000
	s_addc_u32 s41, s41, 0
	s_mov_b32 m0, s48
	ds_read_b128 v[182:185], v155 offset:32768
	ds_read_b128 v[186:189], v155 offset:33792
	ds_read_b128 v[190:193], v155 offset:34816
	ds_read_b128 v[194:197], v155 offset:35840
	ds_read_b128 v[198:201], v155 offset:36864
	ds_read_b128 v[202:205], v155 offset:37888
	ds_read_b128 v[208:211], v155 offset:38912
	ds_read_b128 v[212:215], v155 offset:39936
	global_load_lds_dwordx4 v128, s[40:41]
	s_mov_b32 m0, s49
	s_nop 0
	global_load_lds_dwordx4 v130, s[40:41]
	s_waitcnt vmcnt(8)
	s_waitcnt lgkmcnt(0)
	s_barrier
	s_waitcnt lgkmcnt(0)
	s_nop 0
	v_mfma_f32_16x16x32_bf16 v[124:127], v[140:143], v[182:185], v[124:127]
	v_mfma_f32_16x16x32_bf16 v[120:123], v[158:161], v[182:185], v[120:123]
	v_mfma_f32_16x16x32_bf16 v[108:111], v[140:143], v[190:193], v[108:111]
	v_mfma_f32_16x16x32_bf16 v[104:107], v[158:161], v[190:193], v[104:107]
	v_mfma_f32_16x16x32_bf16 v[92:95], v[140:143], v[198:201], v[92:95]
	v_mfma_f32_16x16x32_bf16 v[88:91], v[158:161], v[198:201], v[88:91]
	v_mfma_f32_16x16x32_bf16 v[76:79], v[140:143], v[208:211], v[76:79]
	v_mfma_f32_16x16x32_bf16 v[72:75], v[158:161], v[208:211], v[72:75]
	v_mfma_f32_16x16x32_bf16 v[124:127], v[144:147], v[186:189], v[124:127]
	v_mfma_f32_16x16x32_bf16 v[120:123], v[162:165], v[186:189], v[120:123]
	v_mfma_f32_16x16x32_bf16 v[108:111], v[144:147], v[194:197], v[108:111]
	v_mfma_f32_16x16x32_bf16 v[104:107], v[162:165], v[194:197], v[104:107]
	v_mfma_f32_16x16x32_bf16 v[92:95], v[144:147], v[202:205], v[92:95]
	v_mfma_f32_16x16x32_bf16 v[88:91], v[162:165], v[202:205], v[88:91]
	v_mfma_f32_16x16x32_bf16 v[76:79], v[144:147], v[212:215], v[76:79]
	v_mfma_f32_16x16x32_bf16 v[72:75], v[162:165], v[212:215], v[72:75]
	v_mfma_f32_16x16x32_bf16 v[116:119], v[166:169], v[182:185], v[116:119]
	v_mfma_f32_16x16x32_bf16 v[112:115], v[174:177], v[182:185], v[112:115]
	v_mfma_f32_16x16x32_bf16 v[100:103], v[166:169], v[190:193], v[100:103]
	v_mfma_f32_16x16x32_bf16 v[96:99], v[174:177], v[190:193], v[96:99]
	v_mfma_f32_16x16x32_bf16 v[84:87], v[166:169], v[198:201], v[84:87]
	v_mfma_f32_16x16x32_bf16 v[80:83], v[174:177], v[198:201], v[80:83]
	v_mfma_f32_16x16x32_bf16 v[68:71], v[166:169], v[208:211], v[68:71]
	v_mfma_f32_16x16x32_bf16 v[64:67], v[174:177], v[208:211], v[64:67]
	v_mfma_f32_16x16x32_bf16 v[116:119], v[170:173], v[186:189], v[116:119]
	v_mfma_f32_16x16x32_bf16 v[112:115], v[178:181], v[186:189], v[112:115]
	v_mfma_f32_16x16x32_bf16 v[100:103], v[170:173], v[194:197], v[100:103]
	v_mfma_f32_16x16x32_bf16 v[96:99], v[178:181], v[194:197], v[96:99]
	v_mfma_f32_16x16x32_bf16 v[84:87], v[170:173], v[202:205], v[84:87]
	v_mfma_f32_16x16x32_bf16 v[80:83], v[178:181], v[202:205], v[80:83]
	v_mfma_f32_16x16x32_bf16 v[68:71], v[170:173], v[212:215], v[68:71]
	v_mfma_f32_16x16x32_bf16 v[64:67], v[178:181], v[212:215], v[64:67]
	s_barrier
	s_add_i32 s40, s62, s45
	s_mov_b32 m0, s40
	ds_read_b128 v[182:185], v155 offset:49152
	ds_read_b128 v[186:189], v155 offset:50176
	ds_read_b128 v[190:193], v155 offset:51200
	ds_read_b128 v[194:197], v155 offset:52224
	ds_read_b128 v[198:201], v155 offset:53248
	ds_read_b128 v[202:205], v155 offset:54272
	ds_read_b128 v[208:211], v155 offset:55296
	ds_read_b128 v[212:215], v155 offset:56320
	global_load_lds_dwordx4 v148, s[38:39]
	s_add_i32 m0, s40, 0x2000
	s_add_u32 s38, s38, 0x40080
	s_addc_u32 s39, s39, 0
	s_add_i32 s40, s63, s45
	global_load_lds_dwordx4 v149, s[98:99]
	s_mov_b32 m0, s40
	s_nop 0
	global_load_lds_dwordx4 v128, s[38:39]
	s_add_i32 m0, s40, 0x2000
	s_nop 0
	global_load_lds_dwordx4 v130, s[38:39]
	s_mov_b32 m0, s51
	s_nop 0
	global_load_lds_dwordx4 v148, s[100:101]
	s_mov_b32 m0, s52
	s_nop 0
	global_load_lds_dwordx4 v149, s[100:101]
	s_waitcnt vmcnt(8)
	s_waitcnt lgkmcnt(0)
	s_barrier
	s_waitcnt lgkmcnt(0)
	v_mfma_f32_16x16x32_bf16 v[60:63], v[140:143], v[182:185], v[60:63]
	v_mfma_f32_16x16x32_bf16 v[56:59], v[158:161], v[182:185], v[56:59]
	v_mfma_f32_16x16x32_bf16 v[44:47], v[140:143], v[190:193], v[44:47]
	v_mfma_f32_16x16x32_bf16 v[40:43], v[158:161], v[190:193], v[40:43]
	v_mfma_f32_16x16x32_bf16 v[28:31], v[140:143], v[198:201], v[28:31]
	v_mfma_f32_16x16x32_bf16 v[24:27], v[158:161], v[198:201], v[24:27]
	v_mfma_f32_16x16x32_bf16 v[12:15], v[140:143], v[208:211], v[12:15]
	v_mfma_f32_16x16x32_bf16 v[8:11], v[158:161], v[208:211], v[8:11]
	v_mfma_f32_16x16x32_bf16 v[60:63], v[144:147], v[186:189], v[60:63]
	v_mfma_f32_16x16x32_bf16 v[56:59], v[162:165], v[186:189], v[56:59]
	v_mfma_f32_16x16x32_bf16 v[44:47], v[144:147], v[194:197], v[44:47]
	v_mfma_f32_16x16x32_bf16 v[40:43], v[162:165], v[194:197], v[40:43]
	v_mfma_f32_16x16x32_bf16 v[28:31], v[144:147], v[202:205], v[28:31]
	v_mfma_f32_16x16x32_bf16 v[24:27], v[162:165], v[202:205], v[24:27]
	v_mfma_f32_16x16x32_bf16 v[12:15], v[144:147], v[212:215], v[12:15]
	v_mfma_f32_16x16x32_bf16 v[8:11], v[162:165], v[212:215], v[8:11]
	v_mfma_f32_16x16x32_bf16 v[52:55], v[166:169], v[182:185], v[52:55]
	v_mfma_f32_16x16x32_bf16 v[48:51], v[174:177], v[182:185], v[48:51]
	v_mfma_f32_16x16x32_bf16 v[36:39], v[166:169], v[190:193], v[36:39]
	v_mfma_f32_16x16x32_bf16 v[32:35], v[174:177], v[190:193], v[32:35]
	v_mfma_f32_16x16x32_bf16 v[20:23], v[166:169], v[198:201], v[20:23]
	v_mfma_f32_16x16x32_bf16 v[16:19], v[174:177], v[198:201], v[16:19]
	v_mfma_f32_16x16x32_bf16 v[4:7], v[166:169], v[208:211], v[4:7]
	v_mfma_f32_16x16x32_bf16 v[0:3], v[174:177], v[208:211], v[0:3]
	v_mfma_f32_16x16x32_bf16 v[52:55], v[170:173], v[186:189], v[52:55]
	v_mfma_f32_16x16x32_bf16 v[48:51], v[178:181], v[186:189], v[48:51]
	v_mfma_f32_16x16x32_bf16 v[36:39], v[170:173], v[194:197], v[36:39]
	v_mfma_f32_16x16x32_bf16 v[32:35], v[178:181], v[194:197], v[32:35]
	v_mfma_f32_16x16x32_bf16 v[20:23], v[170:173], v[202:205], v[20:23]
	v_mfma_f32_16x16x32_bf16 v[16:19], v[178:181], v[202:205], v[16:19]
	v_mfma_f32_16x16x32_bf16 v[4:7], v[170:173], v[212:215], v[4:7]
	v_mfma_f32_16x16x32_bf16 v[0:3], v[178:181], v[212:215], v[0:3]
	s_barrier
	s_add_i32 s61, s61, 2
	s_add_u32 s59, s59, 0x100
	s_addc_u32 s60, s60, 0
	s_add_u32 s36, s36, 0x100
	s_addc_u32 s37, s37, 0
	s_cmp_gt_u32 s61, 13
	s_cbranch_scc0 .LBB0_895
	s_and_b64 vcc, exec, s[24:25]
	s_cbranch_vccz .LBB0_898
	s_barrier

.LBB0_988:
	ds_read_b128 v[144:147], v151
	ds_read_b128 v[156:159], v151 offset:1024
	ds_read_b128 v[160:163], v151 offset:2048
	ds_read_b128 v[164:167], v151 offset:3072
	ds_read_b128 v[168:171], v152
	ds_read_b128 v[172:175], v152 offset:1024
	ds_read_b128 v[176:179], v152 offset:2048
	ds_read_b128 v[180:183], v152 offset:3072
	s_add_u32 s26, s6, 0xfffc0080
	s_addc_u32 s27, s7, -1
	s_cmp_eq_u32 s53, 12
	s_cselect_b32 s29, s19, s27
	s_cselect_b32 s28, s49, s26
	s_cselect_b32 s27, s17, s52
	s_cselect_b32 s26, s50, s51
	s_add_i32 m0, s25, 0xc000
	ds_read_b128 v[184:187], v153
	ds_read_b128 v[188:191], v153 offset:1024
	ds_read_b128 v[192:195], v153 offset:2048
	ds_read_b128 v[196:199], v153 offset:3072
	ds_read_b128 v[200:203], v153 offset:4096
	ds_read_b128 v[208:211], v153 offset:5120
	ds_read_b128 v[212:215], v153 offset:6144
	ds_read_b128 v[216:219], v153 offset:7168
	global_load_lds_dwordx4 v138, s[6:7]
	s_add_i32 m0, s25, 0xe000
	s_nop 0
	global_load_lds_dwordx4 v136, s[6:7]
	s_waitcnt vmcnt(8)
	s_waitcnt lgkmcnt(0)
	s_barrier
	s_waitcnt lgkmcnt(0)
	s_nop 0
	v_mfma_f32_16x16x32_bf16 v[124:127], v[144:147], v[184:187], v[124:127]
	v_mfma_f32_16x16x32_bf16 v[120:123], v[160:163], v[184:187], v[120:123]
	v_mfma_f32_16x16x32_bf16 v[108:111], v[144:147], v[192:195], v[108:111]
	v_mfma_f32_16x16x32_bf16 v[104:107], v[160:163], v[192:195], v[104:107]
	v_mfma_f32_16x16x32_bf16 v[92:95], v[144:147], v[200:203], v[92:95]
	v_mfma_f32_16x16x32_bf16 v[88:91], v[160:163], v[200:203], v[88:91]
	v_mfma_f32_16x16x32_bf16 v[76:79], v[144:147], v[212:215], v[76:79]
	v_mfma_f32_16x16x32_bf16 v[72:75], v[160:163], v[212:215], v[72:75]
	v_mfma_f32_16x16x32_bf16 v[124:127], v[156:159], v[188:191], v[124:127]
	v_mfma_f32_16x16x32_bf16 v[120:123], v[164:167], v[188:191], v[120:123]
	v_mfma_f32_16x16x32_bf16 v[108:111], v[156:159], v[196:199], v[108:111]
	v_mfma_f32_16x16x32_bf16 v[104:107], v[164:167], v[196:199], v[104:107]
	v_mfma_f32_16x16x32_bf16 v[92:95], v[156:159], v[208:211], v[92:95]
	v_mfma_f32_16x16x32_bf16 v[88:91], v[164:167], v[208:211], v[88:91]
	v_mfma_f32_16x16x32_bf16 v[76:79], v[156:159], v[216:219], v[76:79]
	v_mfma_f32_16x16x32_bf16 v[72:75], v[164:167], v[216:219], v[72:75]
	v_mfma_f32_16x16x32_bf16 v[116:119], v[168:171], v[184:187], v[116:119]
	v_mfma_f32_16x16x32_bf16 v[112:115], v[176:179], v[184:187], v[112:115]
	v_mfma_f32_16x16x32_bf16 v[100:103], v[168:171], v[192:195], v[100:103]
	v_mfma_f32_16x16x32_bf16 v[96:99], v[176:179], v[192:195], v[96:99]
	v_mfma_f32_16x16x32_bf16 v[84:87], v[168:171], v[200:203], v[84:87]
	v_mfma_f32_16x16x32_bf16 v[80:83], v[176:179], v[200:203], v[80:83]
	v_mfma_f32_16x16x32_bf16 v[68:71], v[168:171], v[212:215], v[68:71]
	v_mfma_f32_16x16x32_bf16 v[64:67], v[176:179], v[212:215], v[64:67]
	v_mfma_f32_16x16x32_bf16 v[116:119], v[172:175], v[188:191], v[116:119]
	v_mfma_f32_16x16x32_bf16 v[112:115], v[180:183], v[188:191], v[112:115]
	v_mfma_f32_16x16x32_bf16 v[100:103], v[172:175], v[196:199], v[100:103]
	v_mfma_f32_16x16x32_bf16 v[96:99], v[180:183], v[196:199], v[96:99]
	v_mfma_f32_16x16x32_bf16 v[84:87], v[172:175], v[208:211], v[84:87]
	v_mfma_f32_16x16x32_bf16 v[80:83], v[180:183], v[208:211], v[80:83]
	v_mfma_f32_16x16x32_bf16 v[68:71], v[172:175], v[216:219], v[68:71]
	v_mfma_f32_16x16x32_bf16 v[64:67], v[180:183], v[216:219], v[64:67]
	s_barrier
	s_add_i32 s54, s45, s38
	s_mov_b32 m0, s54
	ds_read_b128 v[184:187], v153 offset:16384
	ds_read_b128 v[188:191], v153 offset:17408
	ds_read_b128 v[192:195], v153 offset:18432
	ds_read_b128 v[196:199], v153 offset:19456
	ds_read_b128 v[200:203], v153 offset:20480
	ds_read_b128 v[208:211], v153 offset:21504
	ds_read_b128 v[212:215], v153 offset:22528
	ds_read_b128 v[216:219], v153 offset:23552
	global_load_lds_dwordx4 v130, s[26:27]
	s_add_i32 m0, s54, 0x2000
	s_add_u32 s54, s26, 0x40000
	s_mov_b64 s[98:99], s[26:27]
	s_addc_u32 s55, s27, 0
	s_add_i32 s56, s46, s38
	global_load_lds_dwordx4 v134, s[26:27]
	s_mov_b32 m0, s56
	s_mov_b64 s[100:101], s[28:29]
	global_load_lds_dwordx4 v130, s[54:55]
	s_add_i32 m0, s56, 0x2000
	s_nop 0
	global_load_lds_dwordx4 v134, s[54:55]
	s_mov_b32 m0, s25
	s_nop 0
	global_load_lds_dwordx4 v128, s[28:29]
	s_mov_b32 m0, s39
	s_nop 0
	global_load_lds_dwordx4 v132, s[28:29]
	s_waitcnt vmcnt(8)
	s_waitcnt lgkmcnt(0)
	s_barrier
	s_waitcnt lgkmcnt(0)
	s_nop 0
	v_mfma_f32_16x16x32_bf16 v[60:63], v[144:147], v[184:187], v[60:63]
	v_mfma_f32_16x16x32_bf16 v[56:59], v[160:163], v[184:187], v[56:59]
	v_mfma_f32_16x16x32_bf16 v[44:47], v[144:147], v[192:195], v[44:47]
	v_mfma_f32_16x16x32_bf16 v[40:43], v[160:163], v[192:195], v[40:43]
	v_mfma_f32_16x16x32_bf16 v[28:31], v[144:147], v[200:203], v[28:31]
	v_mfma_f32_16x16x32_bf16 v[24:27], v[160:163], v[200:203], v[24:27]
	v_mfma_f32_16x16x32_bf16 v[12:15], v[144:147], v[212:215], v[12:15]
	v_mfma_f32_16x16x32_bf16 v[8:11], v[160:163], v[212:215], v[8:11]
	v_mfma_f32_16x16x32_bf16 v[60:63], v[156:159], v[188:191], v[60:63]
	v_mfma_f32_16x16x32_bf16 v[56:59], v[164:167], v[188:191], v[56:59]
	v_mfma_f32_16x16x32_bf16 v[44:47], v[156:159], v[196:199], v[44:47]
	v_mfma_f32_16x16x32_bf16 v[40:43], v[164:167], v[196:199], v[40:43]
	v_mfma_f32_16x16x32_bf16 v[28:31], v[156:159], v[208:211], v[28:31]
	v_mfma_f32_16x16x32_bf16 v[24:27], v[164:167], v[208:211], v[24:27]
	v_mfma_f32_16x16x32_bf16 v[12:15], v[156:159], v[216:219], v[12:15]
	v_mfma_f32_16x16x32_bf16 v[8:11], v[164:167], v[216:219], v[8:11]
	v_mfma_f32_16x16x32_bf16 v[52:55], v[168:171], v[184:187], v[52:55]
	v_mfma_f32_16x16x32_bf16 v[48:51], v[176:179], v[184:187], v[48:51]
	v_mfma_f32_16x16x32_bf16 v[36:39], v[168:171], v[192:195], v[36:39]
	v_mfma_f32_16x16x32_bf16 v[32:35], v[176:179], v[192:195], v[32:35]
	v_mfma_f32_16x16x32_bf16 v[20:23], v[168:171], v[200:203], v[20:23]
	v_mfma_f32_16x16x32_bf16 v[16:19], v[176:179], v[200:203], v[16:19]
	v_mfma_f32_16x16x32_bf16 v[4:7], v[168:171], v[212:215], v[4:7]
	v_mfma_f32_16x16x32_bf16 v[0:3], v[176:179], v[212:215], v[0:3]
	v_mfma_f32_16x16x32_bf16 v[52:55], v[172:175], v[188:191], v[52:55]
	v_mfma_f32_16x16x32_bf16 v[48:51], v[180:183], v[188:191], v[48:51]
	v_mfma_f32_16x16x32_bf16 v[36:39], v[172:175], v[196:199], v[36:39]
	v_mfma_f32_16x16x32_bf16 v[32:35], v[180:183], v[196:199], v[32:35]
	v_mfma_f32_16x16x32_bf16 v[20:23], v[172:175], v[208:211], v[20:23]
	v_mfma_f32_16x16x32_bf16 v[16:19], v[180:183], v[208:211], v[16:19]
	v_mfma_f32_16x16x32_bf16 v[4:7], v[172:175], v[216:219], v[4:7]
	v_mfma_f32_16x16x32_bf16 v[0:3], v[180:183], v[216:219], v[0:3]
	s_barrier
	s_add_i32 s54, 0, 0x18000
	v_add_u32_e32 v155, s54, v149
	s_add_i32 s55, 0, 0x1c000
	ds_read_b128 v[144:147], v155
	ds_read_b128 v[156:159], v155 offset:1024
	ds_read_b128 v[160:163], v155 offset:2048
	ds_read_b128 v[164:167], v155 offset:3072
	v_add_u32_e32 v155, s55, v149
	ds_read_b128 v[168:171], v155
	ds_read_b128 v[172:175], v155 offset:1024
	ds_read_b128 v[176:179], v155 offset:2048
	ds_read_b128 v[180:183], v155 offset:3072
	s_add_u32 s28, s28, 0x40000
	s_addc_u32 s29, s29, 0
	s_mov_b32 m0, s40
	ds_read_b128 v[184:187], v153 offset:32768
	ds_read_b128 v[188:191], v153 offset:33792
	ds_read_b128 v[192:195], v153 offset:34816
	ds_read_b128 v[196:199], v153 offset:35840
	ds_read_b128 v[200:203], v153 offset:36864
	ds_read_b128 v[208:211], v153 offset:37888
	ds_read_b128 v[212:215], v153 offset:38912
	ds_read_b128 v[216:219], v153 offset:39936
	global_load_lds_dwordx4 v128, s[28:29]
	s_mov_b32 m0, s41
	s_nop 0
	global_load_lds_dwordx4 v132, s[28:29]
	s_waitcnt vmcnt(8)
	s_waitcnt lgkmcnt(0)
	s_barrier
	s_waitcnt lgkmcnt(0)
	s_nop 0
	v_mfma_f32_16x16x32_bf16 v[124:127], v[144:147], v[184:187], v[124:127]
	v_mfma_f32_16x16x32_bf16 v[120:123], v[160:163], v[184:187], v[120:123]
	v_mfma_f32_16x16x32_bf16 v[108:111], v[144:147], v[192:195], v[108:111]
	v_mfma_f32_16x16x32_bf16 v[104:107], v[160:163], v[192:195], v[104:107]
	v_mfma_f32_16x16x32_bf16 v[92:95], v[144:147], v[200:203], v[92:95]
	v_mfma_f32_16x16x32_bf16 v[88:91], v[160:163], v[200:203], v[88:91]
	v_mfma_f32_16x16x32_bf16 v[76:79], v[144:147], v[212:215], v[76:79]
	v_mfma_f32_16x16x32_bf16 v[72:75], v[160:163], v[212:215], v[72:75]
	v_mfma_f32_16x16x32_bf16 v[124:127], v[156:159], v[188:191], v[124:127]
	v_mfma_f32_16x16x32_bf16 v[120:123], v[164:167], v[188:191], v[120:123]
	v_mfma_f32_16x16x32_bf16 v[108:111], v[156:159], v[196:199], v[108:111]
	v_mfma_f32_16x16x32_bf16 v[104:107], v[164:167], v[196:199], v[104:107]
	v_mfma_f32_16x16x32_bf16 v[92:95], v[156:159], v[208:211], v[92:95]
	v_mfma_f32_16x16x32_bf16 v[88:91], v[164:167], v[208:211], v[88:91]
	v_mfma_f32_16x16x32_bf16 v[76:79], v[156:159], v[216:219], v[76:79]
	v_mfma_f32_16x16x32_bf16 v[72:75], v[164:167], v[216:219], v[72:75]
	v_mfma_f32_16x16x32_bf16 v[116:119], v[168:171], v[184:187], v[116:119]
	v_mfma_f32_16x16x32_bf16 v[112:115], v[176:179], v[184:187], v[112:115]
	v_mfma_f32_16x16x32_bf16 v[100:103], v[168:171], v[192:195], v[100:103]
	v_mfma_f32_16x16x32_bf16 v[96:99], v[176:179], v[192:195], v[96:99]
	v_mfma_f32_16x16x32_bf16 v[84:87], v[168:171], v[200:203], v[84:87]
	v_mfma_f32_16x16x32_bf16 v[80:83], v[176:179], v[200:203], v[80:83]
	v_mfma_f32_16x16x32_bf16 v[68:71], v[168:171], v[212:215], v[68:71]
	v_mfma_f32_16x16x32_bf16 v[64:67], v[176:179], v[212:215], v[64:67]
	v_mfma_f32_16x16x32_bf16 v[116:119], v[172:175], v[188:191], v[116:119]
	v_mfma_f32_16x16x32_bf16 v[112:115], v[180:183], v[188:191], v[112:115]
	v_mfma_f32_16x16x32_bf16 v[100:103], v[172:175], v[196:199], v[100:103]
	v_mfma_f32_16x16x32_bf16 v[96:99], v[180:183], v[196:199], v[96:99]
	v_mfma_f32_16x16x32_bf16 v[84:87], v[172:175], v[208:211], v[84:87]
	v_mfma_f32_16x16x32_bf16 v[80:83], v[180:183], v[208:211], v[80:83]
	v_mfma_f32_16x16x32_bf16 v[68:71], v[172:175], v[216:219], v[68:71]
	v_mfma_f32_16x16x32_bf16 v[64:67], v[180:183], v[216:219], v[64:67]
	s_barrier
	s_add_i32 s28, s54, s38
	s_mov_b32 m0, s28
	ds_read_b128 v[184:187], v153 offset:49152
	ds_read_b128 v[188:191], v153 offset:50176
	ds_read_b128 v[192:195], v153 offset:51200
	ds_read_b128 v[196:199], v153 offset:52224
	ds_read_b128 v[200:203], v153 offset:53248
	ds_read_b128 v[208:211], v153 offset:54272
	ds_read_b128 v[212:215], v153 offset:55296
	ds_read_b128 v[216:219], v153 offset:56320
	global_load_lds_dwordx4 v205, s[26:27]
	s_add_i32 m0, s28, 0x2000
	s_add_u32 s26, s26, 0x40080
	s_addc_u32 s27, s27, 0
	s_add_i32 s28, s55, s38
	global_load_lds_dwordx4 v221, s[98:99]
	s_mov_b32 m0, s28
	s_nop 0
	global_load_lds_dwordx4 v130, s[26:27]
	s_add_i32 m0, s28, 0x2000
	s_nop 0
	global_load_lds_dwordx4 v134, s[26:27]
	s_mov_b32 m0, s43
	s_nop 0
	global_load_lds_dwordx4 v204, s[100:101]
	s_mov_b32 m0, s44
	s_nop 0
	global_load_lds_dwordx4 v220, s[100:101]
	s_waitcnt vmcnt(8)
	s_waitcnt lgkmcnt(0)
	s_barrier
	s_waitcnt lgkmcnt(0)
	v_mfma_f32_16x16x32_bf16 v[60:63], v[144:147], v[184:187], v[60:63]
	v_mfma_f32_16x16x32_bf16 v[56:59], v[160:163], v[184:187], v[56:59]
	v_mfma_f32_16x16x32_bf16 v[44:47], v[144:147], v[192:195], v[44:47]
	v_mfma_f32_16x16x32_bf16 v[40:43], v[160:163], v[192:195], v[40:43]
	v_mfma_f32_16x16x32_bf16 v[28:31], v[144:147], v[200:203], v[28:31]
	v_mfma_f32_16x16x32_bf16 v[24:27], v[160:163], v[200:203], v[24:27]
	v_mfma_f32_16x16x32_bf16 v[12:15], v[144:147], v[212:215], v[12:15]
	v_mfma_f32_16x16x32_bf16 v[8:11], v[160:163], v[212:215], v[8:11]
	v_mfma_f32_16x16x32_bf16 v[60:63], v[156:159], v[188:191], v[60:63]
	v_mfma_f32_16x16x32_bf16 v[56:59], v[164:167], v[188:191], v[56:59]
	v_mfma_f32_16x16x32_bf16 v[44:47], v[156:159], v[196:199], v[44:47]
	v_mfma_f32_16x16x32_bf16 v[40:43], v[164:167], v[196:199], v[40:43]
	v_mfma_f32_16x16x32_bf16 v[28:31], v[156:159], v[208:211], v[28:31]
	v_mfma_f32_16x16x32_bf16 v[24:27], v[164:167], v[208:211], v[24:27]
	v_mfma_f32_16x16x32_bf16 v[12:15], v[156:159], v[216:219], v[12:15]
	v_mfma_f32_16x16x32_bf16 v[8:11], v[164:167], v[216:219], v[8:11]
	v_mfma_f32_16x16x32_bf16 v[52:55], v[168:171], v[184:187], v[52:55]
	v_mfma_f32_16x16x32_bf16 v[48:51], v[176:179], v[184:187], v[48:51]
	v_mfma_f32_16x16x32_bf16 v[36:39], v[168:171], v[192:195], v[36:39]
	v_mfma_f32_16x16x32_bf16 v[32:35], v[176:179], v[192:195], v[32:35]
	v_mfma_f32_16x16x32_bf16 v[20:23], v[168:171], v[200:203], v[20:23]
	v_mfma_f32_16x16x32_bf16 v[16:19], v[176:179], v[200:203], v[16:19]
	v_mfma_f32_16x16x32_bf16 v[4:7], v[168:171], v[212:215], v[4:7]
	v_mfma_f32_16x16x32_bf16 v[0:3], v[176:179], v[212:215], v[0:3]
	v_mfma_f32_16x16x32_bf16 v[52:55], v[172:175], v[188:191], v[52:55]
	v_mfma_f32_16x16x32_bf16 v[48:51], v[180:183], v[188:191], v[48:51]
	v_mfma_f32_16x16x32_bf16 v[36:39], v[172:175], v[196:199], v[36:39]
	v_mfma_f32_16x16x32_bf16 v[32:35], v[180:183], v[196:199], v[32:35]
	v_mfma_f32_16x16x32_bf16 v[20:23], v[172:175], v[208:211], v[20:23]
	v_mfma_f32_16x16x32_bf16 v[16:19], v[180:183], v[208:211], v[16:19]
	v_mfma_f32_16x16x32_bf16 v[4:7], v[172:175], v[216:219], v[4:7]
	v_mfma_f32_16x16x32_bf16 v[0:3], v[180:183], v[216:219], v[0:3]
	s_barrier
	s_add_i32 s53, s53, 2
	s_add_u32 s51, s51, 0x100
	s_addc_u32 s52, s52, 0
	s_add_u32 s6, s6, 0x100
	s_addc_u32 s7, s7, 0
	s_cmp_gt_u32 s53, 13
	s_cbranch_scc0 .LBB0_988
	s_and_b64 vcc, exec, s[14:15]
	s_cbranch_vccz .LBB0_991
	s_barrier

.LBB0_1103:
	s_cmpk_eq_i32 s2, 0xffc0
	s_cbranch_scc1 .LBB0_1106
	s_andn2_b64 vcc, exec, s[24:25]
	s_cbranch_vccnz .LBB0_1106
	s_and_b32 s38, s2, 64
	s_mulk_i32 s38, 0x110
	v_add_u32_e32 v66, s38, v125
	ds_read_b128 v[8:11], v66
	ds_read_b128 v[12:15], v66 offset:64
	ds_read_b128 v[148:151], v66 offset:128
	ds_read_b128 v[152:155], v66 offset:192
	v_lshlrev_b32_e32 v66, 16, v143
	s_waitcnt lgkmcnt(3)
	s_nop 0
	v_mfma_f32_16x16x32_bf16 v[8:11], v[8:11], v[48:51], 0
	v_and_b32_e32 v143, 0xffff0000, v143
	v_lshlrev_b32_e32 v147, 16, v107
	v_lshl_add_u64 v[156:157], v[116:117], 0, s[2:3]
	s_waitcnt lgkmcnt(2)
	v_mfma_f32_16x16x32_bf16 v[8:11], v[12:15], v[44:47], v[8:11]
	v_lshlrev_b64 v[12:13], 10, v[156:157]
	v_lshl_add_u64 v[14:15], v[110:111], 0, v[12:13]
	s_waitcnt lgkmcnt(1)
	s_nop 0
	v_mfma_f32_16x16x32_bf16 v[8:11], v[148:151], v[40:43], v[8:11]
	v_or_b32_e32 v148, 0x400, v12
	v_mov_b32_e32 v149, v13
	s_waitcnt lgkmcnt(0)
	v_mfma_f32_16x16x32_bf16 v[8:11], v[152:155], v[36:39], v[8:11]
	s_nop 7
	v_fma_f32 v8, v142, v66, v8
	v_mul_f32_e32 v66, 0x3d372713, v8
	v_fma_f32 v9, v142, v143, v9
	v_mul_f32_e32 v66, v8, v66
	v_mul_f32_e32 v143, 0x3d372713, v9
	v_fma_f32 v66, v8, v66, v8
	v_mul_f32_e32 v143, v9, v143
	v_mul_f32_e32 v66, 0xbfcc422a, v66
	v_fma_f32 v143, v9, v143, v9
	v_mul_f32_e32 v66, 0x3fb8aa3b, v66
	v_mul_f32_e32 v143, 0xbfcc422a, v143
	v_exp_f32_e32 v66, v66
	v_mul_f32_e32 v143, 0x3fb8aa3b, v143
	v_exp_f32_e32 v143, v143
	v_fma_f32 v10, v142, v147, v10
	v_add_f32_e32 v66, 1.0, v66
	v_rcp_f32_e32 v66, v66
	v_add_f32_e32 v143, 1.0, v143
	v_mul_f32_e32 v147, 0x3d372713, v10
	v_rcp_f32_e32 v143, v143
	v_mul_f32_e32 v147, v10, v147
	v_fma_f32 v147, v10, v147, v10
	v_mul_f32_e32 v8, v8, v66
	v_mul_f32_e32 v147, 0xbfcc422a, v147
	v_cvt_pk_bf16_f32 v8, v8, s0
	v_mul_f32_e32 v9, v9, v143
	global_store_short v[14:15], v8, off
	v_mul_f32_e32 v8, 0x3fb8aa3b, v147
	v_cvt_pk_bf16_f32 v66, v9, s0
	v_exp_f32_e32 v14, v8
	v_lshl_add_u64 v[8:9], v[110:111], 0, v[148:149]
	global_store_short v[8:9], v66, off
	v_and_b32_e32 v9, 0xffff0000, v107
	v_fmac_f32_e32 v11, v142, v9
	v_mul_f32_e32 v9, 0x3d372713, v11
	v_mul_f32_e32 v9, v11, v9
	v_fma_f32 v9, v11, v9, v11
	v_mul_f32_e32 v9, 0xbfcc422a, v9
	v_mul_f32_e32 v9, 0x3fb8aa3b, v9
	v_exp_f32_e32 v9, v9
	v_add_f32_e32 v8, 1.0, v14
	v_rcp_f32_e32 v8, v8
	v_add_f32_e32 v9, 1.0, v9
	v_rcp_f32_e32 v14, v9
	v_mul_f32_e32 v8, v10, v8
	v_cvt_pk_bf16_f32 v10, v8, s0
	v_or_b32_e32 v8, 0x800, v12
	v_mov_b32_e32 v9, v13
	v_lshl_add_u64 v[8:9], v[110:111], 0, v[8:9]
	global_store_short v[8:9], v10, off
	v_mul_f32_e32 v8, v11, v14
	v_or_b32_e32 v12, 0xc00, v12
	v_cvt_pk_bf16_f32 v10, v8, s0
	v_lshl_add_u64 v[8:9], v[110:111], 0, v[12:13]
	global_store_short v[8:9], v10, off
	v_lshl_add_u64 v[8:9], v[120:121], 0, s[30:31]
	v_or_b32_e32 v12, 0x1000, v8
	v_mov_b32_e32 v13, v9
	v_or_b32_e32 v14, 0x2000, v8
	v_or_b32_e32 v8, 0x3000, v8
	v_lshl_add_u64 v[10:11], v[112:113], 0, v[120:121]
	v_lshl_add_u64 v[12:13], v[118:119], 0, v[12:13]
	v_mov_b32_e32 v15, v9
	v_lshl_add_u64 v[8:9], v[118:119], 0, v[8:9]
	v_lshl_add_u64 v[14:15], v[118:119], 0, v[14:15]
	global_load_ushort v10, v[10:11], off
	s_nop 0
	global_load_ushort v11, v[12:13], off
	s_nop 0
	global_load_ushort v12, v[14:15], off
	s_nop 0
	global_load_ushort v8, v[8:9], off
	s_mov_b32 s100, 1

.LBB0_1109:
	s_andn2_b64 vcc, exec, s[26:27]
	s_cbranch_vccnz .LBB0_1050
	ds_read_b128 v[0:3], v133
	ds_read_b128 v[4:7], v133 offset:64
	ds_read_b128 v[8:11], v133 offset:128
	ds_read_b128 v[12:15], v133 offset:192
	s_waitcnt lgkmcnt(3)
	s_nop 0
	v_mfma_f32_16x16x32_bf16 v[0:3], v[0:3], v[48:51], 0
	v_mov_b32_e32 v49, s37
	v_or_b32_e32 v48, s36, v88
	s_waitcnt lgkmcnt(2)
	s_nop 0
	v_mfma_f32_16x16x32_bf16 v[0:3], v[4:7], v[44:47], v[0:3]
	v_lshlrev_b32_e32 v44, 16, v143
	v_and_b32_e32 v45, 0xffff0000, v143
	v_lshlrev_b32_e32 v46, 16, v107
	s_waitcnt lgkmcnt(1)
	s_nop 0
	v_mfma_f32_16x16x32_bf16 v[0:3], v[8:11], v[40:43], v[0:3]
	v_lshlrev_b64 v[4:5], 10, v[48:49]
	v_lshl_add_u64 v[6:7], v[110:111], 0, v[4:5]
	v_or_b32_e32 v8, 0x400, v4
	s_waitcnt lgkmcnt(0)
	s_nop 0
	v_mfma_f32_16x16x32_bf16 v[0:3], v[12:15], v[36:39], v[0:3]
	s_nop 7
	v_fma_f32 v0, v142, v44, v0
	v_mul_f32_e32 v9, 0x3d372713, v0
	v_mul_f32_e32 v9, v0, v9
	v_fma_f32 v1, v142, v45, v1
	v_fma_f32 v9, v0, v9, v0
	v_mul_f32_e32 v10, 0x3d372713, v1
	v_mul_f32_e32 v9, 0xbfcc422a, v9
	v_mul_f32_e32 v10, v1, v10
	v_mul_f32_e32 v9, 0x3fb8aa3b, v9
	v_fma_f32 v10, v1, v10, v1
	v_exp_f32_e32 v9, v9
	v_mul_f32_e32 v10, 0xbfcc422a, v10
	v_mul_f32_e32 v10, 0x3fb8aa3b, v10
	v_exp_f32_e32 v10, v10
	v_add_f32_e32 v9, 1.0, v9
	v_rcp_f32_e32 v9, v9
	v_fma_f32 v2, v142, v46, v2
	v_add_f32_e32 v10, 1.0, v10
	v_mul_f32_e32 v11, 0x3d372713, v2
	v_rcp_f32_e32 v10, v10
	v_mul_f32_e32 v11, v2, v11
	v_mul_f32_e32 v0, v0, v9
	v_fma_f32 v11, v2, v11, v2
	v_cvt_pk_bf16_f32 v0, v0, s0
	global_store_short v[6:7], v0, off
	v_mul_f32_e32 v0, 0xbfcc422a, v11
	v_mul_f32_e32 v1, v1, v10
	v_mul_f32_e32 v0, 0x3fb8aa3b, v0
	v_mov_b32_e32 v9, v5
	v_cvt_pk_bf16_f32 v10, v1, s0
	v_exp_f32_e32 v6, v0
	v_lshl_add_u64 v[0:1], v[110:111], 0, v[8:9]
	global_store_short v[0:1], v10, off
	v_and_b32_e32 v1, 0xffff0000, v107
	v_fmac_f32_e32 v3, v142, v1
	v_mul_f32_e32 v1, 0x3d372713, v3
	v_mul_f32_e32 v1, v3, v1
	v_fma_f32 v1, v3, v1, v3
	v_mul_f32_e32 v1, 0xbfcc422a, v1
	v_mul_f32_e32 v1, 0x3fb8aa3b, v1
	v_exp_f32_e32 v1, v1
	v_add_f32_e32 v0, 1.0, v6
	v_rcp_f32_e32 v0, v0
	v_add_f32_e32 v1, 1.0, v1
	v_rcp_f32_e32 v6, v1
	v_mul_f32_e32 v0, v2, v0
	v_cvt_pk_bf16_f32 v2, v0, s0
	v_or_b32_e32 v0, 0x800, v4
	v_mov_b32_e32 v1, v5
	v_lshl_add_u64 v[0:1], v[110:111], 0, v[0:1]
	global_store_short v[0:1], v2, off
	v_mul_f32_e32 v0, v3, v6
	v_or_b32_e32 v4, 0xc00, v4
	v_cvt_pk_bf16_f32 v2, v0, s0
	v_lshl_add_u64 v[0:1], v[110:111], 0, v[4:5]
	global_store_short v[0:1], v2, off
	s_branch .LBB0_1050

.LBB0_1193:
	ds_read_b128 v[144:147], v151
	ds_read_b128 v[154:157], v151 offset:1024
	ds_read_b128 v[158:161], v151 offset:2048
	ds_read_b128 v[162:165], v151 offset:3072
	ds_read_b128 v[166:169], v152
	ds_read_b128 v[170:173], v152 offset:1024
	ds_read_b128 v[174:177], v152 offset:2048
	ds_read_b128 v[178:181], v152 offset:3072
	s_add_u32 s26, s24, 0xfffe0080
	s_addc_u32 s27, s25, -1
	s_cmp_eq_u32 s50, 4
	s_cselect_b32 s29, s17, s27
	s_cselect_b32 s28, s46, s26
	s_cselect_b32 s27, s15, s49
	s_cselect_b32 s26, s47, s48
	s_add_i32 m0, s23, 0xc000
	ds_read_b128 v[182:185], v153
	ds_read_b128 v[186:189], v153 offset:1024
	ds_read_b128 v[190:193], v153 offset:2048
	ds_read_b128 v[194:197], v153 offset:3072
	ds_read_b128 v[198:201], v153 offset:4096
	ds_read_b128 v[202:205], v153 offset:5120
	ds_read_b128 v[208:211], v153 offset:6144
	ds_read_b128 v[212:215], v153 offset:7168
	global_load_lds_dwordx4 v138, s[24:25]
	s_add_i32 m0, s23, 0xe000
	s_nop 0
	global_load_lds_dwordx4 v136, s[24:25]
	s_waitcnt vmcnt(8)
	s_waitcnt lgkmcnt(0)
	s_barrier
	s_waitcnt lgkmcnt(0)
	s_nop 0
	v_mfma_f32_16x16x32_bf16 v[124:127], v[144:147], v[182:185], v[124:127]
	v_mfma_f32_16x16x32_bf16 v[120:123], v[158:161], v[182:185], v[120:123]
	v_mfma_f32_16x16x32_bf16 v[108:111], v[144:147], v[190:193], v[108:111]
	v_mfma_f32_16x16x32_bf16 v[104:107], v[158:161], v[190:193], v[104:107]
	v_mfma_f32_16x16x32_bf16 v[92:95], v[144:147], v[198:201], v[92:95]
	v_mfma_f32_16x16x32_bf16 v[88:91], v[158:161], v[198:201], v[88:91]
	v_mfma_f32_16x16x32_bf16 v[76:79], v[144:147], v[208:211], v[76:79]
	v_mfma_f32_16x16x32_bf16 v[72:75], v[158:161], v[208:211], v[72:75]
	v_mfma_f32_16x16x32_bf16 v[124:127], v[154:157], v[186:189], v[124:127]
	v_mfma_f32_16x16x32_bf16 v[120:123], v[162:165], v[186:189], v[120:123]
	v_mfma_f32_16x16x32_bf16 v[108:111], v[154:157], v[194:197], v[108:111]
	v_mfma_f32_16x16x32_bf16 v[104:107], v[162:165], v[194:197], v[104:107]
	v_mfma_f32_16x16x32_bf16 v[92:95], v[154:157], v[202:205], v[92:95]
	v_mfma_f32_16x16x32_bf16 v[88:91], v[162:165], v[202:205], v[88:91]
	v_mfma_f32_16x16x32_bf16 v[76:79], v[154:157], v[212:215], v[76:79]
	v_mfma_f32_16x16x32_bf16 v[72:75], v[162:165], v[212:215], v[72:75]
	v_mfma_f32_16x16x32_bf16 v[116:119], v[166:169], v[182:185], v[116:119]
	v_mfma_f32_16x16x32_bf16 v[112:115], v[174:177], v[182:185], v[112:115]
	v_mfma_f32_16x16x32_bf16 v[100:103], v[166:169], v[190:193], v[100:103]
	v_mfma_f32_16x16x32_bf16 v[96:99], v[174:177], v[190:193], v[96:99]
	v_mfma_f32_16x16x32_bf16 v[84:87], v[166:169], v[198:201], v[84:87]
	v_mfma_f32_16x16x32_bf16 v[80:83], v[174:177], v[198:201], v[80:83]
	v_mfma_f32_16x16x32_bf16 v[68:71], v[166:169], v[208:211], v[68:71]
	v_mfma_f32_16x16x32_bf16 v[64:67], v[174:177], v[208:211], v[64:67]
	v_mfma_f32_16x16x32_bf16 v[116:119], v[170:173], v[186:189], v[116:119]
	v_mfma_f32_16x16x32_bf16 v[112:115], v[178:181], v[186:189], v[112:115]
	v_mfma_f32_16x16x32_bf16 v[100:103], v[170:173], v[194:197], v[100:103]
	v_mfma_f32_16x16x32_bf16 v[96:99], v[178:181], v[194:197], v[96:99]
	v_mfma_f32_16x16x32_bf16 v[84:87], v[170:173], v[202:205], v[84:87]
	v_mfma_f32_16x16x32_bf16 v[80:83], v[178:181], v[202:205], v[80:83]
	v_mfma_f32_16x16x32_bf16 v[68:71], v[170:173], v[212:215], v[68:71]
	v_mfma_f32_16x16x32_bf16 v[64:67], v[178:181], v[212:215], v[64:67]
	s_barrier
	s_add_i32 s51, s43, s36
	s_mov_b32 m0, s51
	ds_read_b128 v[182:185], v153 offset:16384
	ds_read_b128 v[186:189], v153 offset:17408
	ds_read_b128 v[190:193], v153 offset:18432
	ds_read_b128 v[194:197], v153 offset:19456
	ds_read_b128 v[198:201], v153 offset:20480
	ds_read_b128 v[202:205], v153 offset:21504
	ds_read_b128 v[208:211], v153 offset:22528
	ds_read_b128 v[212:215], v153 offset:23552
	global_load_lds_dwordx4 v130, s[26:27]
	s_add_i32 m0, s51, 0x2000
	s_add_u32 s52, s26, 0x20000
	s_mov_b64 s[98:99], s[26:27]
	s_addc_u32 s53, s27, 0
	s_add_i32 s51, s44, s36
	global_load_lds_dwordx4 v134, s[26:27]
	s_mov_b32 m0, s51
	s_mov_b64 s[100:101], s[28:29]
	global_load_lds_dwordx4 v130, s[52:53]
	s_add_i32 m0, s51, 0x2000
	s_nop 0
	global_load_lds_dwordx4 v134, s[52:53]
	s_mov_b32 m0, s23
	s_nop 0
	global_load_lds_dwordx4 v128, s[28:29]
	s_mov_b32 m0, s37
	s_nop 0
	global_load_lds_dwordx4 v132, s[28:29]
	s_waitcnt vmcnt(8)
	s_waitcnt lgkmcnt(0)
	s_barrier
	s_waitcnt lgkmcnt(0)
	s_nop 0
	v_mfma_f32_16x16x32_bf16 v[60:63], v[144:147], v[182:185], v[60:63]
	v_mfma_f32_16x16x32_bf16 v[56:59], v[158:161], v[182:185], v[56:59]
	v_mfma_f32_16x16x32_bf16 v[44:47], v[144:147], v[190:193], v[44:47]
	v_mfma_f32_16x16x32_bf16 v[40:43], v[158:161], v[190:193], v[40:43]
	v_mfma_f32_16x16x32_bf16 v[28:31], v[144:147], v[198:201], v[28:31]
	v_mfma_f32_16x16x32_bf16 v[24:27], v[158:161], v[198:201], v[24:27]
	v_mfma_f32_16x16x32_bf16 v[12:15], v[144:147], v[208:211], v[12:15]
	v_mfma_f32_16x16x32_bf16 v[8:11], v[158:161], v[208:211], v[8:11]
	v_mfma_f32_16x16x32_bf16 v[60:63], v[154:157], v[186:189], v[60:63]
	v_mfma_f32_16x16x32_bf16 v[56:59], v[162:165], v[186:189], v[56:59]
	v_mfma_f32_16x16x32_bf16 v[44:47], v[154:157], v[194:197], v[44:47]
	v_mfma_f32_16x16x32_bf16 v[40:43], v[162:165], v[194:197], v[40:43]
	v_mfma_f32_16x16x32_bf16 v[28:31], v[154:157], v[202:205], v[28:31]
	v_mfma_f32_16x16x32_bf16 v[24:27], v[162:165], v[202:205], v[24:27]
	v_mfma_f32_16x16x32_bf16 v[12:15], v[154:157], v[212:215], v[12:15]
	v_mfma_f32_16x16x32_bf16 v[8:11], v[162:165], v[212:215], v[8:11]
	v_mfma_f32_16x16x32_bf16 v[52:55], v[166:169], v[182:185], v[52:55]
	v_mfma_f32_16x16x32_bf16 v[48:51], v[174:177], v[182:185], v[48:51]
	v_mfma_f32_16x16x32_bf16 v[36:39], v[166:169], v[190:193], v[36:39]
	v_mfma_f32_16x16x32_bf16 v[32:35], v[174:177], v[190:193], v[32:35]
	v_mfma_f32_16x16x32_bf16 v[20:23], v[166:169], v[198:201], v[20:23]
	v_mfma_f32_16x16x32_bf16 v[16:19], v[174:177], v[198:201], v[16:19]
	v_mfma_f32_16x16x32_bf16 v[4:7], v[166:169], v[208:211], v[4:7]
	v_mfma_f32_16x16x32_bf16 v[0:3], v[174:177], v[208:211], v[0:3]
	v_mfma_f32_16x16x32_bf16 v[52:55], v[170:173], v[186:189], v[52:55]
	v_mfma_f32_16x16x32_bf16 v[48:51], v[178:181], v[186:189], v[48:51]
	v_mfma_f32_16x16x32_bf16 v[36:39], v[170:173], v[194:197], v[36:39]
	v_mfma_f32_16x16x32_bf16 v[32:35], v[178:181], v[194:197], v[32:35]
	v_mfma_f32_16x16x32_bf16 v[20:23], v[170:173], v[202:205], v[20:23]
	v_mfma_f32_16x16x32_bf16 v[16:19], v[178:181], v[202:205], v[16:19]
	v_mfma_f32_16x16x32_bf16 v[4:7], v[170:173], v[212:215], v[4:7]
	v_mfma_f32_16x16x32_bf16 v[0:3], v[178:181], v[212:215], v[0:3]
	s_barrier
	s_add_i32 s51, 0, 0x18000
	s_add_i32 s52, 0, 0x1c000
	v_add_u32_e32 v162, s51, v149
	v_add_u32_e32 v178, s52, v149
	ds_read_b128 v[144:147], v162
	ds_read_b128 v[154:157], v162 offset:1024
	ds_read_b128 v[158:161], v162 offset:2048
	ds_read_b128 v[162:165], v162 offset:3072
	ds_read_b128 v[166:169], v178
	ds_read_b128 v[170:173], v178 offset:1024
	ds_read_b128 v[174:177], v178 offset:2048
	ds_read_b128 v[178:181], v178 offset:3072
	s_add_u32 s28, s28, 0x20000
	s_addc_u32 s29, s29, 0
	s_mov_b32 m0, s38
	ds_read_b128 v[182:185], v153 offset:32768
	ds_read_b128 v[186:189], v153 offset:33792
	ds_read_b128 v[190:193], v153 offset:34816
	ds_read_b128 v[194:197], v153 offset:35840
	ds_read_b128 v[198:201], v153 offset:36864
	ds_read_b128 v[202:205], v153 offset:37888
	ds_read_b128 v[208:211], v153 offset:38912
	ds_read_b128 v[212:215], v153 offset:39936
	global_load_lds_dwordx4 v128, s[28:29]
	s_mov_b32 m0, s39
	s_nop 0
	global_load_lds_dwordx4 v132, s[28:29]
	s_waitcnt vmcnt(8)
	s_waitcnt lgkmcnt(0)
	s_barrier
	s_waitcnt lgkmcnt(0)
	s_nop 0
	v_mfma_f32_16x16x32_bf16 v[124:127], v[144:147], v[182:185], v[124:127]
	v_mfma_f32_16x16x32_bf16 v[120:123], v[158:161], v[182:185], v[120:123]
	v_mfma_f32_16x16x32_bf16 v[108:111], v[144:147], v[190:193], v[108:111]
	v_mfma_f32_16x16x32_bf16 v[104:107], v[158:161], v[190:193], v[104:107]
	v_mfma_f32_16x16x32_bf16 v[92:95], v[144:147], v[198:201], v[92:95]
	v_mfma_f32_16x16x32_bf16 v[88:91], v[158:161], v[198:201], v[88:91]
	v_mfma_f32_16x16x32_bf16 v[76:79], v[144:147], v[208:211], v[76:79]
	v_mfma_f32_16x16x32_bf16 v[72:75], v[158:161], v[208:211], v[72:75]
	v_mfma_f32_16x16x32_bf16 v[124:127], v[154:157], v[186:189], v[124:127]
	v_mfma_f32_16x16x32_bf16 v[120:123], v[162:165], v[186:189], v[120:123]
	v_mfma_f32_16x16x32_bf16 v[108:111], v[154:157], v[194:197], v[108:111]
	v_mfma_f32_16x16x32_bf16 v[104:107], v[162:165], v[194:197], v[104:107]
	v_mfma_f32_16x16x32_bf16 v[92:95], v[154:157], v[202:205], v[92:95]
	v_mfma_f32_16x16x32_bf16 v[88:91], v[162:165], v[202:205], v[88:91]
	v_mfma_f32_16x16x32_bf16 v[76:79], v[154:157], v[212:215], v[76:79]
	v_mfma_f32_16x16x32_bf16 v[72:75], v[162:165], v[212:215], v[72:75]
	v_mfma_f32_16x16x32_bf16 v[116:119], v[166:169], v[182:185], v[116:119]
	v_mfma_f32_16x16x32_bf16 v[112:115], v[174:177], v[182:185], v[112:115]
	v_mfma_f32_16x16x32_bf16 v[100:103], v[166:169], v[190:193], v[100:103]
	v_mfma_f32_16x16x32_bf16 v[96:99], v[174:177], v[190:193], v[96:99]
	v_mfma_f32_16x16x32_bf16 v[84:87], v[166:169], v[198:201], v[84:87]
	v_mfma_f32_16x16x32_bf16 v[80:83], v[174:177], v[198:201], v[80:83]
	v_mfma_f32_16x16x32_bf16 v[68:71], v[166:169], v[208:211], v[68:71]
	v_mfma_f32_16x16x32_bf16 v[64:67], v[174:177], v[208:211], v[64:67]
	v_mfma_f32_16x16x32_bf16 v[116:119], v[170:173], v[186:189], v[116:119]
	v_mfma_f32_16x16x32_bf16 v[112:115], v[178:181], v[186:189], v[112:115]
	v_mfma_f32_16x16x32_bf16 v[100:103], v[170:173], v[194:197], v[100:103]
	v_mfma_f32_16x16x32_bf16 v[96:99], v[178:181], v[194:197], v[96:99]
	v_mfma_f32_16x16x32_bf16 v[84:87], v[170:173], v[202:205], v[84:87]
	v_mfma_f32_16x16x32_bf16 v[80:83], v[178:181], v[202:205], v[80:83]
	v_mfma_f32_16x16x32_bf16 v[68:71], v[170:173], v[212:215], v[68:71]
	v_mfma_f32_16x16x32_bf16 v[64:67], v[178:181], v[212:215], v[64:67]
	s_barrier
	s_add_i32 s28, s51, s36
	s_mov_b32 m0, s28
	ds_read_b128 v[182:185], v153 offset:49152
	ds_read_b128 v[186:189], v153 offset:50176
	ds_read_b128 v[190:193], v153 offset:51200
	ds_read_b128 v[194:197], v153 offset:52224
	ds_read_b128 v[198:201], v153 offset:53248
	ds_read_b128 v[202:205], v153 offset:54272
	ds_read_b128 v[208:211], v153 offset:55296
	ds_read_b128 v[212:215], v153 offset:56320
	global_load_lds_dwordx4 v217, s[26:27]
	s_add_i32 m0, s28, 0x2000
	s_add_u32 s26, s26, 0x20080
	s_addc_u32 s27, s27, 0
	s_add_i32 s28, s52, s36
	global_load_lds_dwordx4 v219, s[98:99]
	s_mov_b32 m0, s28
	s_nop 0
	global_load_lds_dwordx4 v130, s[26:27]
	s_add_i32 m0, s28, 0x2000
	s_nop 0
	global_load_lds_dwordx4 v134, s[26:27]
	s_mov_b32 m0, s41
	s_nop 0
	global_load_lds_dwordx4 v216, s[100:101]
	s_mov_b32 m0, s42
	s_nop 0
	global_load_lds_dwordx4 v218, s[100:101]
	s_waitcnt vmcnt(8)
	s_waitcnt lgkmcnt(0)
	s_barrier
	s_waitcnt lgkmcnt(0)
	v_mfma_f32_16x16x32_bf16 v[60:63], v[144:147], v[182:185], v[60:63]
	v_mfma_f32_16x16x32_bf16 v[56:59], v[158:161], v[182:185], v[56:59]
	v_mfma_f32_16x16x32_bf16 v[44:47], v[144:147], v[190:193], v[44:47]
	v_mfma_f32_16x16x32_bf16 v[40:43], v[158:161], v[190:193], v[40:43]
	v_mfma_f32_16x16x32_bf16 v[28:31], v[144:147], v[198:201], v[28:31]
	v_mfma_f32_16x16x32_bf16 v[24:27], v[158:161], v[198:201], v[24:27]
	v_mfma_f32_16x16x32_bf16 v[12:15], v[144:147], v[208:211], v[12:15]
	v_mfma_f32_16x16x32_bf16 v[8:11], v[158:161], v[208:211], v[8:11]
	v_mfma_f32_16x16x32_bf16 v[60:63], v[154:157], v[186:189], v[60:63]
	v_mfma_f32_16x16x32_bf16 v[56:59], v[162:165], v[186:189], v[56:59]
	v_mfma_f32_16x16x32_bf16 v[44:47], v[154:157], v[194:197], v[44:47]
	v_mfma_f32_16x16x32_bf16 v[40:43], v[162:165], v[194:197], v[40:43]
	v_mfma_f32_16x16x32_bf16 v[28:31], v[154:157], v[202:205], v[28:31]
	v_mfma_f32_16x16x32_bf16 v[24:27], v[162:165], v[202:205], v[24:27]
	v_mfma_f32_16x16x32_bf16 v[12:15], v[154:157], v[212:215], v[12:15]
	v_mfma_f32_16x16x32_bf16 v[8:11], v[162:165], v[212:215], v[8:11]
	v_mfma_f32_16x16x32_bf16 v[52:55], v[166:169], v[182:185], v[52:55]
	v_mfma_f32_16x16x32_bf16 v[48:51], v[174:177], v[182:185], v[48:51]
	v_mfma_f32_16x16x32_bf16 v[36:39], v[166:169], v[190:193], v[36:39]
	v_mfma_f32_16x16x32_bf16 v[32:35], v[174:177], v[190:193], v[32:35]
	v_mfma_f32_16x16x32_bf16 v[20:23], v[166:169], v[198:201], v[20:23]
	v_mfma_f32_16x16x32_bf16 v[16:19], v[174:177], v[198:201], v[16:19]
	v_mfma_f32_16x16x32_bf16 v[4:7], v[166:169], v[208:211], v[4:7]
	v_mfma_f32_16x16x32_bf16 v[0:3], v[174:177], v[208:211], v[0:3]
	v_mfma_f32_16x16x32_bf16 v[52:55], v[170:173], v[186:189], v[52:55]
	v_mfma_f32_16x16x32_bf16 v[48:51], v[178:181], v[186:189], v[48:51]
	v_mfma_f32_16x16x32_bf16 v[36:39], v[170:173], v[194:197], v[36:39]
	v_mfma_f32_16x16x32_bf16 v[32:35], v[178:181], v[194:197], v[32:35]
	v_mfma_f32_16x16x32_bf16 v[20:23], v[170:173], v[202:205], v[20:23]
	v_mfma_f32_16x16x32_bf16 v[16:19], v[178:181], v[202:205], v[16:19]
	v_mfma_f32_16x16x32_bf16 v[4:7], v[170:173], v[212:215], v[4:7]
	v_mfma_f32_16x16x32_bf16 v[0:3], v[178:181], v[212:215], v[0:3]
	s_barrier
	s_add_i32 s50, s50, 2
	s_add_u32 s48, s48, 0x100
	s_addc_u32 s49, s49, 0
	s_add_u32 s24, s24, 0x100
	s_addc_u32 s25, s25, 0
	s_cmp_gt_u32 s50, 5
	s_cbranch_scc0 .LBB0_1193
	s_and_b64 vcc, exec, s[12:13]
	s_cbranch_vccz .LBB0_1196
	s_barrier

.LBB0_1272:
	ds_read_b128 v[140:143], v147
	ds_read_b128 v[150:153], v147 offset:1024
	ds_read_b128 v[154:157], v147 offset:2048
	ds_read_b128 v[158:161], v147 offset:3072
	ds_read_b128 v[162:165], v148
	ds_read_b128 v[166:169], v148 offset:1024
	ds_read_b128 v[170:173], v148 offset:2048
	ds_read_b128 v[174:177], v148 offset:3072
	s_add_u32 s30, s28, 0x100
	s_addc_u32 s31, s29, 0
	s_cmp_eq_u32 s58, 12
	s_cselect_b32 s37, s21, s31
	s_cselect_b32 s36, s27, s30
	s_cselect_b32 s35, s19, s57
	s_cselect_b32 s34, s55, s56
	s_add_i32 m0, s44, 0xc000
	ds_read_b128 v[178:181], v149
	ds_read_b128 v[182:185], v149 offset:1024
	ds_read_b128 v[186:189], v149 offset:2048
	ds_read_b128 v[190:193], v149 offset:3072
	ds_read_b128 v[194:197], v149 offset:4096
	ds_read_b128 v[198:201], v149 offset:5120
	ds_read_b128 v[202:205], v149 offset:6144
	ds_read_b128 v[208:211], v149 offset:7168
	global_load_lds_dwordx4 v134, s[28:29]
	s_add_i32 m0, s44, 0xe000
	s_nop 0
	global_load_lds_dwordx4 v132, s[28:29]
	s_waitcnt vmcnt(8)
	s_waitcnt lgkmcnt(0)
	s_barrier
	s_waitcnt lgkmcnt(0)
	v_mfma_f32_16x16x32_bf16 v[124:127], v[140:143], v[178:181], v[124:127]
	v_mfma_f32_16x16x32_bf16 v[120:123], v[154:157], v[178:181], v[120:123]
	v_mfma_f32_16x16x32_bf16 v[108:111], v[140:143], v[186:189], v[108:111]
	v_mfma_f32_16x16x32_bf16 v[104:107], v[154:157], v[186:189], v[104:107]
	v_mfma_f32_16x16x32_bf16 v[92:95], v[140:143], v[194:197], v[92:95]
	v_mfma_f32_16x16x32_bf16 v[88:91], v[154:157], v[194:197], v[88:91]
	v_mfma_f32_16x16x32_bf16 v[76:79], v[140:143], v[202:205], v[76:79]
	v_mfma_f32_16x16x32_bf16 v[72:75], v[154:157], v[202:205], v[72:75]
	v_mfma_f32_16x16x32_bf16 v[124:127], v[150:153], v[182:185], v[124:127]
	v_mfma_f32_16x16x32_bf16 v[120:123], v[158:161], v[182:185], v[120:123]
	v_mfma_f32_16x16x32_bf16 v[108:111], v[150:153], v[190:193], v[108:111]
	v_mfma_f32_16x16x32_bf16 v[104:107], v[158:161], v[190:193], v[104:107]
	v_mfma_f32_16x16x32_bf16 v[92:95], v[150:153], v[198:201], v[92:95]
	v_mfma_f32_16x16x32_bf16 v[88:91], v[158:161], v[198:201], v[88:91]
	v_mfma_f32_16x16x32_bf16 v[76:79], v[150:153], v[208:211], v[76:79]
	v_mfma_f32_16x16x32_bf16 v[72:75], v[158:161], v[208:211], v[72:75]
	v_mfma_f32_16x16x32_bf16 v[116:119], v[162:165], v[178:181], v[116:119]
	v_mfma_f32_16x16x32_bf16 v[112:115], v[170:173], v[178:181], v[112:115]
	v_mfma_f32_16x16x32_bf16 v[100:103], v[162:165], v[186:189], v[100:103]
	v_mfma_f32_16x16x32_bf16 v[96:99], v[170:173], v[186:189], v[96:99]
	v_mfma_f32_16x16x32_bf16 v[84:87], v[162:165], v[194:197], v[84:87]
	v_mfma_f32_16x16x32_bf16 v[80:83], v[170:173], v[194:197], v[80:83]
	v_mfma_f32_16x16x32_bf16 v[68:71], v[162:165], v[202:205], v[68:71]
	v_mfma_f32_16x16x32_bf16 v[64:67], v[170:173], v[202:205], v[64:67]
	v_mfma_f32_16x16x32_bf16 v[116:119], v[166:169], v[182:185], v[116:119]
	v_mfma_f32_16x16x32_bf16 v[112:115], v[174:177], v[182:185], v[112:115]
	v_mfma_f32_16x16x32_bf16 v[100:103], v[166:169], v[190:193], v[100:103]
	v_mfma_f32_16x16x32_bf16 v[96:99], v[174:177], v[190:193], v[96:99]
	v_mfma_f32_16x16x32_bf16 v[84:87], v[166:169], v[198:201], v[84:87]
	v_mfma_f32_16x16x32_bf16 v[80:83], v[174:177], v[198:201], v[80:83]
	v_mfma_f32_16x16x32_bf16 v[68:71], v[166:169], v[208:211], v[68:71]
	v_mfma_f32_16x16x32_bf16 v[64:67], v[174:177], v[208:211], v[64:67]
	s_barrier
	s_add_i32 s28, s52, s43
	s_mov_b32 m0, s28
	ds_read_b128 v[178:181], v149 offset:16384
	ds_read_b128 v[182:185], v149 offset:17408
	ds_read_b128 v[186:189], v149 offset:18432
	ds_read_b128 v[190:193], v149 offset:19456
	ds_read_b128 v[194:197], v149 offset:20480
	ds_read_b128 v[198:201], v149 offset:21504
	ds_read_b128 v[202:205], v149 offset:22528
	ds_read_b128 v[208:211], v149 offset:23552
	global_load_lds_dwordx4 v128, s[34:35]
	s_add_i32 m0, s28, 0x2000
	s_add_u32 s28, s34, 0x40000
	s_mov_b64 s[98:99], s[34:35]
	s_addc_u32 s29, s35, 0
	s_add_i32 s59, s53, s43
	global_load_lds_dwordx4 v130, s[34:35]
	s_mov_b32 m0, s59
	s_nop 0
	global_load_lds_dwordx4 v128, s[28:29]
	s_add_i32 m0, s59, 0x2000
	s_nop 0
	global_load_lds_dwordx4 v130, s[28:29]
	s_mov_b32 m0, s44
	s_nop 0
	global_load_lds_dwordx4 v128, s[36:37]
	s_mov_b32 m0, s45
	s_nop 0
	global_load_lds_dwordx4 v130, s[36:37]
	s_waitcnt vmcnt(8)
	s_waitcnt lgkmcnt(0)
	s_barrier
	s_waitcnt lgkmcnt(0)
	s_nop 0
	v_mfma_f32_16x16x32_bf16 v[60:63], v[140:143], v[178:181], v[60:63]
	v_mfma_f32_16x16x32_bf16 v[56:59], v[154:157], v[178:181], v[56:59]
	v_mfma_f32_16x16x32_bf16 v[44:47], v[140:143], v[186:189], v[44:47]
	v_mfma_f32_16x16x32_bf16 v[40:43], v[154:157], v[186:189], v[40:43]
	v_mfma_f32_16x16x32_bf16 v[28:31], v[140:143], v[194:197], v[28:31]
	v_mfma_f32_16x16x32_bf16 v[24:27], v[154:157], v[194:197], v[24:27]
	v_mfma_f32_16x16x32_bf16 v[12:15], v[140:143], v[202:205], v[12:15]
	v_mfma_f32_16x16x32_bf16 v[8:11], v[154:157], v[202:205], v[8:11]
	v_mfma_f32_16x16x32_bf16 v[60:63], v[150:153], v[182:185], v[60:63]
	v_mfma_f32_16x16x32_bf16 v[56:59], v[158:161], v[182:185], v[56:59]
	v_mfma_f32_16x16x32_bf16 v[44:47], v[150:153], v[190:193], v[44:47]
	v_mfma_f32_16x16x32_bf16 v[40:43], v[158:161], v[190:193], v[40:43]
	v_mfma_f32_16x16x32_bf16 v[28:31], v[150:153], v[198:201], v[28:31]
	v_mfma_f32_16x16x32_bf16 v[24:27], v[158:161], v[198:201], v[24:27]
	v_mfma_f32_16x16x32_bf16 v[12:15], v[150:153], v[208:211], v[12:15]
	v_mfma_f32_16x16x32_bf16 v[8:11], v[158:161], v[208:211], v[8:11]
	v_mfma_f32_16x16x32_bf16 v[52:55], v[162:165], v[178:181], v[52:55]
	v_mfma_f32_16x16x32_bf16 v[48:51], v[170:173], v[178:181], v[48:51]
	v_mfma_f32_16x16x32_bf16 v[36:39], v[162:165], v[186:189], v[36:39]
	v_mfma_f32_16x16x32_bf16 v[32:35], v[170:173], v[186:189], v[32:35]
	v_mfma_f32_16x16x32_bf16 v[20:23], v[162:165], v[194:197], v[20:23]
	v_mfma_f32_16x16x32_bf16 v[16:19], v[170:173], v[194:197], v[16:19]
	v_mfma_f32_16x16x32_bf16 v[4:7], v[162:165], v[202:205], v[4:7]
	v_mfma_f32_16x16x32_bf16 v[0:3], v[170:173], v[202:205], v[0:3]
	v_mfma_f32_16x16x32_bf16 v[52:55], v[166:169], v[182:185], v[52:55]
	v_mfma_f32_16x16x32_bf16 v[48:51], v[174:177], v[182:185], v[48:51]
	v_mfma_f32_16x16x32_bf16 v[36:39], v[166:169], v[190:193], v[36:39]
	v_mfma_f32_16x16x32_bf16 v[32:35], v[174:177], v[190:193], v[32:35]
	v_mfma_f32_16x16x32_bf16 v[20:23], v[166:169], v[198:201], v[20:23]
	v_mfma_f32_16x16x32_bf16 v[16:19], v[174:177], v[198:201], v[16:19]
	v_mfma_f32_16x16x32_bf16 v[4:7], v[166:169], v[208:211], v[4:7]
	v_mfma_f32_16x16x32_bf16 v[0:3], v[174:177], v[208:211], v[0:3]
	s_barrier
	s_add_i32 s59, 0, 0x18000
	s_add_i32 s60, 0, 0x1c000
	v_add_u32_e32 v158, s59, v145
	v_add_u32_e32 v174, s60, v145
	ds_read_b128 v[140:143], v158
	ds_read_b128 v[150:153], v158 offset:1024
	ds_read_b128 v[154:157], v158 offset:2048
	ds_read_b128 v[158:161], v158 offset:3072
	ds_read_b128 v[162:165], v174
	ds_read_b128 v[166:169], v174 offset:1024
	ds_read_b128 v[170:173], v174 offset:2048
	ds_read_b128 v[174:177], v174 offset:3072
	s_add_u32 s28, s36, 0x40000
	s_addc_u32 s29, s37, 0
	s_mov_b32 m0, s46
	ds_read_b128 v[178:181], v149 offset:32768
	ds_read_b128 v[182:185], v149 offset:33792
	ds_read_b128 v[186:189], v149 offset:34816
	ds_read_b128 v[190:193], v149 offset:35840
	ds_read_b128 v[194:197], v149 offset:36864
	ds_read_b128 v[198:201], v149 offset:37888
	ds_read_b128 v[202:205], v149 offset:38912
	ds_read_b128 v[208:211], v149 offset:39936
	global_load_lds_dwordx4 v128, s[28:29]
	s_mov_b32 m0, s47
	s_nop 0
	global_load_lds_dwordx4 v130, s[28:29]
	s_waitcnt vmcnt(8)
	s_waitcnt lgkmcnt(0)
	s_barrier
	s_waitcnt lgkmcnt(0)
	s_nop 0
	v_mfma_f32_16x16x32_bf16 v[124:127], v[140:143], v[178:181], v[124:127]
	v_mfma_f32_16x16x32_bf16 v[120:123], v[154:157], v[178:181], v[120:123]
	v_mfma_f32_16x16x32_bf16 v[108:111], v[140:143], v[186:189], v[108:111]
	v_mfma_f32_16x16x32_bf16 v[104:107], v[154:157], v[186:189], v[104:107]
	v_mfma_f32_16x16x32_bf16 v[92:95], v[140:143], v[194:197], v[92:95]
	v_mfma_f32_16x16x32_bf16 v[88:91], v[154:157], v[194:197], v[88:91]
	v_mfma_f32_16x16x32_bf16 v[76:79], v[140:143], v[202:205], v[76:79]
	v_mfma_f32_16x16x32_bf16 v[72:75], v[154:157], v[202:205], v[72:75]
	v_mfma_f32_16x16x32_bf16 v[124:127], v[150:153], v[182:185], v[124:127]
	v_mfma_f32_16x16x32_bf16 v[120:123], v[158:161], v[182:185], v[120:123]
	v_mfma_f32_16x16x32_bf16 v[108:111], v[150:153], v[190:193], v[108:111]
	v_mfma_f32_16x16x32_bf16 v[104:107], v[158:161], v[190:193], v[104:107]
	v_mfma_f32_16x16x32_bf16 v[92:95], v[150:153], v[198:201], v[92:95]
	v_mfma_f32_16x16x32_bf16 v[88:91], v[158:161], v[198:201], v[88:91]
	v_mfma_f32_16x16x32_bf16 v[76:79], v[150:153], v[208:211], v[76:79]
	v_mfma_f32_16x16x32_bf16 v[72:75], v[158:161], v[208:211], v[72:75]
	v_mfma_f32_16x16x32_bf16 v[116:119], v[162:165], v[178:181], v[116:119]
	v_mfma_f32_16x16x32_bf16 v[112:115], v[170:173], v[178:181], v[112:115]
	v_mfma_f32_16x16x32_bf16 v[100:103], v[162:165], v[186:189], v[100:103]
	v_mfma_f32_16x16x32_bf16 v[96:99], v[170:173], v[186:189], v[96:99]
	v_mfma_f32_16x16x32_bf16 v[84:87], v[162:165], v[194:197], v[84:87]
	v_mfma_f32_16x16x32_bf16 v[80:83], v[170:173], v[194:197], v[80:83]
	v_mfma_f32_16x16x32_bf16 v[68:71], v[162:165], v[202:205], v[68:71]
	v_mfma_f32_16x16x32_bf16 v[64:67], v[170:173], v[202:205], v[64:67]
	v_mfma_f32_16x16x32_bf16 v[116:119], v[166:169], v[182:185], v[116:119]
	v_mfma_f32_16x16x32_bf16 v[112:115], v[174:177], v[182:185], v[112:115]
	v_mfma_f32_16x16x32_bf16 v[100:103], v[166:169], v[190:193], v[100:103]
	v_mfma_f32_16x16x32_bf16 v[96:99], v[174:177], v[190:193], v[96:99]
	v_mfma_f32_16x16x32_bf16 v[84:87], v[166:169], v[198:201], v[84:87]
	v_mfma_f32_16x16x32_bf16 v[80:83], v[174:177], v[198:201], v[80:83]
	v_mfma_f32_16x16x32_bf16 v[68:71], v[166:169], v[208:211], v[68:71]
	v_mfma_f32_16x16x32_bf16 v[64:67], v[174:177], v[208:211], v[64:67]
	s_barrier
	s_add_i32 s28, s59, s43
	s_mov_b32 m0, s28
	ds_read_b128 v[178:181], v149 offset:49152
	ds_read_b128 v[182:185], v149 offset:50176
	ds_read_b128 v[186:189], v149 offset:51200
	ds_read_b128 v[190:193], v149 offset:52224
	ds_read_b128 v[194:197], v149 offset:53248
	ds_read_b128 v[198:201], v149 offset:54272
	ds_read_b128 v[202:205], v149 offset:55296
	ds_read_b128 v[208:211], v149 offset:56320
	global_load_lds_dwordx4 v212, s[34:35]
	s_add_i32 m0, s28, 0x2000
	s_add_u32 s28, s34, 0x40080
	s_addc_u32 s29, s35, 0
	s_add_i32 s34, s60, s43
	global_load_lds_dwordx4 v213, s[98:99]
	s_mov_b32 m0, s34
	s_nop 0
	global_load_lds_dwordx4 v128, s[28:29]
	s_add_i32 m0, s34, 0x2000
	s_nop 0
	global_load_lds_dwordx4 v130, s[28:29]
	s_mov_b32 m0, s49
	s_nop 0
	global_load_lds_dwordx4 v212, s[36:37]
	s_mov_b32 m0, s50
	s_nop 0
	global_load_lds_dwordx4 v213, s[36:37]
	s_waitcnt vmcnt(8)
	s_waitcnt lgkmcnt(0)
	s_barrier
	s_waitcnt lgkmcnt(0)
	v_mfma_f32_16x16x32_bf16 v[60:63], v[140:143], v[178:181], v[60:63]
	v_mfma_f32_16x16x32_bf16 v[56:59], v[154:157], v[178:181], v[56:59]
	v_mfma_f32_16x16x32_bf16 v[44:47], v[140:143], v[186:189], v[44:47]
	v_mfma_f32_16x16x32_bf16 v[40:43], v[154:157], v[186:189], v[40:43]
	v_mfma_f32_16x16x32_bf16 v[28:31], v[140:143], v[194:197], v[28:31]
	v_mfma_f32_16x16x32_bf16 v[24:27], v[154:157], v[194:197], v[24:27]
	v_mfma_f32_16x16x32_bf16 v[12:15], v[140:143], v[202:205], v[12:15]
	v_mfma_f32_16x16x32_bf16 v[8:11], v[154:157], v[202:205], v[8:11]
	v_mfma_f32_16x16x32_bf16 v[60:63], v[150:153], v[182:185], v[60:63]
	v_mfma_f32_16x16x32_bf16 v[56:59], v[158:161], v[182:185], v[56:59]
	v_mfma_f32_16x16x32_bf16 v[44:47], v[150:153], v[190:193], v[44:47]
	v_mfma_f32_16x16x32_bf16 v[40:43], v[158:161], v[190:193], v[40:43]
	v_mfma_f32_16x16x32_bf16 v[28:31], v[150:153], v[198:201], v[28:31]
	v_mfma_f32_16x16x32_bf16 v[24:27], v[158:161], v[198:201], v[24:27]
	v_mfma_f32_16x16x32_bf16 v[12:15], v[150:153], v[208:211], v[12:15]
	v_mfma_f32_16x16x32_bf16 v[8:11], v[158:161], v[208:211], v[8:11]
	v_mfma_f32_16x16x32_bf16 v[52:55], v[162:165], v[178:181], v[52:55]
	v_mfma_f32_16x16x32_bf16 v[48:51], v[170:173], v[178:181], v[48:51]
	v_mfma_f32_16x16x32_bf16 v[36:39], v[162:165], v[186:189], v[36:39]
	v_mfma_f32_16x16x32_bf16 v[32:35], v[170:173], v[186:189], v[32:35]
	v_mfma_f32_16x16x32_bf16 v[20:23], v[162:165], v[194:197], v[20:23]
	v_mfma_f32_16x16x32_bf16 v[16:19], v[170:173], v[194:197], v[16:19]
	v_mfma_f32_16x16x32_bf16 v[4:7], v[162:165], v[202:205], v[4:7]
	v_mfma_f32_16x16x32_bf16 v[0:3], v[170:173], v[202:205], v[0:3]
	v_mfma_f32_16x16x32_bf16 v[52:55], v[166:169], v[182:185], v[52:55]
	v_mfma_f32_16x16x32_bf16 v[48:51], v[174:177], v[182:185], v[48:51]
	v_mfma_f32_16x16x32_bf16 v[36:39], v[166:169], v[190:193], v[36:39]
	v_mfma_f32_16x16x32_bf16 v[32:35], v[174:177], v[190:193], v[32:35]
	v_mfma_f32_16x16x32_bf16 v[20:23], v[166:169], v[198:201], v[20:23]
	v_mfma_f32_16x16x32_bf16 v[16:19], v[174:177], v[198:201], v[16:19]
	v_mfma_f32_16x16x32_bf16 v[4:7], v[166:169], v[208:211], v[4:7]
	v_mfma_f32_16x16x32_bf16 v[0:3], v[174:177], v[208:211], v[0:3]
	s_barrier
	s_add_i32 s58, s58, 2
	s_add_u32 s56, s56, 0x100
	s_addc_u32 s57, s57, 0
	s_cmp_gt_u32 s58, 13
	s_mov_b64 s[28:29], s[30:31]
	s_cbranch_scc0 .LBB0_1272
	s_and_b64 vcc, exec, s[16:17]
	s_cbranch_vccz .LBB0_1275
	s_barrier

.LBB0_1365:
	ds_read_b128 v[144:147], v151
	ds_read_b128 v[156:159], v151 offset:1024
	ds_read_b128 v[160:163], v151 offset:2048
	ds_read_b128 v[164:167], v151 offset:3072
	ds_read_b128 v[168:171], v152
	ds_read_b128 v[172:175], v152 offset:1024
	ds_read_b128 v[176:179], v152 offset:2048
	ds_read_b128 v[180:183], v152 offset:3072
	s_add_u32 s26, s24, 0xfffc0080
	s_addc_u32 s27, s25, -1
	s_cmp_eq_u32 s53, 12
	s_cselect_b32 s29, s19, s27
	s_cselect_b32 s28, s49, s26
	s_cselect_b32 s27, s17, s52
	s_cselect_b32 s26, s50, s51
	s_add_i32 m0, s39, 0xc000
	ds_read_b128 v[184:187], v153
	ds_read_b128 v[188:191], v153 offset:1024
	ds_read_b128 v[192:195], v153 offset:2048
	ds_read_b128 v[196:199], v153 offset:3072
	ds_read_b128 v[200:203], v153 offset:4096
	ds_read_b128 v[208:211], v153 offset:5120
	ds_read_b128 v[212:215], v153 offset:6144
	ds_read_b128 v[216:219], v153 offset:7168
	global_load_lds_dwordx4 v138, s[24:25]
	s_add_i32 m0, s39, 0xe000
	s_nop 0
	global_load_lds_dwordx4 v136, s[24:25]
	s_waitcnt vmcnt(8)
	s_waitcnt lgkmcnt(0)
	s_barrier
	s_waitcnt lgkmcnt(0)
	v_mfma_f32_16x16x32_bf16 v[124:127], v[144:147], v[184:187], v[124:127]
	v_mfma_f32_16x16x32_bf16 v[120:123], v[160:163], v[184:187], v[120:123]
	v_mfma_f32_16x16x32_bf16 v[108:111], v[144:147], v[192:195], v[108:111]
	v_mfma_f32_16x16x32_bf16 v[104:107], v[160:163], v[192:195], v[104:107]
	v_mfma_f32_16x16x32_bf16 v[92:95], v[144:147], v[200:203], v[92:95]
	v_mfma_f32_16x16x32_bf16 v[88:91], v[160:163], v[200:203], v[88:91]
	v_mfma_f32_16x16x32_bf16 v[76:79], v[144:147], v[212:215], v[76:79]
	v_mfma_f32_16x16x32_bf16 v[72:75], v[160:163], v[212:215], v[72:75]
	v_mfma_f32_16x16x32_bf16 v[124:127], v[156:159], v[188:191], v[124:127]
	v_mfma_f32_16x16x32_bf16 v[120:123], v[164:167], v[188:191], v[120:123]
	v_mfma_f32_16x16x32_bf16 v[108:111], v[156:159], v[196:199], v[108:111]
	v_mfma_f32_16x16x32_bf16 v[104:107], v[164:167], v[196:199], v[104:107]
	v_mfma_f32_16x16x32_bf16 v[92:95], v[156:159], v[208:211], v[92:95]
	v_mfma_f32_16x16x32_bf16 v[88:91], v[164:167], v[208:211], v[88:91]
	v_mfma_f32_16x16x32_bf16 v[76:79], v[156:159], v[216:219], v[76:79]
	v_mfma_f32_16x16x32_bf16 v[72:75], v[164:167], v[216:219], v[72:75]
	v_mfma_f32_16x16x32_bf16 v[116:119], v[168:171], v[184:187], v[116:119]
	v_mfma_f32_16x16x32_bf16 v[112:115], v[176:179], v[184:187], v[112:115]
	v_mfma_f32_16x16x32_bf16 v[100:103], v[168:171], v[192:195], v[100:103]
	v_mfma_f32_16x16x32_bf16 v[96:99], v[176:179], v[192:195], v[96:99]
	v_mfma_f32_16x16x32_bf16 v[84:87], v[168:171], v[200:203], v[84:87]
	v_mfma_f32_16x16x32_bf16 v[80:83], v[176:179], v[200:203], v[80:83]
	v_mfma_f32_16x16x32_bf16 v[68:71], v[168:171], v[212:215], v[68:71]
	v_mfma_f32_16x16x32_bf16 v[64:67], v[176:179], v[212:215], v[64:67]
	v_mfma_f32_16x16x32_bf16 v[116:119], v[172:175], v[188:191], v[116:119]
	v_mfma_f32_16x16x32_bf16 v[112:115], v[180:183], v[188:191], v[112:115]
	v_mfma_f32_16x16x32_bf16 v[100:103], v[172:175], v[196:199], v[100:103]
	v_mfma_f32_16x16x32_bf16 v[96:99], v[180:183], v[196:199], v[96:99]
	v_mfma_f32_16x16x32_bf16 v[84:87], v[172:175], v[208:211], v[84:87]
	v_mfma_f32_16x16x32_bf16 v[80:83], v[180:183], v[208:211], v[80:83]
	v_mfma_f32_16x16x32_bf16 v[68:71], v[172:175], v[216:219], v[68:71]
	v_mfma_f32_16x16x32_bf16 v[64:67], v[180:183], v[216:219], v[64:67]
	s_barrier
	s_add_i32 s54, s46, s38
	s_mov_b32 m0, s54
	ds_read_b128 v[184:187], v153 offset:16384
	ds_read_b128 v[188:191], v153 offset:17408
	ds_read_b128 v[192:195], v153 offset:18432
	ds_read_b128 v[196:199], v153 offset:19456
	ds_read_b128 v[200:203], v153 offset:20480
	ds_read_b128 v[208:211], v153 offset:21504
	ds_read_b128 v[212:215], v153 offset:22528
	ds_read_b128 v[216:219], v153 offset:23552
	global_load_lds_dwordx4 v130, s[26:27]
	s_add_i32 m0, s54, 0x2000
	s_add_u32 s54, s26, 0x40000
	s_mov_b64 s[98:99], s[26:27]
	s_addc_u32 s55, s27, 0
	s_add_i32 s56, s47, s38
	global_load_lds_dwordx4 v134, s[26:27]
	s_mov_b32 m0, s56
	s_mov_b64 s[100:101], s[28:29]
	global_load_lds_dwordx4 v130, s[54:55]
	s_add_i32 m0, s56, 0x2000
	s_nop 0
	global_load_lds_dwordx4 v134, s[54:55]
	s_mov_b32 m0, s39
	s_nop 0
	global_load_lds_dwordx4 v128, s[28:29]
	s_mov_b32 m0, s40
	s_nop 0
	global_load_lds_dwordx4 v132, s[28:29]
	s_waitcnt vmcnt(8)
	s_waitcnt lgkmcnt(0)
	s_barrier
	s_waitcnt lgkmcnt(0)
	s_nop 0
	v_mfma_f32_16x16x32_bf16 v[60:63], v[144:147], v[184:187], v[60:63]
	v_mfma_f32_16x16x32_bf16 v[56:59], v[160:163], v[184:187], v[56:59]
	v_mfma_f32_16x16x32_bf16 v[44:47], v[144:147], v[192:195], v[44:47]
	v_mfma_f32_16x16x32_bf16 v[40:43], v[160:163], v[192:195], v[40:43]
	v_mfma_f32_16x16x32_bf16 v[28:31], v[144:147], v[200:203], v[28:31]
	v_mfma_f32_16x16x32_bf16 v[24:27], v[160:163], v[200:203], v[24:27]
	v_mfma_f32_16x16x32_bf16 v[12:15], v[144:147], v[212:215], v[12:15]
	v_mfma_f32_16x16x32_bf16 v[8:11], v[160:163], v[212:215], v[8:11]
	v_mfma_f32_16x16x32_bf16 v[60:63], v[156:159], v[188:191], v[60:63]
	v_mfma_f32_16x16x32_bf16 v[56:59], v[164:167], v[188:191], v[56:59]
	v_mfma_f32_16x16x32_bf16 v[44:47], v[156:159], v[196:199], v[44:47]
	v_mfma_f32_16x16x32_bf16 v[40:43], v[164:167], v[196:199], v[40:43]
	v_mfma_f32_16x16x32_bf16 v[28:31], v[156:159], v[208:211], v[28:31]
	v_mfma_f32_16x16x32_bf16 v[24:27], v[164:167], v[208:211], v[24:27]
	v_mfma_f32_16x16x32_bf16 v[12:15], v[156:159], v[216:219], v[12:15]
	v_mfma_f32_16x16x32_bf16 v[8:11], v[164:167], v[216:219], v[8:11]
	v_mfma_f32_16x16x32_bf16 v[52:55], v[168:171], v[184:187], v[52:55]
	v_mfma_f32_16x16x32_bf16 v[48:51], v[176:179], v[184:187], v[48:51]
	v_mfma_f32_16x16x32_bf16 v[36:39], v[168:171], v[192:195], v[36:39]
	v_mfma_f32_16x16x32_bf16 v[32:35], v[176:179], v[192:195], v[32:35]
	v_mfma_f32_16x16x32_bf16 v[20:23], v[168:171], v[200:203], v[20:23]
	v_mfma_f32_16x16x32_bf16 v[16:19], v[176:179], v[200:203], v[16:19]
	v_mfma_f32_16x16x32_bf16 v[4:7], v[168:171], v[212:215], v[4:7]
	v_mfma_f32_16x16x32_bf16 v[0:3], v[176:179], v[212:215], v[0:3]
	v_mfma_f32_16x16x32_bf16 v[52:55], v[172:175], v[188:191], v[52:55]
	v_mfma_f32_16x16x32_bf16 v[48:51], v[180:183], v[188:191], v[48:51]
	v_mfma_f32_16x16x32_bf16 v[36:39], v[172:175], v[196:199], v[36:39]
	v_mfma_f32_16x16x32_bf16 v[32:35], v[180:183], v[196:199], v[32:35]
	v_mfma_f32_16x16x32_bf16 v[20:23], v[172:175], v[208:211], v[20:23]
	v_mfma_f32_16x16x32_bf16 v[16:19], v[180:183], v[208:211], v[16:19]
	v_mfma_f32_16x16x32_bf16 v[4:7], v[172:175], v[216:219], v[4:7]
	v_mfma_f32_16x16x32_bf16 v[0:3], v[180:183], v[216:219], v[0:3]
	s_barrier
	s_add_i32 s54, 0, 0x18000
	v_add_u32_e32 v155, s54, v149
	s_add_i32 s55, 0, 0x1c000
	ds_read_b128 v[144:147], v155
	ds_read_b128 v[156:159], v155 offset:1024
	ds_read_b128 v[160:163], v155 offset:2048
	ds_read_b128 v[164:167], v155 offset:3072
	v_add_u32_e32 v155, s55, v149
	ds_read_b128 v[168:171], v155
	ds_read_b128 v[172:175], v155 offset:1024
	ds_read_b128 v[176:179], v155 offset:2048
	ds_read_b128 v[180:183], v155 offset:3072
	s_add_u32 s28, s28, 0x40000
	s_addc_u32 s29, s29, 0
	s_mov_b32 m0, s41
	ds_read_b128 v[184:187], v153 offset:32768
	ds_read_b128 v[188:191], v153 offset:33792
	ds_read_b128 v[192:195], v153 offset:34816
	ds_read_b128 v[196:199], v153 offset:35840
	ds_read_b128 v[200:203], v153 offset:36864
	ds_read_b128 v[208:211], v153 offset:37888
	ds_read_b128 v[212:215], v153 offset:38912
	ds_read_b128 v[216:219], v153 offset:39936
	global_load_lds_dwordx4 v128, s[28:29]
	s_mov_b32 m0, s42
	s_nop 0
	global_load_lds_dwordx4 v132, s[28:29]
	s_waitcnt vmcnt(8)
	s_waitcnt lgkmcnt(0)
	s_barrier
	s_waitcnt lgkmcnt(0)
	s_nop 0
	v_mfma_f32_16x16x32_bf16 v[124:127], v[144:147], v[184:187], v[124:127]
	v_mfma_f32_16x16x32_bf16 v[120:123], v[160:163], v[184:187], v[120:123]
	v_mfma_f32_16x16x32_bf16 v[108:111], v[144:147], v[192:195], v[108:111]
	v_mfma_f32_16x16x32_bf16 v[104:107], v[160:163], v[192:195], v[104:107]
	v_mfma_f32_16x16x32_bf16 v[92:95], v[144:147], v[200:203], v[92:95]
	v_mfma_f32_16x16x32_bf16 v[88:91], v[160:163], v[200:203], v[88:91]
	v_mfma_f32_16x16x32_bf16 v[76:79], v[144:147], v[212:215], v[76:79]
	v_mfma_f32_16x16x32_bf16 v[72:75], v[160:163], v[212:215], v[72:75]
	v_mfma_f32_16x16x32_bf16 v[124:127], v[156:159], v[188:191], v[124:127]
	v_mfma_f32_16x16x32_bf16 v[120:123], v[164:167], v[188:191], v[120:123]
	v_mfma_f32_16x16x32_bf16 v[108:111], v[156:159], v[196:199], v[108:111]
	v_mfma_f32_16x16x32_bf16 v[104:107], v[164:167], v[196:199], v[104:107]
	v_mfma_f32_16x16x32_bf16 v[92:95], v[156:159], v[208:211], v[92:95]
	v_mfma_f32_16x16x32_bf16 v[88:91], v[164:167], v[208:211], v[88:91]
	v_mfma_f32_16x16x32_bf16 v[76:79], v[156:159], v[216:219], v[76:79]
	v_mfma_f32_16x16x32_bf16 v[72:75], v[164:167], v[216:219], v[72:75]
	v_mfma_f32_16x16x32_bf16 v[116:119], v[168:171], v[184:187], v[116:119]
	v_mfma_f32_16x16x32_bf16 v[112:115], v[176:179], v[184:187], v[112:115]
	v_mfma_f32_16x16x32_bf16 v[100:103], v[168:171], v[192:195], v[100:103]
	v_mfma_f32_16x16x32_bf16 v[96:99], v[176:179], v[192:195], v[96:99]
	v_mfma_f32_16x16x32_bf16 v[84:87], v[168:171], v[200:203], v[84:87]
	v_mfma_f32_16x16x32_bf16 v[80:83], v[176:179], v[200:203], v[80:83]
	v_mfma_f32_16x16x32_bf16 v[68:71], v[168:171], v[212:215], v[68:71]
	v_mfma_f32_16x16x32_bf16 v[64:67], v[176:179], v[212:215], v[64:67]
	v_mfma_f32_16x16x32_bf16 v[116:119], v[172:175], v[188:191], v[116:119]
	v_mfma_f32_16x16x32_bf16 v[112:115], v[180:183], v[188:191], v[112:115]
	v_mfma_f32_16x16x32_bf16 v[100:103], v[172:175], v[196:199], v[100:103]
	v_mfma_f32_16x16x32_bf16 v[96:99], v[180:183], v[196:199], v[96:99]
	v_mfma_f32_16x16x32_bf16 v[84:87], v[172:175], v[208:211], v[84:87]
	v_mfma_f32_16x16x32_bf16 v[80:83], v[180:183], v[208:211], v[80:83]
	v_mfma_f32_16x16x32_bf16 v[68:71], v[172:175], v[216:219], v[68:71]
	v_mfma_f32_16x16x32_bf16 v[64:67], v[180:183], v[216:219], v[64:67]
	s_barrier
	s_add_i32 s28, s54, s38
	s_mov_b32 m0, s28
	ds_read_b128 v[184:187], v153 offset:49152
	ds_read_b128 v[188:191], v153 offset:50176
	ds_read_b128 v[192:195], v153 offset:51200
	ds_read_b128 v[196:199], v153 offset:52224
	ds_read_b128 v[200:203], v153 offset:53248
	ds_read_b128 v[208:211], v153 offset:54272
	ds_read_b128 v[212:215], v153 offset:55296
	ds_read_b128 v[216:219], v153 offset:56320
	global_load_lds_dwordx4 v205, s[26:27]
	s_add_i32 m0, s28, 0x2000
	s_add_u32 s26, s26, 0x40080
	s_addc_u32 s27, s27, 0
	s_add_i32 s28, s55, s38
	global_load_lds_dwordx4 v221, s[98:99]
	s_mov_b32 m0, s28
	s_nop 0
	global_load_lds_dwordx4 v130, s[26:27]
	s_add_i32 m0, s28, 0x2000
	s_nop 0
	global_load_lds_dwordx4 v134, s[26:27]
	s_mov_b32 m0, s44
	s_nop 0
	global_load_lds_dwordx4 v204, s[100:101]
	s_mov_b32 m0, s45
	s_nop 0
	global_load_lds_dwordx4 v220, s[100:101]
	s_waitcnt vmcnt(8)
	s_waitcnt lgkmcnt(0)
	s_barrier
	s_waitcnt lgkmcnt(0)
	v_mfma_f32_16x16x32_bf16 v[60:63], v[144:147], v[184:187], v[60:63]
	v_mfma_f32_16x16x32_bf16 v[56:59], v[160:163], v[184:187], v[56:59]
	v_mfma_f32_16x16x32_bf16 v[44:47], v[144:147], v[192:195], v[44:47]
	v_mfma_f32_16x16x32_bf16 v[40:43], v[160:163], v[192:195], v[40:43]
	v_mfma_f32_16x16x32_bf16 v[28:31], v[144:147], v[200:203], v[28:31]
	v_mfma_f32_16x16x32_bf16 v[24:27], v[160:163], v[200:203], v[24:27]
	v_mfma_f32_16x16x32_bf16 v[12:15], v[144:147], v[212:215], v[12:15]
	v_mfma_f32_16x16x32_bf16 v[8:11], v[160:163], v[212:215], v[8:11]
	v_mfma_f32_16x16x32_bf16 v[60:63], v[156:159], v[188:191], v[60:63]
	v_mfma_f32_16x16x32_bf16 v[56:59], v[164:167], v[188:191], v[56:59]
	v_mfma_f32_16x16x32_bf16 v[44:47], v[156:159], v[196:199], v[44:47]
	v_mfma_f32_16x16x32_bf16 v[40:43], v[164:167], v[196:199], v[40:43]
	v_mfma_f32_16x16x32_bf16 v[28:31], v[156:159], v[208:211], v[28:31]
	v_mfma_f32_16x16x32_bf16 v[24:27], v[164:167], v[208:211], v[24:27]
	v_mfma_f32_16x16x32_bf16 v[12:15], v[156:159], v[216:219], v[12:15]
	v_mfma_f32_16x16x32_bf16 v[8:11], v[164:167], v[216:219], v[8:11]
	v_mfma_f32_16x16x32_bf16 v[52:55], v[168:171], v[184:187], v[52:55]
	v_mfma_f32_16x16x32_bf16 v[48:51], v[176:179], v[184:187], v[48:51]
	v_mfma_f32_16x16x32_bf16 v[36:39], v[168:171], v[192:195], v[36:39]
	v_mfma_f32_16x16x32_bf16 v[32:35], v[176:179], v[192:195], v[32:35]
	v_mfma_f32_16x16x32_bf16 v[20:23], v[168:171], v[200:203], v[20:23]
	v_mfma_f32_16x16x32_bf16 v[16:19], v[176:179], v[200:203], v[16:19]
	v_mfma_f32_16x16x32_bf16 v[4:7], v[168:171], v[212:215], v[4:7]
	v_mfma_f32_16x16x32_bf16 v[0:3], v[176:179], v[212:215], v[0:3]
	v_mfma_f32_16x16x32_bf16 v[52:55], v[172:175], v[188:191], v[52:55]
	v_mfma_f32_16x16x32_bf16 v[48:51], v[180:183], v[188:191], v[48:51]
	v_mfma_f32_16x16x32_bf16 v[36:39], v[172:175], v[196:199], v[36:39]
	v_mfma_f32_16x16x32_bf16 v[32:35], v[180:183], v[196:199], v[32:35]
	v_mfma_f32_16x16x32_bf16 v[20:23], v[172:175], v[208:211], v[20:23]
	v_mfma_f32_16x16x32_bf16 v[16:19], v[180:183], v[208:211], v[16:19]
	v_mfma_f32_16x16x32_bf16 v[4:7], v[172:175], v[216:219], v[4:7]
	v_mfma_f32_16x16x32_bf16 v[0:3], v[180:183], v[216:219], v[0:3]
	s_barrier
	s_add_i32 s53, s53, 2
	s_add_u32 s51, s51, 0x100
	s_addc_u32 s52, s52, 0
	s_add_u32 s24, s24, 0x100
	s_addc_u32 s25, s25, 0
	s_cmp_gt_u32 s53, 13
	s_cbranch_scc0 .LBB0_1365
	s_and_b64 vcc, exec, s[14:15]
	s_cbranch_vccz .LBB0_1368
	s_barrier

.LBB0_1483:
	ds_read_b128 v[0:3], v139
	ds_read_b128 v[4:7], v139 offset:1024
	ds_read_b128 v[8:11], v139 offset:2048
	ds_read_b128 v[12:15], v139 offset:3072
	ds_read_b128 v[16:19], v140
	ds_read_b128 v[20:23], v140 offset:1024
	ds_read_b128 v[24:27], v140 offset:2048
	ds_read_b128 v[28:31], v140 offset:3072
	s_ashr_i32 s29, s28, 31
	s_lshl_b64 s[30:31], s[28:29], 17
	s_add_u32 s30, s46, s30
	s_addc_u32 s31, s47, s31
	s_and_b64 s[34:35], s[4:5], exec
	s_cselect_b32 s45, s31, s39
	s_cselect_b32 s44, s30, s38
	s_ashr_i32 s27, s26, 31
	s_lshl_b64 s[34:35], s[26:27], 17
	s_add_u32 s34, s48, s34
	s_addc_u32 s35, s49, s35
	s_and_b64 s[42:43], s[4:5], exec
	s_cselect_b32 s43, s35, s41
	s_cselect_b32 s42, s34, s40
	s_add_u32 s64, s38, 0x10080
	s_addc_u32 s65, s39, 0
	s_add_i32 s67, s37, 0xc000
	v_lshl_add_u64 v[64:65], s[64:65], 0, v[128:129]
	s_mov_b32 m0, s67
	s_add_i32 s27, s37, 0xe000
	ds_read_b128 v[32:35], v141
	ds_read_b128 v[36:39], v141 offset:1024
	ds_read_b128 v[40:43], v141 offset:2048
	ds_read_b128 v[44:47], v141 offset:3072
	ds_read_b128 v[48:51], v141 offset:4096
	ds_read_b128 v[52:55], v141 offset:5120
	ds_read_b128 v[56:59], v141 offset:6144
	ds_read_b128 v[60:63], v141 offset:7168
	global_load_lds_dwordx4 v[64:65], off
	v_lshl_add_u64 v[64:65], s[64:65], 0, v[130:131]
	s_mov_b32 m0, s27
	s_nop 0
	global_load_lds_dwordx4 v[64:65], off
	s_waitcnt vmcnt(8)
	s_waitcnt lgkmcnt(0)
	s_barrier
	s_waitcnt lgkmcnt(0)
	v_mfma_f32_16x16x32_bf16 v[64:67], v[0:3], v[32:35], 0
	v_mfma_f32_16x16x32_bf16 v[68:71], v[8:11], v[32:35], 0
	v_mfma_f32_16x16x32_bf16 v[72:75], v[0:3], v[40:43], 0
	v_mfma_f32_16x16x32_bf16 v[76:79], v[8:11], v[40:43], 0
	v_mfma_f32_16x16x32_bf16 v[80:83], v[0:3], v[48:51], 0
	v_mfma_f32_16x16x32_bf16 v[84:87], v[8:11], v[48:51], 0
	v_mfma_f32_16x16x32_bf16 v[88:91], v[0:3], v[56:59], 0
	v_mfma_f32_16x16x32_bf16 v[92:95], v[8:11], v[56:59], 0
	v_mfma_f32_16x16x32_bf16 v[64:67], v[4:7], v[36:39], v[64:67]
	v_mfma_f32_16x16x32_bf16 v[68:71], v[12:15], v[36:39], v[68:71]
	v_mfma_f32_16x16x32_bf16 v[72:75], v[4:7], v[44:47], v[72:75]
	v_mfma_f32_16x16x32_bf16 v[76:79], v[12:15], v[44:47], v[76:79]
	v_mfma_f32_16x16x32_bf16 v[80:83], v[4:7], v[52:55], v[80:83]
	v_mfma_f32_16x16x32_bf16 v[84:87], v[12:15], v[52:55], v[84:87]
	v_mfma_f32_16x16x32_bf16 v[88:91], v[4:7], v[60:63], v[88:91]
	v_mfma_f32_16x16x32_bf16 v[92:95], v[12:15], v[60:63], v[92:95]
	v_mfma_f32_16x16x32_bf16 v[96:99], v[16:19], v[32:35], 0
	v_mfma_f32_16x16x32_bf16 v[32:35], v[24:27], v[32:35], 0
	v_mfma_f32_16x16x32_bf16 v[96:99], v[20:23], v[36:39], v[96:99]
	v_mfma_f32_16x16x32_bf16 v[32:35], v[28:31], v[36:39], v[32:35]
	v_mfma_f32_16x16x32_bf16 v[36:39], v[16:19], v[40:43], 0
	v_mfma_f32_16x16x32_bf16 v[40:43], v[24:27], v[40:43], 0
	v_mfma_f32_16x16x32_bf16 v[36:39], v[20:23], v[44:47], v[36:39]
	v_mfma_f32_16x16x32_bf16 v[40:43], v[28:31], v[44:47], v[40:43]
	v_mfma_f32_16x16x32_bf16 v[44:47], v[16:19], v[48:51], 0
	v_mfma_f32_16x16x32_bf16 v[48:51], v[24:27], v[48:51], 0
	v_mfma_f32_16x16x32_bf16 v[44:47], v[20:23], v[52:55], v[44:47]
	v_mfma_f32_16x16x32_bf16 v[48:51], v[28:31], v[52:55], v[48:51]
	v_mfma_f32_16x16x32_bf16 v[52:55], v[16:19], v[56:59], 0
	v_mfma_f32_16x16x32_bf16 v[56:59], v[24:27], v[56:59], 0
	v_mfma_f32_16x16x32_bf16 v[52:55], v[20:23], v[60:63], v[52:55]
	v_mfma_f32_16x16x32_bf16 v[56:59], v[28:31], v[60:63], v[56:59]
	s_barrier
	s_add_i32 s65, s56, s50
	v_lshl_add_u64 v[208:209], s[40:41], 0, v[128:129]
	s_add_i32 s29, s65, 0x2000
	v_lshl_add_u64 v[142:143], v[208:209], 0, s[14:15]
	s_mov_b32 m0, s65
	v_lshl_add_u64 v[210:211], s[40:41], 0, v[130:131]
	s_add_u32 s68, s40, 0x10100
	ds_read_b128 v[60:63], v141 offset:16384
	ds_read_b128 v[100:103], v141 offset:17408
	ds_read_b128 v[104:107], v141 offset:18432
	ds_read_b128 v[108:111], v141 offset:19456
	ds_read_b128 v[112:115], v141 offset:20480
	ds_read_b128 v[116:119], v141 offset:21504
	ds_read_b128 v[120:123], v141 offset:22528
	ds_read_b128 v[124:127], v141 offset:23552
	global_load_lds_dwordx4 v[142:143], off
	v_lshl_add_u64 v[142:143], v[210:211], 0, s[14:15]
	s_mov_b32 m0, s29
	s_addc_u32 s69, s41, 0
	s_add_i32 s63, s57, s50
	global_load_lds_dwordx4 v[142:143], off
	v_lshl_add_u64 v[142:143], s[68:69], 0, v[128:129]
	s_mov_b32 m0, s63
	s_add_i32 s64, s63, 0x2000
	global_load_lds_dwordx4 v[142:143], off
	v_lshl_add_u64 v[142:143], s[68:69], 0, v[130:131]
	s_mov_b32 m0, s64
	v_lshl_add_u64 v[212:213], s[38:39], 0, v[128:129]
	global_load_lds_dwordx4 v[142:143], off
	v_lshl_add_u64 v[142:143], v[212:213], 0, s[14:15]
	s_mov_b32 m0, s37
	v_lshl_add_u64 v[214:215], s[38:39], 0, v[130:131]
	global_load_lds_dwordx4 v[142:143], off
	v_lshl_add_u64 v[142:143], v[214:215], 0, s[14:15]
	s_mov_b32 m0, s51
	s_nop 0
	global_load_lds_dwordx4 v[142:143], off
	s_waitcnt vmcnt(8)
	s_waitcnt lgkmcnt(0)
	s_barrier
	s_waitcnt lgkmcnt(0)
	s_nop 0
	v_mfma_f32_16x16x32_bf16 v[142:145], v[0:3], v[60:63], 0
	v_mfma_f32_16x16x32_bf16 v[150:153], v[0:3], v[104:107], 0
	v_mfma_f32_16x16x32_bf16 v[158:161], v[0:3], v[112:115], 0
	v_mfma_f32_16x16x32_bf16 v[0:3], v[0:3], v[120:123], 0
	v_mfma_f32_16x16x32_bf16 v[142:145], v[4:7], v[100:103], v[142:145]
	v_mfma_f32_16x16x32_bf16 v[150:153], v[4:7], v[108:111], v[150:153]
	v_mfma_f32_16x16x32_bf16 v[158:161], v[4:7], v[116:119], v[158:161]
	v_mfma_f32_16x16x32_bf16 v[0:3], v[4:7], v[124:127], v[0:3]
	v_mfma_f32_16x16x32_bf16 v[4:7], v[8:11], v[120:123], 0
	v_mfma_f32_16x16x32_bf16 v[146:149], v[8:11], v[60:63], 0
	v_mfma_f32_16x16x32_bf16 v[154:157], v[8:11], v[104:107], 0
	v_mfma_f32_16x16x32_bf16 v[162:165], v[8:11], v[112:115], 0
	v_mfma_f32_16x16x32_bf16 v[4:7], v[12:15], v[124:127], v[4:7]
	v_mfma_f32_16x16x32_bf16 v[146:149], v[12:15], v[100:103], v[146:149]
	v_mfma_f32_16x16x32_bf16 v[154:157], v[12:15], v[108:111], v[154:157]
	v_mfma_f32_16x16x32_bf16 v[162:165], v[12:15], v[116:119], v[162:165]
	v_mfma_f32_16x16x32_bf16 v[8:11], v[16:19], v[60:63], 0
	v_mfma_f32_16x16x32_bf16 v[12:15], v[24:27], v[60:63], 0
	v_mfma_f32_16x16x32_bf16 v[8:11], v[20:23], v[100:103], v[8:11]
	v_mfma_f32_16x16x32_bf16 v[12:15], v[28:31], v[100:103], v[12:15]
	v_mfma_f32_16x16x32_bf16 v[60:63], v[16:19], v[104:107], 0
	v_mfma_f32_16x16x32_bf16 v[100:103], v[24:27], v[104:107], 0
	v_mfma_f32_16x16x32_bf16 v[104:107], v[16:19], v[112:115], 0
	v_mfma_f32_16x16x32_bf16 v[16:19], v[16:19], v[120:123], 0
	v_mfma_f32_16x16x32_bf16 v[60:63], v[20:23], v[108:111], v[60:63]
	v_mfma_f32_16x16x32_bf16 v[100:103], v[28:31], v[108:111], v[100:103]
	v_mfma_f32_16x16x32_bf16 v[104:107], v[20:23], v[116:119], v[104:107]
	v_mfma_f32_16x16x32_bf16 v[108:111], v[24:27], v[112:115], 0
	v_mfma_f32_16x16x32_bf16 v[16:19], v[20:23], v[124:127], v[16:19]
	v_mfma_f32_16x16x32_bf16 v[20:23], v[24:27], v[120:123], 0
	v_mfma_f32_16x16x32_bf16 v[108:111], v[28:31], v[116:119], v[108:111]
	v_mfma_f32_16x16x32_bf16 v[20:23], v[28:31], v[124:127], v[20:23]
	s_barrier
	s_add_i32 s66, 0, 0x18000
	s_add_i32 s72, 0, 0x1c000
	v_add_u32_e32 v220, s66, v137
	v_add_u32_e32 v228, s72, v137
	ds_read_b128 v[24:27], v220
	ds_read_b128 v[28:31], v220 offset:1024
	ds_read_b128 v[112:115], v220 offset:2048
	ds_read_b128 v[116:119], v220 offset:3072
	ds_read_b128 v[120:123], v228
	ds_read_b128 v[124:127], v228 offset:1024
	ds_read_b128 v[166:169], v228 offset:2048
	ds_read_b128 v[170:173], v228 offset:3072
	s_add_u32 s68, s38, 0x10100
	s_addc_u32 s69, s39, 0
	s_mov_b32 m0, s52
	v_lshl_add_u64 v[216:217], s[68:69], 0, v[128:129]
	ds_read_b128 v[174:177], v141 offset:32768
	ds_read_b128 v[178:181], v141 offset:33792
	ds_read_b128 v[182:185], v141 offset:34816
	ds_read_b128 v[186:189], v141 offset:35840
	ds_read_b128 v[190:193], v141 offset:36864
	ds_read_b128 v[194:197], v141 offset:37888
	ds_read_b128 v[198:201], v141 offset:38912
	ds_read_b128 v[202:205], v141 offset:39936
	global_load_lds_dwordx4 v[216:217], off
	v_lshl_add_u64 v[216:217], s[68:69], 0, v[130:131]
	s_mov_b32 m0, s53
	s_nop 0
	global_load_lds_dwordx4 v[216:217], off
	s_waitcnt vmcnt(8)
	s_waitcnt lgkmcnt(0)
	s_barrier
	s_waitcnt lgkmcnt(0)
	s_nop 0
	v_mfma_f32_16x16x32_bf16 v[64:67], v[24:27], v[174:177], v[64:67]
	v_mfma_f32_16x16x32_bf16 v[68:71], v[112:115], v[174:177], v[68:71]
	v_mfma_f32_16x16x32_bf16 v[72:75], v[24:27], v[182:185], v[72:75]
	v_mfma_f32_16x16x32_bf16 v[76:79], v[112:115], v[182:185], v[76:79]
	v_mfma_f32_16x16x32_bf16 v[80:83], v[24:27], v[190:193], v[80:83]
	v_mfma_f32_16x16x32_bf16 v[84:87], v[112:115], v[190:193], v[84:87]
	v_mfma_f32_16x16x32_bf16 v[88:91], v[24:27], v[198:201], v[88:91]
	v_mfma_f32_16x16x32_bf16 v[92:95], v[112:115], v[198:201], v[92:95]
	v_mfma_f32_16x16x32_bf16 v[64:67], v[28:31], v[178:181], v[64:67]
	v_mfma_f32_16x16x32_bf16 v[68:71], v[116:119], v[178:181], v[68:71]
	v_mfma_f32_16x16x32_bf16 v[72:75], v[28:31], v[186:189], v[72:75]
	v_mfma_f32_16x16x32_bf16 v[76:79], v[116:119], v[186:189], v[76:79]
	v_mfma_f32_16x16x32_bf16 v[80:83], v[28:31], v[194:197], v[80:83]
	v_mfma_f32_16x16x32_bf16 v[84:87], v[116:119], v[194:197], v[84:87]
	v_mfma_f32_16x16x32_bf16 v[88:91], v[28:31], v[202:205], v[88:91]
	v_mfma_f32_16x16x32_bf16 v[92:95], v[116:119], v[202:205], v[92:95]
	v_mfma_f32_16x16x32_bf16 v[96:99], v[120:123], v[174:177], v[96:99]
	v_mfma_f32_16x16x32_bf16 v[32:35], v[166:169], v[174:177], v[32:35]
	v_mfma_f32_16x16x32_bf16 v[36:39], v[120:123], v[182:185], v[36:39]
	v_mfma_f32_16x16x32_bf16 v[40:43], v[166:169], v[182:185], v[40:43]
	v_mfma_f32_16x16x32_bf16 v[44:47], v[120:123], v[190:193], v[44:47]
	v_mfma_f32_16x16x32_bf16 v[48:51], v[166:169], v[190:193], v[48:51]
	v_mfma_f32_16x16x32_bf16 v[52:55], v[120:123], v[198:201], v[52:55]
	v_mfma_f32_16x16x32_bf16 v[56:59], v[166:169], v[198:201], v[56:59]
	v_mfma_f32_16x16x32_bf16 v[96:99], v[124:127], v[178:181], v[96:99]
	v_mfma_f32_16x16x32_bf16 v[32:35], v[170:173], v[178:181], v[32:35]
	v_mfma_f32_16x16x32_bf16 v[36:39], v[124:127], v[186:189], v[36:39]
	v_mfma_f32_16x16x32_bf16 v[40:43], v[170:173], v[186:189], v[40:43]
	v_mfma_f32_16x16x32_bf16 v[44:47], v[124:127], v[194:197], v[44:47]
	v_mfma_f32_16x16x32_bf16 v[48:51], v[170:173], v[194:197], v[48:51]
	v_mfma_f32_16x16x32_bf16 v[52:55], v[124:127], v[202:205], v[52:55]
	v_mfma_f32_16x16x32_bf16 v[56:59], v[170:173], v[202:205], v[56:59]
	s_barrier
	s_add_i32 s68, s66, s50
	s_add_i32 s66, s68, 0x2000
	v_lshl_add_u64 v[208:209], v[208:209], 0, s[16:17]
	s_mov_b32 m0, s68
	s_add_u32 s70, s40, 0x10180
	ds_read_b128 v[174:177], v141 offset:49152
	ds_read_b128 v[178:181], v141 offset:50176
	ds_read_b128 v[182:185], v141 offset:51200
	ds_read_b128 v[186:189], v141 offset:52224
	ds_read_b128 v[190:193], v141 offset:53248
	ds_read_b128 v[194:197], v141 offset:54272
	ds_read_b128 v[198:201], v141 offset:55296
	ds_read_b128 v[202:205], v141 offset:56320
	global_load_lds_dwordx4 v[208:209], off
	v_lshl_add_u64 v[208:209], v[210:211], 0, s[16:17]
	s_mov_b32 m0, s66
	s_addc_u32 s71, s41, 0
	s_add_i32 s40, s72, s50
	global_load_lds_dwordx4 v[208:209], off
	v_lshl_add_u64 v[208:209], s[70:71], 0, v[128:129]
	s_mov_b32 m0, s40
	s_add_i32 s41, s40, 0x2000
	global_load_lds_dwordx4 v[208:209], off
	v_lshl_add_u64 v[208:209], s[70:71], 0, v[130:131]
	s_mov_b32 m0, s41
	s_nop 0
	global_load_lds_dwordx4 v[208:209], off
	v_lshl_add_u64 v[208:209], v[212:213], 0, s[16:17]
	s_mov_b32 m0, s54
	s_nop 0
	global_load_lds_dwordx4 v[208:209], off
	v_lshl_add_u64 v[208:209], v[214:215], 0, s[16:17]
	s_mov_b32 m0, s55
	s_nop 0
	global_load_lds_dwordx4 v[208:209], off
	s_waitcnt vmcnt(8)
	s_waitcnt lgkmcnt(0)
	s_barrier
	s_waitcnt lgkmcnt(0)
	s_nop 0
	v_mfma_f32_16x16x32_bf16 v[0:3], v[24:27], v[198:201], v[0:3]
	v_mfma_f32_16x16x32_bf16 v[4:7], v[112:115], v[198:201], v[4:7]
	v_mfma_f32_16x16x32_bf16 v[142:145], v[24:27], v[174:177], v[142:145]
	v_mfma_f32_16x16x32_bf16 v[146:149], v[112:115], v[174:177], v[146:149]
	v_mfma_f32_16x16x32_bf16 v[150:153], v[24:27], v[182:185], v[150:153]
	v_mfma_f32_16x16x32_bf16 v[154:157], v[112:115], v[182:185], v[154:157]
	v_mfma_f32_16x16x32_bf16 v[158:161], v[24:27], v[190:193], v[158:161]
	v_mfma_f32_16x16x32_bf16 v[162:165], v[112:115], v[190:193], v[162:165]
	v_mfma_f32_16x16x32_bf16 v[0:3], v[28:31], v[202:205], v[0:3]
	v_mfma_f32_16x16x32_bf16 v[4:7], v[116:119], v[202:205], v[4:7]
	v_mfma_f32_16x16x32_bf16 v[142:145], v[28:31], v[178:181], v[142:145]
	v_mfma_f32_16x16x32_bf16 v[146:149], v[116:119], v[178:181], v[146:149]
	v_mfma_f32_16x16x32_bf16 v[150:153], v[28:31], v[186:189], v[150:153]
	v_mfma_f32_16x16x32_bf16 v[154:157], v[116:119], v[186:189], v[154:157]
	v_mfma_f32_16x16x32_bf16 v[158:161], v[28:31], v[194:197], v[158:161]
	v_mfma_f32_16x16x32_bf16 v[162:165], v[116:119], v[194:197], v[162:165]
	v_mfma_f32_16x16x32_bf16 v[8:11], v[120:123], v[174:177], v[8:11]
	v_mfma_f32_16x16x32_bf16 v[12:15], v[166:169], v[174:177], v[12:15]
	v_mfma_f32_16x16x32_bf16 v[24:27], v[120:123], v[182:185], v[60:63]
	v_mfma_f32_16x16x32_bf16 v[28:31], v[166:169], v[182:185], v[100:103]
	v_mfma_f32_16x16x32_bf16 v[60:63], v[120:123], v[190:193], v[104:107]
	v_mfma_f32_16x16x32_bf16 v[100:103], v[166:169], v[190:193], v[108:111]
	v_mfma_f32_16x16x32_bf16 v[16:19], v[120:123], v[198:201], v[16:19]
	v_mfma_f32_16x16x32_bf16 v[20:23], v[166:169], v[198:201], v[20:23]
	v_mfma_f32_16x16x32_bf16 v[8:11], v[124:127], v[178:181], v[8:11]
	v_mfma_f32_16x16x32_bf16 v[12:15], v[170:173], v[178:181], v[12:15]
	v_mfma_f32_16x16x32_bf16 v[24:27], v[124:127], v[186:189], v[24:27]
	v_mfma_f32_16x16x32_bf16 v[28:31], v[170:173], v[186:189], v[28:31]
	v_mfma_f32_16x16x32_bf16 v[60:63], v[124:127], v[194:197], v[60:63]
	v_mfma_f32_16x16x32_bf16 v[100:103], v[170:173], v[194:197], v[100:103]
	v_mfma_f32_16x16x32_bf16 v[16:19], v[124:127], v[202:205], v[16:19]
	v_mfma_f32_16x16x32_bf16 v[20:23], v[170:173], v[202:205], v[20:23]
	s_barrier
	ds_read_b128 v[104:107], v139
	ds_read_b128 v[108:111], v139 offset:1024
	ds_read_b128 v[112:115], v139 offset:2048
	ds_read_b128 v[116:119], v139 offset:3072
	ds_read_b128 v[120:123], v140
	ds_read_b128 v[124:127], v140 offset:1024
	ds_read_b128 v[166:169], v140 offset:2048
	ds_read_b128 v[170:173], v140 offset:3072
	s_add_u32 s38, s38, 0x10180
	s_addc_u32 s39, s39, 0
	s_mov_b32 m0, s67
	v_lshl_add_u64 v[208:209], s[38:39], 0, v[128:129]
	ds_read_b128 v[174:177], v141
	ds_read_b128 v[178:181], v141 offset:1024
	ds_read_b128 v[182:185], v141 offset:2048
	ds_read_b128 v[186:189], v141 offset:3072
	ds_read_b128 v[190:193], v141 offset:4096
	ds_read_b128 v[194:197], v141 offset:5120
	ds_read_b128 v[198:201], v141 offset:6144
	ds_read_b128 v[202:205], v141 offset:7168
	global_load_lds_dwordx4 v[208:209], off
	v_lshl_add_u64 v[208:209], s[38:39], 0, v[130:131]
	s_mov_b32 m0, s27
	s_nop 0
	global_load_lds_dwordx4 v[208:209], off
	s_waitcnt vmcnt(8)
	s_waitcnt lgkmcnt(0)
	s_barrier
	s_waitcnt lgkmcnt(0)
	s_nop 0
	v_mfma_f32_16x16x32_bf16 v[64:67], v[104:107], v[174:177], v[64:67]
	v_mfma_f32_16x16x32_bf16 v[68:71], v[112:115], v[174:177], v[68:71]
	v_mfma_f32_16x16x32_bf16 v[72:75], v[104:107], v[182:185], v[72:75]
	v_mfma_f32_16x16x32_bf16 v[76:79], v[112:115], v[182:185], v[76:79]
	v_mfma_f32_16x16x32_bf16 v[80:83], v[104:107], v[190:193], v[80:83]
	v_mfma_f32_16x16x32_bf16 v[84:87], v[112:115], v[190:193], v[84:87]
	v_mfma_f32_16x16x32_bf16 v[88:91], v[104:107], v[198:201], v[88:91]
	v_mfma_f32_16x16x32_bf16 v[64:67], v[108:111], v[178:181], v[64:67]
	v_mfma_f32_16x16x32_bf16 v[68:71], v[116:119], v[178:181], v[68:71]
	v_mfma_f32_16x16x32_bf16 v[72:75], v[108:111], v[186:189], v[72:75]
	v_mfma_f32_16x16x32_bf16 v[76:79], v[116:119], v[186:189], v[76:79]
	v_mfma_f32_16x16x32_bf16 v[80:83], v[108:111], v[194:197], v[80:83]
	v_mfma_f32_16x16x32_bf16 v[84:87], v[116:119], v[194:197], v[84:87]
	v_mfma_f32_16x16x32_bf16 v[88:91], v[108:111], v[202:205], v[88:91]
	v_mfma_f32_16x16x32_bf16 v[92:95], v[112:115], v[198:201], v[92:95]
	v_mfma_f32_16x16x32_bf16 v[208:211], v[116:119], v[202:205], v[92:95]
	v_mfma_f32_16x16x32_bf16 v[48:51], v[166:169], v[190:193], v[48:51]
	v_mfma_f32_16x16x32_bf16 v[92:95], v[120:123], v[174:177], v[96:99]
	v_mfma_f32_16x16x32_bf16 v[32:35], v[166:169], v[174:177], v[32:35]
	v_mfma_f32_16x16x32_bf16 v[36:39], v[120:123], v[182:185], v[36:39]
	v_mfma_f32_16x16x32_bf16 v[40:43], v[166:169], v[182:185], v[40:43]
	v_mfma_f32_16x16x32_bf16 v[44:47], v[120:123], v[190:193], v[44:47]
	v_mfma_f32_16x16x32_bf16 v[174:177], v[170:173], v[194:197], v[48:51]
	v_mfma_f32_16x16x32_bf16 v[48:51], v[120:123], v[198:201], v[52:55]
	v_mfma_f32_16x16x32_bf16 v[32:35], v[170:173], v[178:181], v[32:35]
	v_mfma_f32_16x16x32_bf16 v[36:39], v[124:127], v[186:189], v[36:39]
	v_mfma_f32_16x16x32_bf16 v[40:43], v[170:173], v[186:189], v[40:43]
	v_mfma_f32_16x16x32_bf16 v[44:47], v[124:127], v[194:197], v[44:47]
	v_mfma_f32_16x16x32_bf16 v[52:55], v[124:127], v[202:205], v[48:51]
	v_mfma_f32_16x16x32_bf16 v[48:51], v[166:169], v[198:201], v[56:59]
	v_mfma_f32_16x16x32_bf16 v[212:215], v[124:127], v[178:181], v[92:95]
	v_mfma_f32_16x16x32_bf16 v[178:181], v[170:173], v[202:205], v[48:51]
	s_barrier
	s_mov_b32 m0, s65
	v_lshl_add_u64 v[248:249], s[42:43], 0, v[128:129]
	s_add_u32 s38, s42, 0x10000
	s_nop 0
	ds_read_b128 v[48:51], v141 offset:16384
	ds_read_b128 v[56:59], v141 offset:17408
	ds_read_b128 v[92:95], v141 offset:18432
	ds_read_b128 v[96:99], v141 offset:19456
	ds_read_b128 v[182:185], v141 offset:20480
	ds_read_b128 v[186:189], v141 offset:21504
	ds_read_b128 v[190:193], v141 offset:22528
	ds_read_b128 v[194:197], v141 offset:23552
	global_load_lds_dwordx4 v[248:249], off
	v_lshl_add_u64 v[250:251], s[42:43], 0, v[130:131]
	s_mov_b32 m0, s29
	s_addc_u32 s39, s43, 0
	global_load_lds_dwordx4 v[250:251], off
	v_lshl_add_u64 v[198:199], s[38:39], 0, v[128:129]
	s_mov_b32 m0, s63
	v_lshl_add_u64 v[252:253], s[44:45], 0, v[128:129]
	global_load_lds_dwordx4 v[198:199], off
	v_lshl_add_u64 v[198:199], s[38:39], 0, v[130:131]
	s_mov_b32 m0, s64
	v_lshl_add_u64 v[132:133], s[44:45], 0, v[130:131]
	global_load_lds_dwordx4 v[198:199], off
	s_mov_b32 m0, s37
	s_nop 0
	global_load_lds_dwordx4 v[252:253], off
	s_mov_b32 m0, s51
	s_nop 0
	global_load_lds_dwordx4 v[132:133], off
	s_waitcnt vmcnt(8)
	s_waitcnt lgkmcnt(0)
	s_barrier
	s_waitcnt lgkmcnt(0)
	s_nop 0
	v_mfma_f32_16x16x32_bf16 v[0:3], v[104:107], v[190:193], v[0:3]
	v_mfma_f32_16x16x32_bf16 v[4:7], v[112:115], v[190:193], v[4:7]
	v_mfma_f32_16x16x32_bf16 v[142:145], v[104:107], v[48:51], v[142:145]
	v_mfma_f32_16x16x32_bf16 v[146:149], v[112:115], v[48:51], v[146:149]
	v_mfma_f32_16x16x32_bf16 v[150:153], v[104:107], v[92:95], v[150:153]
	v_mfma_f32_16x16x32_bf16 v[154:157], v[112:115], v[92:95], v[154:157]
	v_mfma_f32_16x16x32_bf16 v[158:161], v[104:107], v[182:185], v[158:161]
	v_mfma_f32_16x16x32_bf16 v[162:165], v[112:115], v[182:185], v[162:165]
	v_mfma_f32_16x16x32_bf16 v[0:3], v[108:111], v[194:197], v[0:3]
	v_mfma_f32_16x16x32_bf16 v[4:7], v[116:119], v[194:197], v[4:7]
	v_mfma_f32_16x16x32_bf16 v[142:145], v[108:111], v[56:59], v[142:145]
	v_mfma_f32_16x16x32_bf16 v[146:149], v[116:119], v[56:59], v[146:149]
	v_mfma_f32_16x16x32_bf16 v[150:153], v[108:111], v[96:99], v[150:153]
	v_mfma_f32_16x16x32_bf16 v[154:157], v[116:119], v[96:99], v[154:157]
	v_mfma_f32_16x16x32_bf16 v[158:161], v[108:111], v[186:189], v[158:161]
	v_mfma_f32_16x16x32_bf16 v[162:165], v[116:119], v[186:189], v[162:165]
	v_mfma_f32_16x16x32_bf16 v[12:15], v[166:169], v[48:51], v[12:15]
	v_mfma_f32_16x16x32_bf16 v[198:201], v[170:173], v[56:59], v[12:15]
	v_mfma_f32_16x16x32_bf16 v[12:15], v[120:123], v[92:95], v[24:27]
	v_mfma_f32_16x16x32_bf16 v[24:27], v[124:127], v[96:99], v[12:15]
	v_mfma_f32_16x16x32_bf16 v[12:15], v[166:169], v[92:95], v[28:31]
	v_mfma_f32_16x16x32_bf16 v[202:205], v[170:173], v[96:99], v[12:15]
	v_mfma_f32_16x16x32_bf16 v[12:15], v[120:123], v[182:185], v[60:63]
	v_mfma_f32_16x16x32_bf16 v[216:219], v[124:127], v[186:189], v[12:15]
	v_mfma_f32_16x16x32_bf16 v[12:15], v[166:169], v[182:185], v[100:103]
	v_mfma_f32_16x16x32_bf16 v[8:11], v[120:123], v[48:51], v[8:11]
	v_mfma_f32_16x16x32_bf16 v[182:185], v[170:173], v[186:189], v[12:15]
	v_mfma_f32_16x16x32_bf16 v[12:15], v[120:123], v[190:193], v[16:19]
	v_mfma_f32_16x16x32_bf16 v[8:11], v[124:127], v[56:59], v[8:11]
	v_mfma_f32_16x16x32_bf16 v[186:189], v[124:127], v[194:197], v[12:15]
	v_mfma_f32_16x16x32_bf16 v[12:15], v[166:169], v[190:193], v[20:23]
	v_mfma_f32_16x16x32_bf16 v[166:169], v[170:173], v[194:197], v[12:15]
	s_barrier
	s_nop 4
	ds_read_b128 v[12:15], v220
	ds_read_b128 v[20:23], v220 offset:1024
	ds_read_b128 v[170:173], v220 offset:2048
	ds_read_b128 v[190:193], v220 offset:3072
	ds_read_b128 v[194:197], v228
	ds_read_b128 v[220:223], v228 offset:1024
	ds_read_b128 v[224:227], v228 offset:2048
	ds_read_b128 v[228:231], v228 offset:3072
	s_add_u32 s38, s44, 0x10000
	s_addc_u32 s39, s45, 0
	s_mov_b32 m0, s52
	v_lshl_add_u64 v[48:49], s[38:39], 0, v[128:129]
	ds_read_b128 v[16:19], v141 offset:32768
	ds_read_b128 v[28:31], v141 offset:33792
	ds_read_b128 v[56:59], v141 offset:34816
	ds_read_b128 v[100:103], v141 offset:35840
	ds_read_b128 v[232:235], v141 offset:36864
	ds_read_b128 v[236:239], v141 offset:37888
	ds_read_b128 v[240:243], v141 offset:38912
	ds_read_b128 v[244:247], v141 offset:39936
	global_load_lds_dwordx4 v[48:49], off
	v_lshl_add_u64 v[48:49], s[38:39], 0, v[130:131]
	s_mov_b32 m0, s53
	s_nop 0
	global_load_lds_dwordx4 v[48:49], off
	s_waitcnt vmcnt(8)
	s_waitcnt lgkmcnt(0)
	s_barrier
	s_waitcnt lgkmcnt(0)
	v_mfma_f32_16x16x32_bf16 v[48:51], v[12:15], v[16:19], v[64:67]
	v_mfma_f32_16x16x32_bf16 v[124:127], v[20:23], v[28:31], v[48:51]
	v_mfma_f32_16x16x32_bf16 v[48:51], v[170:173], v[16:19], v[68:71]
	v_mfma_f32_16x16x32_bf16 v[112:115], v[190:193], v[28:31], v[48:51]
	v_mfma_f32_16x16x32_bf16 v[48:51], v[12:15], v[56:59], v[72:75]
	v_mfma_f32_16x16x32_bf16 v[108:111], v[20:23], v[100:103], v[48:51]
	v_mfma_f32_16x16x32_bf16 v[48:51], v[170:173], v[56:59], v[76:79]
	v_mfma_f32_16x16x32_bf16 v[96:99], v[190:193], v[100:103], v[48:51]
	v_mfma_f32_16x16x32_bf16 v[48:51], v[12:15], v[232:235], v[80:83]
	v_mfma_f32_16x16x32_bf16 v[92:95], v[20:23], v[236:239], v[48:51]
	v_mfma_f32_16x16x32_bf16 v[48:51], v[170:173], v[232:235], v[84:87]
	v_mfma_f32_16x16x32_bf16 v[80:83], v[190:193], v[236:239], v[48:51]
	v_mfma_f32_16x16x32_bf16 v[48:51], v[12:15], v[240:243], v[88:91]
	v_mfma_f32_16x16x32_bf16 v[60:63], v[20:23], v[244:247], v[48:51]
	v_mfma_f32_16x16x32_bf16 v[48:51], v[170:173], v[240:243], v[208:211]
	v_mfma_f32_16x16x32_bf16 v[48:51], v[190:193], v[244:247], v[48:51]
	v_mfma_f32_16x16x32_bf16 v[64:67], v[194:197], v[16:19], v[212:215]
	v_mfma_f32_16x16x32_bf16 v[16:19], v[224:227], v[16:19], v[32:35]
	v_mfma_f32_16x16x32_bf16 v[116:119], v[228:231], v[28:31], v[16:19]
	v_mfma_f32_16x16x32_bf16 v[16:19], v[194:197], v[56:59], v[36:39]
	v_mfma_f32_16x16x32_bf16 v[104:107], v[220:223], v[100:103], v[16:19]
	v_mfma_f32_16x16x32_bf16 v[16:19], v[224:227], v[56:59], v[40:43]
	v_mfma_f32_16x16x32_bf16 v[100:103], v[228:231], v[100:103], v[16:19]
	v_mfma_f32_16x16x32_bf16 v[16:19], v[194:197], v[232:235], v[44:47]
	v_mfma_f32_16x16x32_bf16 v[88:91], v[220:223], v[236:239], v[16:19]
	v_mfma_f32_16x16x32_bf16 v[16:19], v[224:227], v[232:235], v[174:177]
	v_mfma_f32_16x16x32_bf16 v[84:87], v[228:231], v[236:239], v[16:19]
	v_mfma_f32_16x16x32_bf16 v[16:19], v[194:197], v[240:243], v[52:55]
	v_mfma_f32_16x16x32_bf16 v[56:59], v[220:223], v[244:247], v[16:19]
	v_mfma_f32_16x16x32_bf16 v[16:19], v[224:227], v[240:243], v[178:181]
	v_mfma_f32_16x16x32_bf16 v[120:123], v[220:223], v[28:31], v[64:67]
	v_mfma_f32_16x16x32_bf16 v[52:55], v[228:231], v[244:247], v[16:19]
	s_barrier
	s_mov_b32 m0, s68
	s_nop 2
	v_lshl_add_u64 v[16:17], v[248:249], 0, s[8:9]
	s_add_u32 s38, s42, 0x10080
	ds_read_b128 v[36:39], v141 offset:49152
	ds_read_b128 v[40:43], v141 offset:50176
	ds_read_b128 v[174:177], v141 offset:51200
	ds_read_b128 v[178:181], v141 offset:52224
	ds_read_b128 v[208:211], v141 offset:53248
	ds_read_b128 v[212:215], v141 offset:54272
	ds_read_b128 v[232:235], v141 offset:55296
	ds_read_b128 v[236:239], v141 offset:56320
	global_load_lds_dwordx4 v[16:17], off
	v_lshl_add_u64 v[16:17], v[250:251], 0, s[8:9]
	s_mov_b32 m0, s66
	s_addc_u32 s39, s43, 0
	global_load_lds_dwordx4 v[16:17], off
	v_lshl_add_u64 v[16:17], s[38:39], 0, v[128:129]
	s_mov_b32 m0, s40
	s_nop 0
	global_load_lds_dwordx4 v[16:17], off
	v_lshl_add_u64 v[16:17], s[38:39], 0, v[130:131]
	s_mov_b32 m0, s41
	s_nop 0
	global_load_lds_dwordx4 v[16:17], off
	v_lshl_add_u64 v[16:17], v[252:253], 0, s[8:9]
	s_mov_b32 m0, s54
	s_nop 0
	global_load_lds_dwordx4 v[16:17], off
	v_lshl_add_u64 v[16:17], v[132:133], 0, s[8:9]
	s_mov_b32 m0, s55
	s_nop 0
	global_load_lds_dwordx4 v[16:17], off
	s_waitcnt vmcnt(8)
	s_waitcnt lgkmcnt(0)
	s_barrier
	s_waitcnt lgkmcnt(0)
	s_nop 0
	v_mfma_f32_16x16x32_bf16 v[16:19], v[12:15], v[36:39], v[142:145]
	v_mfma_f32_16x16x32_bf16 v[76:79], v[20:23], v[40:43], v[16:19]
	v_mfma_f32_16x16x32_bf16 v[16:19], v[170:173], v[36:39], v[146:149]
	v_mfma_f32_16x16x32_bf16 v[64:67], v[190:193], v[40:43], v[16:19]
	v_mfma_f32_16x16x32_bf16 v[16:19], v[12:15], v[174:177], v[150:153]
	v_mfma_f32_16x16x32_bf16 v[44:47], v[20:23], v[178:181], v[16:19]
	v_mfma_f32_16x16x32_bf16 v[16:19], v[170:173], v[174:177], v[154:157]
	v_mfma_f32_16x16x32_bf16 v[32:35], v[190:193], v[178:181], v[16:19]
	v_mfma_f32_16x16x32_bf16 v[16:19], v[12:15], v[208:211], v[158:161]
	v_mfma_f32_16x16x32_bf16 v[0:3], v[12:15], v[232:235], v[0:3]
	v_mfma_f32_16x16x32_bf16 v[28:31], v[20:23], v[212:215], v[16:19]
	v_mfma_f32_16x16x32_bf16 v[16:19], v[170:173], v[208:211], v[162:165]
	v_mfma_f32_16x16x32_bf16 v[12:15], v[20:23], v[236:239], v[0:3]
	v_mfma_f32_16x16x32_bf16 v[0:3], v[170:173], v[232:235], v[4:7]
	v_mfma_f32_16x16x32_bf16 v[16:19], v[190:193], v[212:215], v[16:19]
	v_mfma_f32_16x16x32_bf16 v[0:3], v[190:193], v[236:239], v[0:3]
	v_mfma_f32_16x16x32_bf16 v[4:7], v[194:197], v[36:39], v[8:11]
	v_mfma_f32_16x16x32_bf16 v[72:75], v[220:223], v[40:43], v[4:7]
	v_mfma_f32_16x16x32_bf16 v[4:7], v[224:227], v[36:39], v[198:201]
	v_mfma_f32_16x16x32_bf16 v[68:71], v[228:231], v[40:43], v[4:7]
	v_mfma_f32_16x16x32_bf16 v[4:7], v[194:197], v[174:177], v[24:27]
	v_mfma_f32_16x16x32_bf16 v[40:43], v[220:223], v[178:181], v[4:7]
	v_mfma_f32_16x16x32_bf16 v[4:7], v[224:227], v[174:177], v[202:205]
	v_mfma_f32_16x16x32_bf16 v[36:39], v[228:231], v[178:181], v[4:7]
	v_mfma_f32_16x16x32_bf16 v[4:7], v[194:197], v[208:211], v[216:219]
	v_mfma_f32_16x16x32_bf16 v[24:27], v[220:223], v[212:215], v[4:7]
	v_mfma_f32_16x16x32_bf16 v[4:7], v[224:227], v[208:211], v[182:185]
	v_mfma_f32_16x16x32_bf16 v[20:23], v[228:231], v[212:215], v[4:7]
	v_mfma_f32_16x16x32_bf16 v[4:7], v[194:197], v[232:235], v[186:189]
	v_mfma_f32_16x16x32_bf16 v[8:11], v[220:223], v[236:239], v[4:7]
	v_mfma_f32_16x16x32_bf16 v[4:7], v[224:227], v[232:235], v[166:169]
	v_mfma_f32_16x16x32_bf16 v[4:7], v[228:231], v[236:239], v[4:7]
	s_barrier
	s_andn2_b64 vcc, exec, s[10:11]
	s_cbranch_vccnz .LBB0_1485
	s_barrier

.LBB0_1561:
	ds_read_b128 v[140:143], v151
	ds_read_b128 v[144:147], v151 offset:1024
	ds_read_b128 v[156:159], v151 offset:2048
	ds_read_b128 v[160:163], v151 offset:3072
	ds_read_b128 v[164:167], v152
	ds_read_b128 v[168:171], v152 offset:1024
	ds_read_b128 v[172:175], v152 offset:2048
	ds_read_b128 v[176:179], v152 offset:3072
	s_add_u32 s38, s36, 0xfffc0080
	s_addc_u32 s39, s37, -1
	s_cmp_eq_u32 s61, 12
	s_cselect_b32 s41, s3, s39
	s_cselect_b32 s40, s29, s38
	s_cselect_b32 s39, s27, s60
	s_cselect_b32 s38, s58, s59
	s_add_i32 m0, s46, 0xc000
	ds_read_b128 v[180:183], v153
	ds_read_b128 v[184:187], v153 offset:1024
	ds_read_b128 v[188:191], v153 offset:2048
	ds_read_b128 v[192:195], v153 offset:3072
	ds_read_b128 v[196:199], v153 offset:4096
	ds_read_b128 v[200:203], v153 offset:5120
	ds_read_b128 v[208:211], v153 offset:6144
	ds_read_b128 v[212:215], v153 offset:7168
	global_load_lds_dwordx4 v134, s[36:37]
	s_add_i32 m0, s46, 0xe000
	s_nop 0
	global_load_lds_dwordx4 v132, s[36:37]
	s_waitcnt vmcnt(8)
	s_waitcnt lgkmcnt(0)
	s_barrier
	s_waitcnt lgkmcnt(0)
	v_mfma_f32_16x16x32_bf16 v[124:127], v[140:143], v[180:183], v[124:127]
	v_mfma_f32_16x16x32_bf16 v[120:123], v[156:159], v[180:183], v[120:123]
	v_mfma_f32_16x16x32_bf16 v[108:111], v[140:143], v[188:191], v[108:111]
	v_mfma_f32_16x16x32_bf16 v[104:107], v[156:159], v[188:191], v[104:107]
	v_mfma_f32_16x16x32_bf16 v[92:95], v[140:143], v[196:199], v[92:95]
	v_mfma_f32_16x16x32_bf16 v[88:91], v[156:159], v[196:199], v[88:91]
	v_mfma_f32_16x16x32_bf16 v[76:79], v[140:143], v[208:211], v[76:79]
	v_mfma_f32_16x16x32_bf16 v[72:75], v[156:159], v[208:211], v[72:75]
	v_mfma_f32_16x16x32_bf16 v[124:127], v[144:147], v[184:187], v[124:127]
	v_mfma_f32_16x16x32_bf16 v[120:123], v[160:163], v[184:187], v[120:123]
	v_mfma_f32_16x16x32_bf16 v[108:111], v[144:147], v[192:195], v[108:111]
	v_mfma_f32_16x16x32_bf16 v[104:107], v[160:163], v[192:195], v[104:107]
	v_mfma_f32_16x16x32_bf16 v[92:95], v[144:147], v[200:203], v[92:95]
	v_mfma_f32_16x16x32_bf16 v[88:91], v[160:163], v[200:203], v[88:91]
	v_mfma_f32_16x16x32_bf16 v[76:79], v[144:147], v[212:215], v[76:79]
	v_mfma_f32_16x16x32_bf16 v[72:75], v[160:163], v[212:215], v[72:75]
	v_mfma_f32_16x16x32_bf16 v[116:119], v[164:167], v[180:183], v[116:119]
	v_mfma_f32_16x16x32_bf16 v[112:115], v[172:175], v[180:183], v[112:115]
	v_mfma_f32_16x16x32_bf16 v[100:103], v[164:167], v[188:191], v[100:103]
	v_mfma_f32_16x16x32_bf16 v[96:99], v[172:175], v[188:191], v[96:99]
	v_mfma_f32_16x16x32_bf16 v[84:87], v[164:167], v[196:199], v[84:87]
	v_mfma_f32_16x16x32_bf16 v[80:83], v[172:175], v[196:199], v[80:83]
	v_mfma_f32_16x16x32_bf16 v[68:71], v[164:167], v[208:211], v[68:71]
	v_mfma_f32_16x16x32_bf16 v[64:67], v[172:175], v[208:211], v[64:67]
	v_mfma_f32_16x16x32_bf16 v[116:119], v[168:171], v[184:187], v[116:119]
	v_mfma_f32_16x16x32_bf16 v[112:115], v[176:179], v[184:187], v[112:115]
	v_mfma_f32_16x16x32_bf16 v[100:103], v[168:171], v[192:195], v[100:103]
	v_mfma_f32_16x16x32_bf16 v[96:99], v[176:179], v[192:195], v[96:99]
	v_mfma_f32_16x16x32_bf16 v[84:87], v[168:171], v[200:203], v[84:87]
	v_mfma_f32_16x16x32_bf16 v[80:83], v[176:179], v[200:203], v[80:83]
	v_mfma_f32_16x16x32_bf16 v[68:71], v[168:171], v[212:215], v[68:71]
	v_mfma_f32_16x16x32_bf16 v[64:67], v[176:179], v[212:215], v[64:67]
	s_barrier
	s_add_i32 s62, s54, s45
	s_mov_b32 m0, s62
	ds_read_b128 v[180:183], v153 offset:16384
	ds_read_b128 v[184:187], v153 offset:17408
	ds_read_b128 v[188:191], v153 offset:18432
	ds_read_b128 v[192:195], v153 offset:19456
	ds_read_b128 v[196:199], v153 offset:20480
	ds_read_b128 v[200:203], v153 offset:21504
	ds_read_b128 v[208:211], v153 offset:22528
	ds_read_b128 v[212:215], v153 offset:23552
	global_load_lds_dwordx4 v128, s[38:39]
	s_add_i32 m0, s62, 0x2000
	s_add_u32 s62, s38, 0x40000
	s_mov_b64 s[98:99], s[38:39]
	s_addc_u32 s63, s39, 0
	s_add_i32 s64, s55, s45
	global_load_lds_dwordx4 v130, s[38:39]
	s_mov_b32 m0, s64
	s_mov_b64 s[100:101], s[40:41]
	global_load_lds_dwordx4 v128, s[62:63]
	s_add_i32 m0, s64, 0x2000
	s_nop 0
	global_load_lds_dwordx4 v130, s[62:63]
	s_mov_b32 m0, s46
	s_nop 0
	global_load_lds_dwordx4 v128, s[40:41]
	s_mov_b32 m0, s47
	s_nop 0
	global_load_lds_dwordx4 v130, s[40:41]
	s_waitcnt vmcnt(8)
	s_waitcnt lgkmcnt(0)
	s_barrier
	s_waitcnt lgkmcnt(0)
	s_nop 0
	v_mfma_f32_16x16x32_bf16 v[60:63], v[140:143], v[180:183], v[60:63]
	v_mfma_f32_16x16x32_bf16 v[56:59], v[156:159], v[180:183], v[56:59]
	v_mfma_f32_16x16x32_bf16 v[44:47], v[140:143], v[188:191], v[44:47]
	v_mfma_f32_16x16x32_bf16 v[40:43], v[156:159], v[188:191], v[40:43]
	v_mfma_f32_16x16x32_bf16 v[28:31], v[140:143], v[196:199], v[28:31]
	v_mfma_f32_16x16x32_bf16 v[24:27], v[156:159], v[196:199], v[24:27]
	v_mfma_f32_16x16x32_bf16 v[12:15], v[140:143], v[208:211], v[12:15]
	v_mfma_f32_16x16x32_bf16 v[8:11], v[156:159], v[208:211], v[8:11]
	v_mfma_f32_16x16x32_bf16 v[60:63], v[144:147], v[184:187], v[60:63]
	v_mfma_f32_16x16x32_bf16 v[56:59], v[160:163], v[184:187], v[56:59]
	v_mfma_f32_16x16x32_bf16 v[44:47], v[144:147], v[192:195], v[44:47]
	v_mfma_f32_16x16x32_bf16 v[40:43], v[160:163], v[192:195], v[40:43]
	v_mfma_f32_16x16x32_bf16 v[28:31], v[144:147], v[200:203], v[28:31]
	v_mfma_f32_16x16x32_bf16 v[24:27], v[160:163], v[200:203], v[24:27]
	v_mfma_f32_16x16x32_bf16 v[12:15], v[144:147], v[212:215], v[12:15]
	v_mfma_f32_16x16x32_bf16 v[8:11], v[160:163], v[212:215], v[8:11]
	v_mfma_f32_16x16x32_bf16 v[52:55], v[164:167], v[180:183], v[52:55]
	v_mfma_f32_16x16x32_bf16 v[48:51], v[172:175], v[180:183], v[48:51]
	v_mfma_f32_16x16x32_bf16 v[36:39], v[164:167], v[188:191], v[36:39]
	v_mfma_f32_16x16x32_bf16 v[32:35], v[172:175], v[188:191], v[32:35]
	v_mfma_f32_16x16x32_bf16 v[20:23], v[164:167], v[196:199], v[20:23]
	v_mfma_f32_16x16x32_bf16 v[16:19], v[172:175], v[196:199], v[16:19]
	v_mfma_f32_16x16x32_bf16 v[4:7], v[164:167], v[208:211], v[4:7]
	v_mfma_f32_16x16x32_bf16 v[0:3], v[172:175], v[208:211], v[0:3]
	v_mfma_f32_16x16x32_bf16 v[52:55], v[168:171], v[184:187], v[52:55]
	v_mfma_f32_16x16x32_bf16 v[48:51], v[176:179], v[184:187], v[48:51]
	v_mfma_f32_16x16x32_bf16 v[36:39], v[168:171], v[192:195], v[36:39]
	v_mfma_f32_16x16x32_bf16 v[32:35], v[176:179], v[192:195], v[32:35]
	v_mfma_f32_16x16x32_bf16 v[20:23], v[168:171], v[200:203], v[20:23]
	v_mfma_f32_16x16x32_bf16 v[16:19], v[176:179], v[200:203], v[16:19]
	v_mfma_f32_16x16x32_bf16 v[4:7], v[168:171], v[212:215], v[4:7]
	v_mfma_f32_16x16x32_bf16 v[0:3], v[176:179], v[212:215], v[0:3]
	s_barrier
	s_add_i32 s62, 0, 0x18000
	v_add_u32_e32 v155, s62, v149
	s_add_i32 s63, 0, 0x1c000
	ds_read_b128 v[140:143], v155
	ds_read_b128 v[144:147], v155 offset:1024
	ds_read_b128 v[156:159], v155 offset:2048
	ds_read_b128 v[160:163], v155 offset:3072
	v_add_u32_e32 v155, s63, v149
	ds_read_b128 v[164:167], v155
	ds_read_b128 v[168:171], v155 offset:1024
	ds_read_b128 v[172:175], v155 offset:2048
	ds_read_b128 v[176:179], v155 offset:3072
	s_add_u32 s40, s40, 0x40000
	s_addc_u32 s41, s41, 0
	s_mov_b32 m0, s48
	ds_read_b128 v[180:183], v153 offset:32768
	ds_read_b128 v[184:187], v153 offset:33792
	ds_read_b128 v[188:191], v153 offset:34816
	ds_read_b128 v[192:195], v153 offset:35840
	ds_read_b128 v[196:199], v153 offset:36864
	ds_read_b128 v[200:203], v153 offset:37888
	ds_read_b128 v[208:211], v153 offset:38912
	ds_read_b128 v[212:215], v153 offset:39936
	global_load_lds_dwordx4 v128, s[40:41]
	s_mov_b32 m0, s49
	s_nop 0
	global_load_lds_dwordx4 v130, s[40:41]
	s_waitcnt vmcnt(8)
	s_waitcnt lgkmcnt(0)
	s_barrier
	s_waitcnt lgkmcnt(0)
	s_nop 0
	v_mfma_f32_16x16x32_bf16 v[124:127], v[140:143], v[180:183], v[124:127]
	v_mfma_f32_16x16x32_bf16 v[120:123], v[156:159], v[180:183], v[120:123]
	v_mfma_f32_16x16x32_bf16 v[108:111], v[140:143], v[188:191], v[108:111]
	v_mfma_f32_16x16x32_bf16 v[104:107], v[156:159], v[188:191], v[104:107]
	v_mfma_f32_16x16x32_bf16 v[92:95], v[140:143], v[196:199], v[92:95]
	v_mfma_f32_16x16x32_bf16 v[88:91], v[156:159], v[196:199], v[88:91]
	v_mfma_f32_16x16x32_bf16 v[76:79], v[140:143], v[208:211], v[76:79]
	v_mfma_f32_16x16x32_bf16 v[72:75], v[156:159], v[208:211], v[72:75]
	v_mfma_f32_16x16x32_bf16 v[124:127], v[144:147], v[184:187], v[124:127]
	v_mfma_f32_16x16x32_bf16 v[120:123], v[160:163], v[184:187], v[120:123]
	v_mfma_f32_16x16x32_bf16 v[108:111], v[144:147], v[192:195], v[108:111]
	v_mfma_f32_16x16x32_bf16 v[104:107], v[160:163], v[192:195], v[104:107]
	v_mfma_f32_16x16x32_bf16 v[92:95], v[144:147], v[200:203], v[92:95]
	v_mfma_f32_16x16x32_bf16 v[88:91], v[160:163], v[200:203], v[88:91]
	v_mfma_f32_16x16x32_bf16 v[76:79], v[144:147], v[212:215], v[76:79]
	v_mfma_f32_16x16x32_bf16 v[72:75], v[160:163], v[212:215], v[72:75]
	v_mfma_f32_16x16x32_bf16 v[116:119], v[164:167], v[180:183], v[116:119]
	v_mfma_f32_16x16x32_bf16 v[112:115], v[172:175], v[180:183], v[112:115]
	v_mfma_f32_16x16x32_bf16 v[100:103], v[164:167], v[188:191], v[100:103]
	v_mfma_f32_16x16x32_bf16 v[96:99], v[172:175], v[188:191], v[96:99]
	v_mfma_f32_16x16x32_bf16 v[84:87], v[164:167], v[196:199], v[84:87]
	v_mfma_f32_16x16x32_bf16 v[80:83], v[172:175], v[196:199], v[80:83]
	v_mfma_f32_16x16x32_bf16 v[68:71], v[164:167], v[208:211], v[68:71]
	v_mfma_f32_16x16x32_bf16 v[64:67], v[172:175], v[208:211], v[64:67]
	v_mfma_f32_16x16x32_bf16 v[116:119], v[168:171], v[184:187], v[116:119]
	v_mfma_f32_16x16x32_bf16 v[112:115], v[176:179], v[184:187], v[112:115]
	v_mfma_f32_16x16x32_bf16 v[100:103], v[168:171], v[192:195], v[100:103]
	v_mfma_f32_16x16x32_bf16 v[96:99], v[176:179], v[192:195], v[96:99]
	v_mfma_f32_16x16x32_bf16 v[84:87], v[168:171], v[200:203], v[84:87]
	v_mfma_f32_16x16x32_bf16 v[80:83], v[176:179], v[200:203], v[80:83]
	v_mfma_f32_16x16x32_bf16 v[68:71], v[168:171], v[212:215], v[68:71]
	v_mfma_f32_16x16x32_bf16 v[64:67], v[176:179], v[212:215], v[64:67]
	s_barrier
	s_add_i32 s40, s62, s45
	s_mov_b32 m0, s40
	ds_read_b128 v[180:183], v153 offset:49152
	ds_read_b128 v[184:187], v153 offset:50176
	ds_read_b128 v[188:191], v153 offset:51200
	ds_read_b128 v[192:195], v153 offset:52224
	ds_read_b128 v[196:199], v153 offset:53248
	ds_read_b128 v[200:203], v153 offset:54272
	ds_read_b128 v[208:211], v153 offset:55296
	ds_read_b128 v[212:215], v153 offset:56320
	global_load_lds_dwordx4 v204, s[38:39]
	s_add_i32 m0, s40, 0x2000
	s_add_u32 s38, s38, 0x40080
	s_addc_u32 s39, s39, 0
	s_add_i32 s40, s63, s45
	global_load_lds_dwordx4 v205, s[98:99]
	s_mov_b32 m0, s40
	s_nop 0
	global_load_lds_dwordx4 v128, s[38:39]
	s_add_i32 m0, s40, 0x2000
	s_nop 0
	global_load_lds_dwordx4 v130, s[38:39]
	s_mov_b32 m0, s51
	s_nop 0
	global_load_lds_dwordx4 v204, s[100:101]
	s_mov_b32 m0, s52
	s_nop 0
	global_load_lds_dwordx4 v205, s[100:101]
	s_waitcnt vmcnt(8)
	s_waitcnt lgkmcnt(0)
	s_barrier
	s_waitcnt lgkmcnt(0)
	v_mfma_f32_16x16x32_bf16 v[60:63], v[140:143], v[180:183], v[60:63]
	v_mfma_f32_16x16x32_bf16 v[56:59], v[156:159], v[180:183], v[56:59]
	v_mfma_f32_16x16x32_bf16 v[44:47], v[140:143], v[188:191], v[44:47]
	v_mfma_f32_16x16x32_bf16 v[40:43], v[156:159], v[188:191], v[40:43]
	v_mfma_f32_16x16x32_bf16 v[28:31], v[140:143], v[196:199], v[28:31]
	v_mfma_f32_16x16x32_bf16 v[24:27], v[156:159], v[196:199], v[24:27]
	v_mfma_f32_16x16x32_bf16 v[12:15], v[140:143], v[208:211], v[12:15]
	v_mfma_f32_16x16x32_bf16 v[8:11], v[156:159], v[208:211], v[8:11]
	v_mfma_f32_16x16x32_bf16 v[60:63], v[144:147], v[184:187], v[60:63]
	v_mfma_f32_16x16x32_bf16 v[56:59], v[160:163], v[184:187], v[56:59]
	v_mfma_f32_16x16x32_bf16 v[44:47], v[144:147], v[192:195], v[44:47]
	v_mfma_f32_16x16x32_bf16 v[40:43], v[160:163], v[192:195], v[40:43]
	v_mfma_f32_16x16x32_bf16 v[28:31], v[144:147], v[200:203], v[28:31]
	v_mfma_f32_16x16x32_bf16 v[24:27], v[160:163], v[200:203], v[24:27]
	v_mfma_f32_16x16x32_bf16 v[12:15], v[144:147], v[212:215], v[12:15]
	v_mfma_f32_16x16x32_bf16 v[8:11], v[160:163], v[212:215], v[8:11]
	v_mfma_f32_16x16x32_bf16 v[52:55], v[164:167], v[180:183], v[52:55]
	v_mfma_f32_16x16x32_bf16 v[48:51], v[172:175], v[180:183], v[48:51]
	v_mfma_f32_16x16x32_bf16 v[36:39], v[164:167], v[188:191], v[36:39]
	v_mfma_f32_16x16x32_bf16 v[32:35], v[172:175], v[188:191], v[32:35]
	v_mfma_f32_16x16x32_bf16 v[20:23], v[164:167], v[196:199], v[20:23]
	v_mfma_f32_16x16x32_bf16 v[16:19], v[172:175], v[196:199], v[16:19]
	v_mfma_f32_16x16x32_bf16 v[4:7], v[164:167], v[208:211], v[4:7]
	v_mfma_f32_16x16x32_bf16 v[0:3], v[172:175], v[208:211], v[0:3]
	v_mfma_f32_16x16x32_bf16 v[52:55], v[168:171], v[184:187], v[52:55]
	v_mfma_f32_16x16x32_bf16 v[48:51], v[176:179], v[184:187], v[48:51]
	v_mfma_f32_16x16x32_bf16 v[36:39], v[168:171], v[192:195], v[36:39]
	v_mfma_f32_16x16x32_bf16 v[32:35], v[176:179], v[192:195], v[32:35]
	v_mfma_f32_16x16x32_bf16 v[20:23], v[168:171], v[200:203], v[20:23]
	v_mfma_f32_16x16x32_bf16 v[16:19], v[176:179], v[200:203], v[16:19]
	v_mfma_f32_16x16x32_bf16 v[4:7], v[168:171], v[212:215], v[4:7]
	v_mfma_f32_16x16x32_bf16 v[0:3], v[176:179], v[212:215], v[0:3]
	s_barrier
	s_add_i32 s61, s61, 2
	s_add_u32 s59, s59, 0x100
	s_addc_u32 s60, s60, 0
	s_add_u32 s36, s36, 0x100
	s_addc_u32 s37, s37, 0
	s_cmp_gt_u32 s61, 13
	s_cbranch_scc0 .LBB0_1561
	s_and_b64 vcc, exec, s[24:25]
	s_cbranch_vccz .LBB0_1564
	s_barrier

.LBB0_1646:
	ds_read_b128 v[144:147], v151
	ds_read_b128 v[156:159], v151 offset:1024
	ds_read_b128 v[160:163], v151 offset:2048
	ds_read_b128 v[164:167], v151 offset:3072
	ds_read_b128 v[168:171], v152
	ds_read_b128 v[172:175], v152 offset:1024
	ds_read_b128 v[176:179], v152 offset:2048
	ds_read_b128 v[180:183], v152 offset:3072
	s_add_u32 s26, s24, 0xfffc0080
	s_addc_u32 s27, s25, -1
	s_cmp_eq_u32 s54, 12
	s_cselect_b32 s29, s19, s27
	s_cselect_b32 s28, s50, s26
	s_cselect_b32 s27, s17, s53
	s_cselect_b32 s26, s51, s52
	s_add_i32 m0, s38, 0xc000
	ds_read_b128 v[184:187], v153
	ds_read_b128 v[188:191], v153 offset:1024
	ds_read_b128 v[192:195], v153 offset:2048
	ds_read_b128 v[196:199], v153 offset:3072
	ds_read_b128 v[200:203], v153 offset:4096
	ds_read_b128 v[208:211], v153 offset:5120
	ds_read_b128 v[212:215], v153 offset:6144
	ds_read_b128 v[216:219], v153 offset:7168
	global_load_lds_dwordx4 v138, s[24:25]
	s_add_i32 m0, s38, 0xe000
	s_nop 0
	global_load_lds_dwordx4 v136, s[24:25]
	s_waitcnt vmcnt(8)
	s_waitcnt lgkmcnt(0)
	s_barrier
	s_waitcnt lgkmcnt(0)
	s_nop 0
	v_mfma_f32_16x16x32_bf16 v[124:127], v[144:147], v[184:187], v[124:127]
	v_mfma_f32_16x16x32_bf16 v[120:123], v[160:163], v[184:187], v[120:123]
	v_mfma_f32_16x16x32_bf16 v[108:111], v[144:147], v[192:195], v[108:111]
	v_mfma_f32_16x16x32_bf16 v[104:107], v[160:163], v[192:195], v[104:107]
	v_mfma_f32_16x16x32_bf16 v[92:95], v[144:147], v[200:203], v[92:95]
	v_mfma_f32_16x16x32_bf16 v[88:91], v[160:163], v[200:203], v[88:91]
	v_mfma_f32_16x16x32_bf16 v[76:79], v[144:147], v[212:215], v[76:79]
	v_mfma_f32_16x16x32_bf16 v[72:75], v[160:163], v[212:215], v[72:75]
	v_mfma_f32_16x16x32_bf16 v[124:127], v[156:159], v[188:191], v[124:127]
	v_mfma_f32_16x16x32_bf16 v[120:123], v[164:167], v[188:191], v[120:123]
	v_mfma_f32_16x16x32_bf16 v[108:111], v[156:159], v[196:199], v[108:111]
	v_mfma_f32_16x16x32_bf16 v[104:107], v[164:167], v[196:199], v[104:107]
	v_mfma_f32_16x16x32_bf16 v[92:95], v[156:159], v[208:211], v[92:95]
	v_mfma_f32_16x16x32_bf16 v[88:91], v[164:167], v[208:211], v[88:91]
	v_mfma_f32_16x16x32_bf16 v[76:79], v[156:159], v[216:219], v[76:79]
	v_mfma_f32_16x16x32_bf16 v[72:75], v[164:167], v[216:219], v[72:75]
	v_mfma_f32_16x16x32_bf16 v[116:119], v[168:171], v[184:187], v[116:119]
	v_mfma_f32_16x16x32_bf16 v[112:115], v[176:179], v[184:187], v[112:115]
	v_mfma_f32_16x16x32_bf16 v[100:103], v[168:171], v[192:195], v[100:103]
	v_mfma_f32_16x16x32_bf16 v[96:99], v[176:179], v[192:195], v[96:99]
	v_mfma_f32_16x16x32_bf16 v[84:87], v[168:171], v[200:203], v[84:87]
	v_mfma_f32_16x16x32_bf16 v[80:83], v[176:179], v[200:203], v[80:83]
	v_mfma_f32_16x16x32_bf16 v[68:71], v[168:171], v[212:215], v[68:71]
	v_mfma_f32_16x16x32_bf16 v[64:67], v[176:179], v[212:215], v[64:67]
	v_mfma_f32_16x16x32_bf16 v[116:119], v[172:175], v[188:191], v[116:119]
	v_mfma_f32_16x16x32_bf16 v[112:115], v[180:183], v[188:191], v[112:115]
	v_mfma_f32_16x16x32_bf16 v[100:103], v[172:175], v[196:199], v[100:103]
	v_mfma_f32_16x16x32_bf16 v[96:99], v[180:183], v[196:199], v[96:99]
	v_mfma_f32_16x16x32_bf16 v[84:87], v[172:175], v[208:211], v[84:87]
	v_mfma_f32_16x16x32_bf16 v[80:83], v[180:183], v[208:211], v[80:83]
	v_mfma_f32_16x16x32_bf16 v[68:71], v[172:175], v[216:219], v[68:71]
	v_mfma_f32_16x16x32_bf16 v[64:67], v[180:183], v[216:219], v[64:67]
	s_barrier
	s_add_i32 s55, s47, s35
	s_mov_b32 m0, s55
	ds_read_b128 v[184:187], v153 offset:16384
	ds_read_b128 v[188:191], v153 offset:17408
	ds_read_b128 v[192:195], v153 offset:18432
	ds_read_b128 v[196:199], v153 offset:19456
	ds_read_b128 v[200:203], v153 offset:20480
	ds_read_b128 v[208:211], v153 offset:21504
	ds_read_b128 v[212:215], v153 offset:22528
	ds_read_b128 v[216:219], v153 offset:23552
	global_load_lds_dwordx4 v132, s[26:27]
	s_add_i32 m0, s55, 0x2000
	s_add_u32 s56, s26, 0x40000
	s_mov_b64 s[98:99], s[26:27]
	s_addc_u32 s57, s27, 0
	s_add_i32 s55, s48, s35
	global_load_lds_dwordx4 v128, s[26:27]
	s_mov_b32 m0, s55
	s_mov_b64 s[100:101], s[28:29]
	global_load_lds_dwordx4 v132, s[56:57]
	s_add_i32 m0, s55, 0x2000
	s_nop 0
	global_load_lds_dwordx4 v128, s[56:57]
	s_mov_b32 m0, s38
	s_nop 0
	global_load_lds_dwordx4 v134, s[28:29]
	s_mov_b32 m0, s39
	s_nop 0
	global_load_lds_dwordx4 v130, s[28:29]
	s_waitcnt vmcnt(8)
	s_waitcnt lgkmcnt(0)
	s_barrier
	s_waitcnt lgkmcnt(0)
	s_nop 0
	v_mfma_f32_16x16x32_bf16 v[60:63], v[144:147], v[184:187], v[60:63]
	v_mfma_f32_16x16x32_bf16 v[56:59], v[160:163], v[184:187], v[56:59]
	v_mfma_f32_16x16x32_bf16 v[44:47], v[144:147], v[192:195], v[44:47]
	v_mfma_f32_16x16x32_bf16 v[40:43], v[160:163], v[192:195], v[40:43]
	v_mfma_f32_16x16x32_bf16 v[28:31], v[144:147], v[200:203], v[28:31]
	v_mfma_f32_16x16x32_bf16 v[24:27], v[160:163], v[200:203], v[24:27]
	v_mfma_f32_16x16x32_bf16 v[12:15], v[144:147], v[212:215], v[12:15]
	v_mfma_f32_16x16x32_bf16 v[8:11], v[160:163], v[212:215], v[8:11]
	v_mfma_f32_16x16x32_bf16 v[60:63], v[156:159], v[188:191], v[60:63]
	v_mfma_f32_16x16x32_bf16 v[56:59], v[164:167], v[188:191], v[56:59]
	v_mfma_f32_16x16x32_bf16 v[44:47], v[156:159], v[196:199], v[44:47]
	v_mfma_f32_16x16x32_bf16 v[40:43], v[164:167], v[196:199], v[40:43]
	v_mfma_f32_16x16x32_bf16 v[28:31], v[156:159], v[208:211], v[28:31]
	v_mfma_f32_16x16x32_bf16 v[24:27], v[164:167], v[208:211], v[24:27]
	v_mfma_f32_16x16x32_bf16 v[12:15], v[156:159], v[216:219], v[12:15]
	v_mfma_f32_16x16x32_bf16 v[8:11], v[164:167], v[216:219], v[8:11]
	v_mfma_f32_16x16x32_bf16 v[52:55], v[168:171], v[184:187], v[52:55]
	v_mfma_f32_16x16x32_bf16 v[48:51], v[176:179], v[184:187], v[48:51]
	v_mfma_f32_16x16x32_bf16 v[36:39], v[168:171], v[192:195], v[36:39]
	v_mfma_f32_16x16x32_bf16 v[32:35], v[176:179], v[192:195], v[32:35]
	v_mfma_f32_16x16x32_bf16 v[20:23], v[168:171], v[200:203], v[20:23]
	v_mfma_f32_16x16x32_bf16 v[16:19], v[176:179], v[200:203], v[16:19]
	v_mfma_f32_16x16x32_bf16 v[4:7], v[168:171], v[212:215], v[4:7]
	v_mfma_f32_16x16x32_bf16 v[0:3], v[176:179], v[212:215], v[0:3]
	v_mfma_f32_16x16x32_bf16 v[52:55], v[172:175], v[188:191], v[52:55]
	v_mfma_f32_16x16x32_bf16 v[48:51], v[180:183], v[188:191], v[48:51]
	v_mfma_f32_16x16x32_bf16 v[36:39], v[172:175], v[196:199], v[36:39]
	v_mfma_f32_16x16x32_bf16 v[32:35], v[180:183], v[196:199], v[32:35]
	v_mfma_f32_16x16x32_bf16 v[20:23], v[172:175], v[208:211], v[20:23]
	v_mfma_f32_16x16x32_bf16 v[16:19], v[180:183], v[208:211], v[16:19]
	v_mfma_f32_16x16x32_bf16 v[4:7], v[172:175], v[216:219], v[4:7]
	v_mfma_f32_16x16x32_bf16 v[0:3], v[180:183], v[216:219], v[0:3]
	s_barrier
	s_add_i32 s55, 0, 0x18000
	s_add_i32 s56, 0, 0x1c000
	v_add_u32_e32 v164, s55, v149
	v_add_u32_e32 v180, s56, v149
	ds_read_b128 v[144:147], v164
	ds_read_b128 v[156:159], v164 offset:1024
	ds_read_b128 v[160:163], v164 offset:2048
	ds_read_b128 v[164:167], v164 offset:3072
	ds_read_b128 v[168:171], v180
	ds_read_b128 v[172:175], v180 offset:1024
	ds_read_b128 v[176:179], v180 offset:2048
	ds_read_b128 v[180:183], v180 offset:3072
	s_add_u32 s28, s28, 0x40000
	s_addc_u32 s29, s29, 0
	s_mov_b32 m0, s40
	ds_read_b128 v[184:187], v153 offset:32768
	ds_read_b128 v[188:191], v153 offset:33792
	ds_read_b128 v[192:195], v153 offset:34816
	ds_read_b128 v[196:199], v153 offset:35840
	ds_read_b128 v[200:203], v153 offset:36864
	ds_read_b128 v[208:211], v153 offset:37888
	ds_read_b128 v[212:215], v153 offset:38912
	ds_read_b128 v[216:219], v153 offset:39936
	global_load_lds_dwordx4 v134, s[28:29]
	s_mov_b32 m0, s41
	s_nop 0
	global_load_lds_dwordx4 v130, s[28:29]
	s_waitcnt vmcnt(8)
	s_waitcnt lgkmcnt(0)
	s_barrier
	s_waitcnt lgkmcnt(0)
	s_nop 0
	v_mfma_f32_16x16x32_bf16 v[124:127], v[144:147], v[184:187], v[124:127]
	v_mfma_f32_16x16x32_bf16 v[120:123], v[160:163], v[184:187], v[120:123]
	v_mfma_f32_16x16x32_bf16 v[108:111], v[144:147], v[192:195], v[108:111]
	v_mfma_f32_16x16x32_bf16 v[104:107], v[160:163], v[192:195], v[104:107]
	v_mfma_f32_16x16x32_bf16 v[92:95], v[144:147], v[200:203], v[92:95]
	v_mfma_f32_16x16x32_bf16 v[88:91], v[160:163], v[200:203], v[88:91]
	v_mfma_f32_16x16x32_bf16 v[76:79], v[144:147], v[212:215], v[76:79]
	v_mfma_f32_16x16x32_bf16 v[72:75], v[160:163], v[212:215], v[72:75]
	v_mfma_f32_16x16x32_bf16 v[124:127], v[156:159], v[188:191], v[124:127]
	v_mfma_f32_16x16x32_bf16 v[120:123], v[164:167], v[188:191], v[120:123]
	v_mfma_f32_16x16x32_bf16 v[108:111], v[156:159], v[196:199], v[108:111]
	v_mfma_f32_16x16x32_bf16 v[104:107], v[164:167], v[196:199], v[104:107]
	v_mfma_f32_16x16x32_bf16 v[92:95], v[156:159], v[208:211], v[92:95]
	v_mfma_f32_16x16x32_bf16 v[88:91], v[164:167], v[208:211], v[88:91]
	v_mfma_f32_16x16x32_bf16 v[76:79], v[156:159], v[216:219], v[76:79]
	v_mfma_f32_16x16x32_bf16 v[72:75], v[164:167], v[216:219], v[72:75]
	v_mfma_f32_16x16x32_bf16 v[116:119], v[168:171], v[184:187], v[116:119]
	v_mfma_f32_16x16x32_bf16 v[112:115], v[176:179], v[184:187], v[112:115]
	v_mfma_f32_16x16x32_bf16 v[100:103], v[168:171], v[192:195], v[100:103]
	v_mfma_f32_16x16x32_bf16 v[96:99], v[176:179], v[192:195], v[96:99]
	v_mfma_f32_16x16x32_bf16 v[84:87], v[168:171], v[200:203], v[84:87]
	v_mfma_f32_16x16x32_bf16 v[80:83], v[176:179], v[200:203], v[80:83]
	v_mfma_f32_16x16x32_bf16 v[68:71], v[168:171], v[212:215], v[68:71]
	v_mfma_f32_16x16x32_bf16 v[64:67], v[176:179], v[212:215], v[64:67]
	v_mfma_f32_16x16x32_bf16 v[116:119], v[172:175], v[188:191], v[116:119]
	v_mfma_f32_16x16x32_bf16 v[112:115], v[180:183], v[188:191], v[112:115]
	v_mfma_f32_16x16x32_bf16 v[100:103], v[172:175], v[196:199], v[100:103]
	v_mfma_f32_16x16x32_bf16 v[96:99], v[180:183], v[196:199], v[96:99]
	v_mfma_f32_16x16x32_bf16 v[84:87], v[172:175], v[208:211], v[84:87]
	v_mfma_f32_16x16x32_bf16 v[80:83], v[180:183], v[208:211], v[80:83]
	v_mfma_f32_16x16x32_bf16 v[68:71], v[172:175], v[216:219], v[68:71]
	v_mfma_f32_16x16x32_bf16 v[64:67], v[180:183], v[216:219], v[64:67]
	s_barrier
	s_add_i32 s28, s55, s35
	s_mov_b32 m0, s28
	ds_read_b128 v[184:187], v153 offset:49152
	ds_read_b128 v[188:191], v153 offset:50176
	ds_read_b128 v[192:195], v153 offset:51200
	ds_read_b128 v[196:199], v153 offset:52224
	ds_read_b128 v[200:203], v153 offset:53248
	ds_read_b128 v[208:211], v153 offset:54272
	ds_read_b128 v[212:215], v153 offset:55296
	ds_read_b128 v[216:219], v153 offset:56320
	global_load_lds_dwordx4 v220, s[26:27]
	s_add_i32 m0, s28, 0x2000
	s_add_u32 s26, s26, 0x40080
	s_addc_u32 s27, s27, 0
	s_add_i32 s28, s56, s35
	global_load_lds_dwordx4 v204, s[98:99]
	s_mov_b32 m0, s28
	s_nop 0
	global_load_lds_dwordx4 v132, s[26:27]
	s_add_i32 m0, s28, 0x2000
	s_nop 0
	global_load_lds_dwordx4 v128, s[26:27]
	s_mov_b32 m0, s45
	s_nop 0
	global_load_lds_dwordx4 v221, s[100:101]
	s_mov_b32 m0, s46
	s_nop 0
	global_load_lds_dwordx4 v205, s[100:101]
	s_waitcnt vmcnt(8)
	s_waitcnt lgkmcnt(0)
	s_barrier
	s_waitcnt lgkmcnt(0)
	v_mfma_f32_16x16x32_bf16 v[60:63], v[144:147], v[184:187], v[60:63]
	v_mfma_f32_16x16x32_bf16 v[56:59], v[160:163], v[184:187], v[56:59]
	v_mfma_f32_16x16x32_bf16 v[44:47], v[144:147], v[192:195], v[44:47]
	v_mfma_f32_16x16x32_bf16 v[40:43], v[160:163], v[192:195], v[40:43]
	v_mfma_f32_16x16x32_bf16 v[28:31], v[144:147], v[200:203], v[28:31]
	v_mfma_f32_16x16x32_bf16 v[24:27], v[160:163], v[200:203], v[24:27]
	v_mfma_f32_16x16x32_bf16 v[12:15], v[144:147], v[212:215], v[12:15]
	v_mfma_f32_16x16x32_bf16 v[8:11], v[160:163], v[212:215], v[8:11]
	v_mfma_f32_16x16x32_bf16 v[60:63], v[156:159], v[188:191], v[60:63]
	v_mfma_f32_16x16x32_bf16 v[56:59], v[164:167], v[188:191], v[56:59]
	v_mfma_f32_16x16x32_bf16 v[44:47], v[156:159], v[196:199], v[44:47]
	v_mfma_f32_16x16x32_bf16 v[40:43], v[164:167], v[196:199], v[40:43]
	v_mfma_f32_16x16x32_bf16 v[28:31], v[156:159], v[208:211], v[28:31]
	v_mfma_f32_16x16x32_bf16 v[24:27], v[164:167], v[208:211], v[24:27]
	v_mfma_f32_16x16x32_bf16 v[12:15], v[156:159], v[216:219], v[12:15]
	v_mfma_f32_16x16x32_bf16 v[8:11], v[164:167], v[216:219], v[8:11]
	v_mfma_f32_16x16x32_bf16 v[52:55], v[168:171], v[184:187], v[52:55]
	v_mfma_f32_16x16x32_bf16 v[48:51], v[176:179], v[184:187], v[48:51]
	v_mfma_f32_16x16x32_bf16 v[36:39], v[168:171], v[192:195], v[36:39]
	v_mfma_f32_16x16x32_bf16 v[32:35], v[176:179], v[192:195], v[32:35]
	v_mfma_f32_16x16x32_bf16 v[20:23], v[168:171], v[200:203], v[20:23]
	v_mfma_f32_16x16x32_bf16 v[16:19], v[176:179], v[200:203], v[16:19]
	v_mfma_f32_16x16x32_bf16 v[4:7], v[168:171], v[212:215], v[4:7]
	v_mfma_f32_16x16x32_bf16 v[0:3], v[176:179], v[212:215], v[0:3]
	v_mfma_f32_16x16x32_bf16 v[52:55], v[172:175], v[188:191], v[52:55]
	v_mfma_f32_16x16x32_bf16 v[48:51], v[180:183], v[188:191], v[48:51]
	v_mfma_f32_16x16x32_bf16 v[36:39], v[172:175], v[196:199], v[36:39]
	v_mfma_f32_16x16x32_bf16 v[32:35], v[180:183], v[196:199], v[32:35]
	v_mfma_f32_16x16x32_bf16 v[20:23], v[172:175], v[208:211], v[20:23]
	v_mfma_f32_16x16x32_bf16 v[16:19], v[180:183], v[208:211], v[16:19]
	v_mfma_f32_16x16x32_bf16 v[4:7], v[172:175], v[216:219], v[4:7]
	v_mfma_f32_16x16x32_bf16 v[0:3], v[180:183], v[216:219], v[0:3]
	s_barrier
	s_add_i32 s54, s54, 2
	s_add_u32 s52, s52, 0x100
	s_addc_u32 s53, s53, 0
	s_add_u32 s24, s24, 0x100
	s_addc_u32 s25, s25, 0
	s_cmp_gt_u32 s54, 13
	s_cbranch_scc0 .LBB0_1646
	s_and_b64 vcc, exec, s[14:15]
	s_cbranch_vccz .LBB0_1649
	s_barrier

.LBB0_2583:
	s_cmpk_eq_i32 s2, 0xffc0
	s_cbranch_scc1 .LBB0_2586
	s_andn2_b64 vcc, exec, s[24:25]
	s_cbranch_vccnz .LBB0_2586
	s_and_b32 s38, s2, 64
	s_mulk_i32 s38, 0x110
	v_add_u32_e32 v66, s38, v125
	ds_read_b128 v[8:11], v66
	ds_read_b128 v[12:15], v66 offset:64
	ds_read_b128 v[148:151], v66 offset:128
	ds_read_b128 v[152:155], v66 offset:192
	v_lshlrev_b32_e32 v66, 16, v143
	s_waitcnt lgkmcnt(3)
	v_mfma_f32_16x16x32_bf16 v[8:11], v[8:11], v[48:51], 0
	v_and_b32_e32 v143, 0xffff0000, v143
	v_lshlrev_b32_e32 v147, 16, v107
	v_lshl_add_u64 v[156:157], v[116:117], 0, s[2:3]
	s_waitcnt lgkmcnt(2)
	v_mfma_f32_16x16x32_bf16 v[8:11], v[12:15], v[44:47], v[8:11]
	v_lshlrev_b64 v[12:13], 10, v[156:157]
	v_lshl_add_u64 v[14:15], v[110:111], 0, v[12:13]
	s_waitcnt lgkmcnt(1)
	s_nop 0
	v_mfma_f32_16x16x32_bf16 v[8:11], v[148:151], v[40:43], v[8:11]
	v_or_b32_e32 v148, 0x400, v12
	v_mov_b32_e32 v149, v13
	s_waitcnt lgkmcnt(0)
	v_mfma_f32_16x16x32_bf16 v[8:11], v[152:155], v[36:39], v[8:11]
	s_nop 7
	v_fma_f32 v8, v142, v66, v8
	v_mul_f32_e32 v66, 0x3d372713, v8
	v_fma_f32 v9, v142, v143, v9
	v_mul_f32_e32 v66, v8, v66
	v_mul_f32_e32 v143, 0x3d372713, v9
	v_fma_f32 v66, v8, v66, v8
	v_mul_f32_e32 v143, v9, v143
	v_mul_f32_e32 v66, 0xbfcc422a, v66
	v_fma_f32 v143, v9, v143, v9
	v_mul_f32_e32 v66, 0x3fb8aa3b, v66
	v_mul_f32_e32 v143, 0xbfcc422a, v143
	v_exp_f32_e32 v66, v66
	v_mul_f32_e32 v143, 0x3fb8aa3b, v143
	v_exp_f32_e32 v143, v143
	v_fma_f32 v10, v142, v147, v10
	v_add_f32_e32 v66, 1.0, v66
	v_rcp_f32_e32 v66, v66
	v_add_f32_e32 v143, 1.0, v143
	v_mul_f32_e32 v147, 0x3d372713, v10
	v_rcp_f32_e32 v143, v143
	v_mul_f32_e32 v147, v10, v147
	v_fma_f32 v147, v10, v147, v10
	v_mul_f32_e32 v8, v8, v66
	v_mul_f32_e32 v147, 0xbfcc422a, v147
	v_cvt_pk_bf16_f32 v8, v8, s0
	v_mul_f32_e32 v9, v9, v143
	global_store_short v[14:15], v8, off
	v_mul_f32_e32 v8, 0x3fb8aa3b, v147
	v_cvt_pk_bf16_f32 v66, v9, s0
	v_exp_f32_e32 v14, v8
	v_lshl_add_u64 v[8:9], v[110:111], 0, v[148:149]
	global_store_short v[8:9], v66, off
	v_and_b32_e32 v9, 0xffff0000, v107
	v_fmac_f32_e32 v11, v142, v9
	v_mul_f32_e32 v9, 0x3d372713, v11
	v_mul_f32_e32 v9, v11, v9
	v_fma_f32 v9, v11, v9, v11
	v_mul_f32_e32 v9, 0xbfcc422a, v9
	v_mul_f32_e32 v9, 0x3fb8aa3b, v9
	v_exp_f32_e32 v9, v9
	v_add_f32_e32 v8, 1.0, v14
	v_rcp_f32_e32 v8, v8
	v_add_f32_e32 v9, 1.0, v9
	v_rcp_f32_e32 v14, v9
	v_mul_f32_e32 v8, v10, v8
	v_cvt_pk_bf16_f32 v10, v8, s0
	v_or_b32_e32 v8, 0x800, v12
	v_mov_b32_e32 v9, v13
	v_lshl_add_u64 v[8:9], v[110:111], 0, v[8:9]
	global_store_short v[8:9], v10, off
	v_mul_f32_e32 v8, v11, v14
	v_or_b32_e32 v12, 0xc00, v12
	v_cvt_pk_bf16_f32 v10, v8, s0
	v_lshl_add_u64 v[8:9], v[110:111], 0, v[12:13]
	global_store_short v[8:9], v10, off
	v_lshl_add_u64 v[8:9], v[120:121], 0, s[30:31]
	v_or_b32_e32 v12, 0x1000, v8
	v_mov_b32_e32 v13, v9
	v_or_b32_e32 v14, 0x2000, v8
	v_or_b32_e32 v8, 0x3000, v8
	v_lshl_add_u64 v[10:11], v[112:113], 0, v[120:121]
	v_lshl_add_u64 v[12:13], v[118:119], 0, v[12:13]
	v_mov_b32_e32 v15, v9
	v_lshl_add_u64 v[8:9], v[118:119], 0, v[8:9]
	v_lshl_add_u64 v[14:15], v[118:119], 0, v[14:15]
	global_load_ushort v10, v[10:11], off
	s_nop 0
	global_load_ushort v11, v[12:13], off
	s_nop 0
	global_load_ushort v12, v[14:15], off
	s_nop 0
	global_load_ushort v8, v[8:9], off
	s_mov_b32 s100, 1

.LBB0_2673:
	ds_read_b128 v[144:147], v151
	ds_read_b128 v[154:157], v151 offset:1024
	ds_read_b128 v[158:161], v151 offset:2048
	ds_read_b128 v[162:165], v151 offset:3072
	ds_read_b128 v[166:169], v152
	ds_read_b128 v[170:173], v152 offset:1024
	ds_read_b128 v[174:177], v152 offset:2048
	ds_read_b128 v[178:181], v152 offset:3072
	s_add_u32 s26, s24, 0xfffe0080
	s_addc_u32 s27, s25, -1
	s_cmp_eq_u32 s50, 4
	s_cselect_b32 s29, s17, s27
	s_cselect_b32 s28, s46, s26
	s_cselect_b32 s27, s15, s49
	s_cselect_b32 s26, s47, s48
	s_add_i32 m0, s23, 0xc000
	ds_read_b128 v[182:185], v153
	ds_read_b128 v[186:189], v153 offset:1024
	ds_read_b128 v[190:193], v153 offset:2048
	ds_read_b128 v[194:197], v153 offset:3072
	ds_read_b128 v[198:201], v153 offset:4096
	ds_read_b128 v[202:205], v153 offset:5120
	ds_read_b128 v[208:211], v153 offset:6144
	ds_read_b128 v[212:215], v153 offset:7168
	global_load_lds_dwordx4 v138, s[24:25]
	s_add_i32 m0, s23, 0xe000
	s_nop 0
	global_load_lds_dwordx4 v136, s[24:25]
	s_waitcnt vmcnt(8)
	s_waitcnt lgkmcnt(0)
	s_barrier
	s_waitcnt lgkmcnt(0)
	v_mfma_f32_16x16x32_bf16 v[124:127], v[144:147], v[182:185], v[124:127]
	v_mfma_f32_16x16x32_bf16 v[120:123], v[158:161], v[182:185], v[120:123]
	v_mfma_f32_16x16x32_bf16 v[108:111], v[144:147], v[190:193], v[108:111]
	v_mfma_f32_16x16x32_bf16 v[104:107], v[158:161], v[190:193], v[104:107]
	v_mfma_f32_16x16x32_bf16 v[92:95], v[144:147], v[198:201], v[92:95]
	v_mfma_f32_16x16x32_bf16 v[88:91], v[158:161], v[198:201], v[88:91]
	v_mfma_f32_16x16x32_bf16 v[76:79], v[144:147], v[208:211], v[76:79]
	v_mfma_f32_16x16x32_bf16 v[72:75], v[158:161], v[208:211], v[72:75]
	v_mfma_f32_16x16x32_bf16 v[124:127], v[154:157], v[186:189], v[124:127]
	v_mfma_f32_16x16x32_bf16 v[120:123], v[162:165], v[186:189], v[120:123]
	v_mfma_f32_16x16x32_bf16 v[108:111], v[154:157], v[194:197], v[108:111]
	v_mfma_f32_16x16x32_bf16 v[104:107], v[162:165], v[194:197], v[104:107]
	v_mfma_f32_16x16x32_bf16 v[92:95], v[154:157], v[202:205], v[92:95]
	v_mfma_f32_16x16x32_bf16 v[88:91], v[162:165], v[202:205], v[88:91]
	v_mfma_f32_16x16x32_bf16 v[76:79], v[154:157], v[212:215], v[76:79]
	v_mfma_f32_16x16x32_bf16 v[72:75], v[162:165], v[212:215], v[72:75]
	v_mfma_f32_16x16x32_bf16 v[116:119], v[166:169], v[182:185], v[116:119]
	v_mfma_f32_16x16x32_bf16 v[112:115], v[174:177], v[182:185], v[112:115]
	v_mfma_f32_16x16x32_bf16 v[100:103], v[166:169], v[190:193], v[100:103]
	v_mfma_f32_16x16x32_bf16 v[96:99], v[174:177], v[190:193], v[96:99]
	v_mfma_f32_16x16x32_bf16 v[84:87], v[166:169], v[198:201], v[84:87]
	v_mfma_f32_16x16x32_bf16 v[80:83], v[174:177], v[198:201], v[80:83]
	v_mfma_f32_16x16x32_bf16 v[68:71], v[166:169], v[208:211], v[68:71]
	v_mfma_f32_16x16x32_bf16 v[64:67], v[174:177], v[208:211], v[64:67]
	v_mfma_f32_16x16x32_bf16 v[116:119], v[170:173], v[186:189], v[116:119]
	v_mfma_f32_16x16x32_bf16 v[112:115], v[178:181], v[186:189], v[112:115]
	v_mfma_f32_16x16x32_bf16 v[100:103], v[170:173], v[194:197], v[100:103]
	v_mfma_f32_16x16x32_bf16 v[96:99], v[178:181], v[194:197], v[96:99]
	v_mfma_f32_16x16x32_bf16 v[84:87], v[170:173], v[202:205], v[84:87]
	v_mfma_f32_16x16x32_bf16 v[80:83], v[178:181], v[202:205], v[80:83]
	v_mfma_f32_16x16x32_bf16 v[68:71], v[170:173], v[212:215], v[68:71]
	v_mfma_f32_16x16x32_bf16 v[64:67], v[178:181], v[212:215], v[64:67]
	s_barrier
	s_add_i32 s51, s43, s36
	s_mov_b32 m0, s51
	ds_read_b128 v[182:185], v153 offset:16384
	ds_read_b128 v[186:189], v153 offset:17408
	ds_read_b128 v[190:193], v153 offset:18432
	ds_read_b128 v[194:197], v153 offset:19456
	ds_read_b128 v[198:201], v153 offset:20480
	ds_read_b128 v[202:205], v153 offset:21504
	ds_read_b128 v[208:211], v153 offset:22528
	ds_read_b128 v[212:215], v153 offset:23552
	global_load_lds_dwordx4 v130, s[26:27]
	s_add_i32 m0, s51, 0x2000
	s_add_u32 s52, s26, 0x20000
	s_mov_b64 s[98:99], s[26:27]
	s_addc_u32 s53, s27, 0
	s_add_i32 s51, s44, s36
	global_load_lds_dwordx4 v134, s[26:27]
	s_mov_b32 m0, s51
	s_mov_b64 s[100:101], s[28:29]
	global_load_lds_dwordx4 v130, s[52:53]
	s_add_i32 m0, s51, 0x2000
	s_nop 0
	global_load_lds_dwordx4 v134, s[52:53]
	s_mov_b32 m0, s23
	s_nop 0
	global_load_lds_dwordx4 v128, s[28:29]
	s_mov_b32 m0, s37
	s_nop 0
	global_load_lds_dwordx4 v132, s[28:29]
	s_waitcnt vmcnt(8)
	s_waitcnt lgkmcnt(0)
	s_barrier
	s_waitcnt lgkmcnt(0)
	s_nop 0
	v_mfma_f32_16x16x32_bf16 v[60:63], v[144:147], v[182:185], v[60:63]
	v_mfma_f32_16x16x32_bf16 v[56:59], v[158:161], v[182:185], v[56:59]
	v_mfma_f32_16x16x32_bf16 v[44:47], v[144:147], v[190:193], v[44:47]
	v_mfma_f32_16x16x32_bf16 v[40:43], v[158:161], v[190:193], v[40:43]
	v_mfma_f32_16x16x32_bf16 v[28:31], v[144:147], v[198:201], v[28:31]
	v_mfma_f32_16x16x32_bf16 v[24:27], v[158:161], v[198:201], v[24:27]
	v_mfma_f32_16x16x32_bf16 v[12:15], v[144:147], v[208:211], v[12:15]
	v_mfma_f32_16x16x32_bf16 v[8:11], v[158:161], v[208:211], v[8:11]
	v_mfma_f32_16x16x32_bf16 v[60:63], v[154:157], v[186:189], v[60:63]
	v_mfma_f32_16x16x32_bf16 v[56:59], v[162:165], v[186:189], v[56:59]
	v_mfma_f32_16x16x32_bf16 v[44:47], v[154:157], v[194:197], v[44:47]
	v_mfma_f32_16x16x32_bf16 v[40:43], v[162:165], v[194:197], v[40:43]
	v_mfma_f32_16x16x32_bf16 v[28:31], v[154:157], v[202:205], v[28:31]
	v_mfma_f32_16x16x32_bf16 v[24:27], v[162:165], v[202:205], v[24:27]
	v_mfma_f32_16x16x32_bf16 v[12:15], v[154:157], v[212:215], v[12:15]
	v_mfma_f32_16x16x32_bf16 v[8:11], v[162:165], v[212:215], v[8:11]
	v_mfma_f32_16x16x32_bf16 v[52:55], v[166:169], v[182:185], v[52:55]
	v_mfma_f32_16x16x32_bf16 v[48:51], v[174:177], v[182:185], v[48:51]
	v_mfma_f32_16x16x32_bf16 v[36:39], v[166:169], v[190:193], v[36:39]
	v_mfma_f32_16x16x32_bf16 v[32:35], v[174:177], v[190:193], v[32:35]
	v_mfma_f32_16x16x32_bf16 v[20:23], v[166:169], v[198:201], v[20:23]
	v_mfma_f32_16x16x32_bf16 v[16:19], v[174:177], v[198:201], v[16:19]
	v_mfma_f32_16x16x32_bf16 v[4:7], v[166:169], v[208:211], v[4:7]
	v_mfma_f32_16x16x32_bf16 v[0:3], v[174:177], v[208:211], v[0:3]
	v_mfma_f32_16x16x32_bf16 v[52:55], v[170:173], v[186:189], v[52:55]
	v_mfma_f32_16x16x32_bf16 v[48:51], v[178:181], v[186:189], v[48:51]
	v_mfma_f32_16x16x32_bf16 v[36:39], v[170:173], v[194:197], v[36:39]
	v_mfma_f32_16x16x32_bf16 v[32:35], v[178:181], v[194:197], v[32:35]
	v_mfma_f32_16x16x32_bf16 v[20:23], v[170:173], v[202:205], v[20:23]
	v_mfma_f32_16x16x32_bf16 v[16:19], v[178:181], v[202:205], v[16:19]
	v_mfma_f32_16x16x32_bf16 v[4:7], v[170:173], v[212:215], v[4:7]
	v_mfma_f32_16x16x32_bf16 v[0:3], v[178:181], v[212:215], v[0:3]
	s_barrier
	s_add_i32 s51, 0, 0x18000
	s_add_i32 s52, 0, 0x1c000
	v_add_u32_e32 v162, s51, v149
	v_add_u32_e32 v178, s52, v149
	ds_read_b128 v[144:147], v162
	ds_read_b128 v[154:157], v162 offset:1024
	ds_read_b128 v[158:161], v162 offset:2048
	ds_read_b128 v[162:165], v162 offset:3072
	ds_read_b128 v[166:169], v178
	ds_read_b128 v[170:173], v178 offset:1024
	ds_read_b128 v[174:177], v178 offset:2048
	ds_read_b128 v[178:181], v178 offset:3072
	s_add_u32 s28, s28, 0x20000
	s_addc_u32 s29, s29, 0
	s_mov_b32 m0, s38
	ds_read_b128 v[182:185], v153 offset:32768
	ds_read_b128 v[186:189], v153 offset:33792
	ds_read_b128 v[190:193], v153 offset:34816
	ds_read_b128 v[194:197], v153 offset:35840
	ds_read_b128 v[198:201], v153 offset:36864
	ds_read_b128 v[202:205], v153 offset:37888
	ds_read_b128 v[208:211], v153 offset:38912
	ds_read_b128 v[212:215], v153 offset:39936
	global_load_lds_dwordx4 v128, s[28:29]
	s_mov_b32 m0, s39
	s_nop 0
	global_load_lds_dwordx4 v132, s[28:29]
	s_waitcnt vmcnt(8)
	s_waitcnt lgkmcnt(0)
	s_barrier
	s_waitcnt lgkmcnt(0)
	s_nop 0
	v_mfma_f32_16x16x32_bf16 v[124:127], v[144:147], v[182:185], v[124:127]
	v_mfma_f32_16x16x32_bf16 v[120:123], v[158:161], v[182:185], v[120:123]
	v_mfma_f32_16x16x32_bf16 v[108:111], v[144:147], v[190:193], v[108:111]
	v_mfma_f32_16x16x32_bf16 v[104:107], v[158:161], v[190:193], v[104:107]
	v_mfma_f32_16x16x32_bf16 v[92:95], v[144:147], v[198:201], v[92:95]
	v_mfma_f32_16x16x32_bf16 v[88:91], v[158:161], v[198:201], v[88:91]
	v_mfma_f32_16x16x32_bf16 v[76:79], v[144:147], v[208:211], v[76:79]
	v_mfma_f32_16x16x32_bf16 v[72:75], v[158:161], v[208:211], v[72:75]
	v_mfma_f32_16x16x32_bf16 v[124:127], v[154:157], v[186:189], v[124:127]
	v_mfma_f32_16x16x32_bf16 v[120:123], v[162:165], v[186:189], v[120:123]
	v_mfma_f32_16x16x32_bf16 v[108:111], v[154:157], v[194:197], v[108:111]
	v_mfma_f32_16x16x32_bf16 v[104:107], v[162:165], v[194:197], v[104:107]
	v_mfma_f32_16x16x32_bf16 v[92:95], v[154:157], v[202:205], v[92:95]
	v_mfma_f32_16x16x32_bf16 v[88:91], v[162:165], v[202:205], v[88:91]
	v_mfma_f32_16x16x32_bf16 v[76:79], v[154:157], v[212:215], v[76:79]
	v_mfma_f32_16x16x32_bf16 v[72:75], v[162:165], v[212:215], v[72:75]
	v_mfma_f32_16x16x32_bf16 v[116:119], v[166:169], v[182:185], v[116:119]
	v_mfma_f32_16x16x32_bf16 v[112:115], v[174:177], v[182:185], v[112:115]
	v_mfma_f32_16x16x32_bf16 v[100:103], v[166:169], v[190:193], v[100:103]
	v_mfma_f32_16x16x32_bf16 v[96:99], v[174:177], v[190:193], v[96:99]
	v_mfma_f32_16x16x32_bf16 v[84:87], v[166:169], v[198:201], v[84:87]
	v_mfma_f32_16x16x32_bf16 v[80:83], v[174:177], v[198:201], v[80:83]
	v_mfma_f32_16x16x32_bf16 v[68:71], v[166:169], v[208:211], v[68:71]
	v_mfma_f32_16x16x32_bf16 v[64:67], v[174:177], v[208:211], v[64:67]
	v_mfma_f32_16x16x32_bf16 v[116:119], v[170:173], v[186:189], v[116:119]
	v_mfma_f32_16x16x32_bf16 v[112:115], v[178:181], v[186:189], v[112:115]
	v_mfma_f32_16x16x32_bf16 v[100:103], v[170:173], v[194:197], v[100:103]
	v_mfma_f32_16x16x32_bf16 v[96:99], v[178:181], v[194:197], v[96:99]
	v_mfma_f32_16x16x32_bf16 v[84:87], v[170:173], v[202:205], v[84:87]
	v_mfma_f32_16x16x32_bf16 v[80:83], v[178:181], v[202:205], v[80:83]
	v_mfma_f32_16x16x32_bf16 v[68:71], v[170:173], v[212:215], v[68:71]
	v_mfma_f32_16x16x32_bf16 v[64:67], v[178:181], v[212:215], v[64:67]
	s_barrier
	s_add_i32 s28, s51, s36
	s_mov_b32 m0, s28
	ds_read_b128 v[182:185], v153 offset:49152
	ds_read_b128 v[186:189], v153 offset:50176
	ds_read_b128 v[190:193], v153 offset:51200
	ds_read_b128 v[194:197], v153 offset:52224
	ds_read_b128 v[198:201], v153 offset:53248
	ds_read_b128 v[202:205], v153 offset:54272
	ds_read_b128 v[208:211], v153 offset:55296
	ds_read_b128 v[212:215], v153 offset:56320
	global_load_lds_dwordx4 v217, s[26:27]
	s_add_i32 m0, s28, 0x2000
	s_add_u32 s26, s26, 0x20080
	s_addc_u32 s27, s27, 0
	s_add_i32 s28, s52, s36
	global_load_lds_dwordx4 v219, s[98:99]
	s_mov_b32 m0, s28
	s_nop 0
	global_load_lds_dwordx4 v130, s[26:27]
	s_add_i32 m0, s28, 0x2000
	s_nop 0
	global_load_lds_dwordx4 v134, s[26:27]
	s_mov_b32 m0, s41
	s_nop 0
	global_load_lds_dwordx4 v216, s[100:101]
	s_mov_b32 m0, s42
	s_nop 0
	global_load_lds_dwordx4 v218, s[100:101]
	s_waitcnt vmcnt(8)
	s_waitcnt lgkmcnt(0)
	s_barrier
	s_waitcnt lgkmcnt(0)
	v_mfma_f32_16x16x32_bf16 v[60:63], v[144:147], v[182:185], v[60:63]
	v_mfma_f32_16x16x32_bf16 v[56:59], v[158:161], v[182:185], v[56:59]
	v_mfma_f32_16x16x32_bf16 v[44:47], v[144:147], v[190:193], v[44:47]
	v_mfma_f32_16x16x32_bf16 v[40:43], v[158:161], v[190:193], v[40:43]
	v_mfma_f32_16x16x32_bf16 v[28:31], v[144:147], v[198:201], v[28:31]
	v_mfma_f32_16x16x32_bf16 v[24:27], v[158:161], v[198:201], v[24:27]
	v_mfma_f32_16x16x32_bf16 v[12:15], v[144:147], v[208:211], v[12:15]
	v_mfma_f32_16x16x32_bf16 v[8:11], v[158:161], v[208:211], v[8:11]
	v_mfma_f32_16x16x32_bf16 v[60:63], v[154:157], v[186:189], v[60:63]
	v_mfma_f32_16x16x32_bf16 v[56:59], v[162:165], v[186:189], v[56:59]
	v_mfma_f32_16x16x32_bf16 v[44:47], v[154:157], v[194:197], v[44:47]
	v_mfma_f32_16x16x32_bf16 v[40:43], v[162:165], v[194:197], v[40:43]
	v_mfma_f32_16x16x32_bf16 v[28:31], v[154:157], v[202:205], v[28:31]
	v_mfma_f32_16x16x32_bf16 v[24:27], v[162:165], v[202:205], v[24:27]
	v_mfma_f32_16x16x32_bf16 v[12:15], v[154:157], v[212:215], v[12:15]
	v_mfma_f32_16x16x32_bf16 v[8:11], v[162:165], v[212:215], v[8:11]
	v_mfma_f32_16x16x32_bf16 v[52:55], v[166:169], v[182:185], v[52:55]
	v_mfma_f32_16x16x32_bf16 v[48:51], v[174:177], v[182:185], v[48:51]
	v_mfma_f32_16x16x32_bf16 v[36:39], v[166:169], v[190:193], v[36:39]
	v_mfma_f32_16x16x32_bf16 v[32:35], v[174:177], v[190:193], v[32:35]
	v_mfma_f32_16x16x32_bf16 v[20:23], v[166:169], v[198:201], v[20:23]
	v_mfma_f32_16x16x32_bf16 v[16:19], v[174:177], v[198:201], v[16:19]
	v_mfma_f32_16x16x32_bf16 v[4:7], v[166:169], v[208:211], v[4:7]
	v_mfma_f32_16x16x32_bf16 v[0:3], v[174:177], v[208:211], v[0:3]
	v_mfma_f32_16x16x32_bf16 v[52:55], v[170:173], v[186:189], v[52:55]
	v_mfma_f32_16x16x32_bf16 v[48:51], v[178:181], v[186:189], v[48:51]
	v_mfma_f32_16x16x32_bf16 v[36:39], v[170:173], v[194:197], v[36:39]
	v_mfma_f32_16x16x32_bf16 v[32:35], v[178:181], v[194:197], v[32:35]
	v_mfma_f32_16x16x32_bf16 v[20:23], v[170:173], v[202:205], v[20:23]
	v_mfma_f32_16x16x32_bf16 v[16:19], v[178:181], v[202:205], v[16:19]
	v_mfma_f32_16x16x32_bf16 v[4:7], v[170:173], v[212:215], v[4:7]
	v_mfma_f32_16x16x32_bf16 v[0:3], v[178:181], v[212:215], v[0:3]
	s_barrier
	s_add_i32 s50, s50, 2
	s_add_u32 s48, s48, 0x100
	s_addc_u32 s49, s49, 0
	s_add_u32 s24, s24, 0x100
	s_addc_u32 s25, s25, 0
	s_cmp_gt_u32 s50, 5
	s_cbranch_scc0 .LBB0_2673
	s_and_b64 vcc, exec, s[12:13]
	s_cbranch_vccz .LBB0_2676
	s_barrier

.LBB0_3041:
	ds_read_b128 v[140:143], v151
	ds_read_b128 v[144:147], v151 offset:1024
	ds_read_b128 v[156:159], v151 offset:2048
	ds_read_b128 v[160:163], v151 offset:3072
	ds_read_b128 v[164:167], v152
	ds_read_b128 v[168:171], v152 offset:1024
	ds_read_b128 v[172:175], v152 offset:2048
	ds_read_b128 v[176:179], v152 offset:3072
	s_add_u32 s38, s36, 0xfffc0080
	s_addc_u32 s39, s37, -1
	s_cmp_eq_u32 s61, 12
	s_cselect_b32 s41, s3, s39
	s_cselect_b32 s40, s29, s38
	s_cselect_b32 s39, s27, s60
	s_cselect_b32 s38, s58, s59
	s_add_i32 m0, s46, 0xc000
	ds_read_b128 v[180:183], v153
	ds_read_b128 v[184:187], v153 offset:1024
	ds_read_b128 v[188:191], v153 offset:2048
	ds_read_b128 v[192:195], v153 offset:3072
	ds_read_b128 v[196:199], v153 offset:4096
	ds_read_b128 v[200:203], v153 offset:5120
	ds_read_b128 v[208:211], v153 offset:6144
	ds_read_b128 v[212:215], v153 offset:7168
	global_load_lds_dwordx4 v134, s[36:37]
	s_add_i32 m0, s46, 0xe000
	s_nop 0
	global_load_lds_dwordx4 v132, s[36:37]
	s_waitcnt vmcnt(8)
	s_waitcnt lgkmcnt(0)
	s_barrier
	s_waitcnt lgkmcnt(0)
	s_nop 0
	v_mfma_f32_16x16x32_bf16 v[124:127], v[140:143], v[180:183], v[124:127]
	v_mfma_f32_16x16x32_bf16 v[120:123], v[156:159], v[180:183], v[120:123]
	v_mfma_f32_16x16x32_bf16 v[108:111], v[140:143], v[188:191], v[108:111]
	v_mfma_f32_16x16x32_bf16 v[104:107], v[156:159], v[188:191], v[104:107]
	v_mfma_f32_16x16x32_bf16 v[92:95], v[140:143], v[196:199], v[92:95]
	v_mfma_f32_16x16x32_bf16 v[88:91], v[156:159], v[196:199], v[88:91]
	v_mfma_f32_16x16x32_bf16 v[76:79], v[140:143], v[208:211], v[76:79]
	v_mfma_f32_16x16x32_bf16 v[72:75], v[156:159], v[208:211], v[72:75]
	v_mfma_f32_16x16x32_bf16 v[124:127], v[144:147], v[184:187], v[124:127]
	v_mfma_f32_16x16x32_bf16 v[120:123], v[160:163], v[184:187], v[120:123]
	v_mfma_f32_16x16x32_bf16 v[108:111], v[144:147], v[192:195], v[108:111]
	v_mfma_f32_16x16x32_bf16 v[104:107], v[160:163], v[192:195], v[104:107]
	v_mfma_f32_16x16x32_bf16 v[92:95], v[144:147], v[200:203], v[92:95]
	v_mfma_f32_16x16x32_bf16 v[88:91], v[160:163], v[200:203], v[88:91]
	v_mfma_f32_16x16x32_bf16 v[76:79], v[144:147], v[212:215], v[76:79]
	v_mfma_f32_16x16x32_bf16 v[72:75], v[160:163], v[212:215], v[72:75]
	v_mfma_f32_16x16x32_bf16 v[116:119], v[164:167], v[180:183], v[116:119]
	v_mfma_f32_16x16x32_bf16 v[112:115], v[172:175], v[180:183], v[112:115]
	v_mfma_f32_16x16x32_bf16 v[100:103], v[164:167], v[188:191], v[100:103]
	v_mfma_f32_16x16x32_bf16 v[96:99], v[172:175], v[188:191], v[96:99]
	v_mfma_f32_16x16x32_bf16 v[84:87], v[164:167], v[196:199], v[84:87]
	v_mfma_f32_16x16x32_bf16 v[80:83], v[172:175], v[196:199], v[80:83]
	v_mfma_f32_16x16x32_bf16 v[68:71], v[164:167], v[208:211], v[68:71]
	v_mfma_f32_16x16x32_bf16 v[64:67], v[172:175], v[208:211], v[64:67]
	v_mfma_f32_16x16x32_bf16 v[116:119], v[168:171], v[184:187], v[116:119]
	v_mfma_f32_16x16x32_bf16 v[112:115], v[176:179], v[184:187], v[112:115]
	v_mfma_f32_16x16x32_bf16 v[100:103], v[168:171], v[192:195], v[100:103]
	v_mfma_f32_16x16x32_bf16 v[96:99], v[176:179], v[192:195], v[96:99]
	v_mfma_f32_16x16x32_bf16 v[84:87], v[168:171], v[200:203], v[84:87]
	v_mfma_f32_16x16x32_bf16 v[80:83], v[176:179], v[200:203], v[80:83]
	v_mfma_f32_16x16x32_bf16 v[68:71], v[168:171], v[212:215], v[68:71]
	v_mfma_f32_16x16x32_bf16 v[64:67], v[176:179], v[212:215], v[64:67]
	s_barrier
	s_add_i32 s62, s54, s45
	s_mov_b32 m0, s62
	ds_read_b128 v[180:183], v153 offset:16384
	ds_read_b128 v[184:187], v153 offset:17408
	ds_read_b128 v[188:191], v153 offset:18432
	ds_read_b128 v[192:195], v153 offset:19456
	ds_read_b128 v[196:199], v153 offset:20480
	ds_read_b128 v[200:203], v153 offset:21504
	ds_read_b128 v[208:211], v153 offset:22528
	ds_read_b128 v[212:215], v153 offset:23552
	global_load_lds_dwordx4 v128, s[38:39]
	s_add_i32 m0, s62, 0x2000
	s_add_u32 s62, s38, 0x40000
	s_mov_b64 s[98:99], s[38:39]
	s_addc_u32 s63, s39, 0
	s_add_i32 s64, s55, s45
	global_load_lds_dwordx4 v130, s[38:39]
	s_mov_b32 m0, s64
	s_mov_b64 s[100:101], s[40:41]
	global_load_lds_dwordx4 v128, s[62:63]
	s_add_i32 m0, s64, 0x2000
	s_nop 0
	global_load_lds_dwordx4 v130, s[62:63]
	s_mov_b32 m0, s46
	s_nop 0
	global_load_lds_dwordx4 v128, s[40:41]
	s_mov_b32 m0, s47
	s_nop 0
	global_load_lds_dwordx4 v130, s[40:41]
	s_waitcnt vmcnt(8)
	s_waitcnt lgkmcnt(0)
	s_barrier
	s_waitcnt lgkmcnt(0)
	s_nop 0
	v_mfma_f32_16x16x32_bf16 v[60:63], v[140:143], v[180:183], v[60:63]
	v_mfma_f32_16x16x32_bf16 v[56:59], v[156:159], v[180:183], v[56:59]
	v_mfma_f32_16x16x32_bf16 v[44:47], v[140:143], v[188:191], v[44:47]
	v_mfma_f32_16x16x32_bf16 v[40:43], v[156:159], v[188:191], v[40:43]
	v_mfma_f32_16x16x32_bf16 v[28:31], v[140:143], v[196:199], v[28:31]
	v_mfma_f32_16x16x32_bf16 v[24:27], v[156:159], v[196:199], v[24:27]
	v_mfma_f32_16x16x32_bf16 v[12:15], v[140:143], v[208:211], v[12:15]
	v_mfma_f32_16x16x32_bf16 v[8:11], v[156:159], v[208:211], v[8:11]
	v_mfma_f32_16x16x32_bf16 v[60:63], v[144:147], v[184:187], v[60:63]
	v_mfma_f32_16x16x32_bf16 v[56:59], v[160:163], v[184:187], v[56:59]
	v_mfma_f32_16x16x32_bf16 v[44:47], v[144:147], v[192:195], v[44:47]
	v_mfma_f32_16x16x32_bf16 v[40:43], v[160:163], v[192:195], v[40:43]
	v_mfma_f32_16x16x32_bf16 v[28:31], v[144:147], v[200:203], v[28:31]
	v_mfma_f32_16x16x32_bf16 v[24:27], v[160:163], v[200:203], v[24:27]
	v_mfma_f32_16x16x32_bf16 v[12:15], v[144:147], v[212:215], v[12:15]
	v_mfma_f32_16x16x32_bf16 v[8:11], v[160:163], v[212:215], v[8:11]
	v_mfma_f32_16x16x32_bf16 v[52:55], v[164:167], v[180:183], v[52:55]
	v_mfma_f32_16x16x32_bf16 v[48:51], v[172:175], v[180:183], v[48:51]
	v_mfma_f32_16x16x32_bf16 v[36:39], v[164:167], v[188:191], v[36:39]
	v_mfma_f32_16x16x32_bf16 v[32:35], v[172:175], v[188:191], v[32:35]
	v_mfma_f32_16x16x32_bf16 v[20:23], v[164:167], v[196:199], v[20:23]
	v_mfma_f32_16x16x32_bf16 v[16:19], v[172:175], v[196:199], v[16:19]
	v_mfma_f32_16x16x32_bf16 v[4:7], v[164:167], v[208:211], v[4:7]
	v_mfma_f32_16x16x32_bf16 v[0:3], v[172:175], v[208:211], v[0:3]
	v_mfma_f32_16x16x32_bf16 v[52:55], v[168:171], v[184:187], v[52:55]
	v_mfma_f32_16x16x32_bf16 v[48:51], v[176:179], v[184:187], v[48:51]
	v_mfma_f32_16x16x32_bf16 v[36:39], v[168:171], v[192:195], v[36:39]
	v_mfma_f32_16x16x32_bf16 v[32:35], v[176:179], v[192:195], v[32:35]
	v_mfma_f32_16x16x32_bf16 v[20:23], v[168:171], v[200:203], v[20:23]
	v_mfma_f32_16x16x32_bf16 v[16:19], v[176:179], v[200:203], v[16:19]
	v_mfma_f32_16x16x32_bf16 v[4:7], v[168:171], v[212:215], v[4:7]
	v_mfma_f32_16x16x32_bf16 v[0:3], v[176:179], v[212:215], v[0:3]
	s_barrier
	s_add_i32 s62, 0, 0x18000
	v_add_u32_e32 v155, s62, v149
	s_add_i32 s63, 0, 0x1c000
	ds_read_b128 v[140:143], v155
	ds_read_b128 v[144:147], v155 offset:1024
	ds_read_b128 v[156:159], v155 offset:2048
	ds_read_b128 v[160:163], v155 offset:3072
	v_add_u32_e32 v155, s63, v149
	ds_read_b128 v[164:167], v155
	ds_read_b128 v[168:171], v155 offset:1024
	ds_read_b128 v[172:175], v155 offset:2048
	ds_read_b128 v[176:179], v155 offset:3072
	s_add_u32 s40, s40, 0x40000
	s_addc_u32 s41, s41, 0
	s_mov_b32 m0, s48
	ds_read_b128 v[180:183], v153 offset:32768
	ds_read_b128 v[184:187], v153 offset:33792
	ds_read_b128 v[188:191], v153 offset:34816
	ds_read_b128 v[192:195], v153 offset:35840
	ds_read_b128 v[196:199], v153 offset:36864
	ds_read_b128 v[200:203], v153 offset:37888
	ds_read_b128 v[208:211], v153 offset:38912
	ds_read_b128 v[212:215], v153 offset:39936
	global_load_lds_dwordx4 v128, s[40:41]
	s_mov_b32 m0, s49
	s_nop 0
	global_load_lds_dwordx4 v130, s[40:41]
	s_waitcnt vmcnt(8)
	s_waitcnt lgkmcnt(0)
	s_barrier
	s_waitcnt lgkmcnt(0)
	s_nop 0
	v_mfma_f32_16x16x32_bf16 v[124:127], v[140:143], v[180:183], v[124:127]
	v_mfma_f32_16x16x32_bf16 v[120:123], v[156:159], v[180:183], v[120:123]
	v_mfma_f32_16x16x32_bf16 v[108:111], v[140:143], v[188:191], v[108:111]
	v_mfma_f32_16x16x32_bf16 v[104:107], v[156:159], v[188:191], v[104:107]
	v_mfma_f32_16x16x32_bf16 v[92:95], v[140:143], v[196:199], v[92:95]
	v_mfma_f32_16x16x32_bf16 v[88:91], v[156:159], v[196:199], v[88:91]
	v_mfma_f32_16x16x32_bf16 v[76:79], v[140:143], v[208:211], v[76:79]
	v_mfma_f32_16x16x32_bf16 v[72:75], v[156:159], v[208:211], v[72:75]
	v_mfma_f32_16x16x32_bf16 v[124:127], v[144:147], v[184:187], v[124:127]
	v_mfma_f32_16x16x32_bf16 v[120:123], v[160:163], v[184:187], v[120:123]
	v_mfma_f32_16x16x32_bf16 v[108:111], v[144:147], v[192:195], v[108:111]
	v_mfma_f32_16x16x32_bf16 v[104:107], v[160:163], v[192:195], v[104:107]
	v_mfma_f32_16x16x32_bf16 v[92:95], v[144:147], v[200:203], v[92:95]
	v_mfma_f32_16x16x32_bf16 v[88:91], v[160:163], v[200:203], v[88:91]
	v_mfma_f32_16x16x32_bf16 v[76:79], v[144:147], v[212:215], v[76:79]
	v_mfma_f32_16x16x32_bf16 v[72:75], v[160:163], v[212:215], v[72:75]
	v_mfma_f32_16x16x32_bf16 v[116:119], v[164:167], v[180:183], v[116:119]
	v_mfma_f32_16x16x32_bf16 v[112:115], v[172:175], v[180:183], v[112:115]
	v_mfma_f32_16x16x32_bf16 v[100:103], v[164:167], v[188:191], v[100:103]
	v_mfma_f32_16x16x32_bf16 v[96:99], v[172:175], v[188:191], v[96:99]
	v_mfma_f32_16x16x32_bf16 v[84:87], v[164:167], v[196:199], v[84:87]
	v_mfma_f32_16x16x32_bf16 v[80:83], v[172:175], v[196:199], v[80:83]
	v_mfma_f32_16x16x32_bf16 v[68:71], v[164:167], v[208:211], v[68:71]
	v_mfma_f32_16x16x32_bf16 v[64:67], v[172:175], v[208:211], v[64:67]
	v_mfma_f32_16x16x32_bf16 v[116:119], v[168:171], v[184:187], v[116:119]
	v_mfma_f32_16x16x32_bf16 v[112:115], v[176:179], v[184:187], v[112:115]
	v_mfma_f32_16x16x32_bf16 v[100:103], v[168:171], v[192:195], v[100:103]
	v_mfma_f32_16x16x32_bf16 v[96:99], v[176:179], v[192:195], v[96:99]
	v_mfma_f32_16x16x32_bf16 v[84:87], v[168:171], v[200:203], v[84:87]
	v_mfma_f32_16x16x32_bf16 v[80:83], v[176:179], v[200:203], v[80:83]
	v_mfma_f32_16x16x32_bf16 v[68:71], v[168:171], v[212:215], v[68:71]
	v_mfma_f32_16x16x32_bf16 v[64:67], v[176:179], v[212:215], v[64:67]
	s_barrier
	s_add_i32 s40, s62, s45
	s_mov_b32 m0, s40
	ds_read_b128 v[180:183], v153 offset:49152
	ds_read_b128 v[184:187], v153 offset:50176
	ds_read_b128 v[188:191], v153 offset:51200
	ds_read_b128 v[192:195], v153 offset:52224
	ds_read_b128 v[196:199], v153 offset:53248
	ds_read_b128 v[200:203], v153 offset:54272
	ds_read_b128 v[208:211], v153 offset:55296
	ds_read_b128 v[212:215], v153 offset:56320
	global_load_lds_dwordx4 v204, s[38:39]
	s_add_i32 m0, s40, 0x2000
	s_add_u32 s38, s38, 0x40080
	s_addc_u32 s39, s39, 0
	s_add_i32 s40, s63, s45
	global_load_lds_dwordx4 v205, s[98:99]
	s_mov_b32 m0, s40
	s_nop 0
	global_load_lds_dwordx4 v128, s[38:39]
	s_add_i32 m0, s40, 0x2000
	s_nop 0
	global_load_lds_dwordx4 v130, s[38:39]
	s_mov_b32 m0, s51
	s_nop 0
	global_load_lds_dwordx4 v204, s[100:101]
	s_mov_b32 m0, s52
	s_nop 0
	global_load_lds_dwordx4 v205, s[100:101]
	s_waitcnt vmcnt(8)
	s_waitcnt lgkmcnt(0)
	s_barrier
	s_waitcnt lgkmcnt(0)
	v_mfma_f32_16x16x32_bf16 v[60:63], v[140:143], v[180:183], v[60:63]
	v_mfma_f32_16x16x32_bf16 v[56:59], v[156:159], v[180:183], v[56:59]
	v_mfma_f32_16x16x32_bf16 v[44:47], v[140:143], v[188:191], v[44:47]
	v_mfma_f32_16x16x32_bf16 v[40:43], v[156:159], v[188:191], v[40:43]
	v_mfma_f32_16x16x32_bf16 v[28:31], v[140:143], v[196:199], v[28:31]
	v_mfma_f32_16x16x32_bf16 v[24:27], v[156:159], v[196:199], v[24:27]
	v_mfma_f32_16x16x32_bf16 v[12:15], v[140:143], v[208:211], v[12:15]
	v_mfma_f32_16x16x32_bf16 v[8:11], v[156:159], v[208:211], v[8:11]
	v_mfma_f32_16x16x32_bf16 v[60:63], v[144:147], v[184:187], v[60:63]
	v_mfma_f32_16x16x32_bf16 v[56:59], v[160:163], v[184:187], v[56:59]
	v_mfma_f32_16x16x32_bf16 v[44:47], v[144:147], v[192:195], v[44:47]
	v_mfma_f32_16x16x32_bf16 v[40:43], v[160:163], v[192:195], v[40:43]
	v_mfma_f32_16x16x32_bf16 v[28:31], v[144:147], v[200:203], v[28:31]
	v_mfma_f32_16x16x32_bf16 v[24:27], v[160:163], v[200:203], v[24:27]
	v_mfma_f32_16x16x32_bf16 v[12:15], v[144:147], v[212:215], v[12:15]
	v_mfma_f32_16x16x32_bf16 v[8:11], v[160:163], v[212:215], v[8:11]
	v_mfma_f32_16x16x32_bf16 v[52:55], v[164:167], v[180:183], v[52:55]
	v_mfma_f32_16x16x32_bf16 v[48:51], v[172:175], v[180:183], v[48:51]
	v_mfma_f32_16x16x32_bf16 v[36:39], v[164:167], v[188:191], v[36:39]
	v_mfma_f32_16x16x32_bf16 v[32:35], v[172:175], v[188:191], v[32:35]
	v_mfma_f32_16x16x32_bf16 v[20:23], v[164:167], v[196:199], v[20:23]
	v_mfma_f32_16x16x32_bf16 v[16:19], v[172:175], v[196:199], v[16:19]
	v_mfma_f32_16x16x32_bf16 v[4:7], v[164:167], v[208:211], v[4:7]
	v_mfma_f32_16x16x32_bf16 v[0:3], v[172:175], v[208:211], v[0:3]
	v_mfma_f32_16x16x32_bf16 v[52:55], v[168:171], v[184:187], v[52:55]
	v_mfma_f32_16x16x32_bf16 v[48:51], v[176:179], v[184:187], v[48:51]
	v_mfma_f32_16x16x32_bf16 v[36:39], v[168:171], v[192:195], v[36:39]
	v_mfma_f32_16x16x32_bf16 v[32:35], v[176:179], v[192:195], v[32:35]
	v_mfma_f32_16x16x32_bf16 v[20:23], v[168:171], v[200:203], v[20:23]
	v_mfma_f32_16x16x32_bf16 v[16:19], v[176:179], v[200:203], v[16:19]
	v_mfma_f32_16x16x32_bf16 v[4:7], v[168:171], v[212:215], v[4:7]
	v_mfma_f32_16x16x32_bf16 v[0:3], v[176:179], v[212:215], v[0:3]
	s_barrier
	s_add_i32 s61, s61, 2
	s_add_u32 s59, s59, 0x100
	s_addc_u32 s60, s60, 0
	s_add_u32 s36, s36, 0x100
	s_addc_u32 s37, s37, 0
	s_cmp_gt_u32 s61, 13
	s_cbranch_scc0 .LBB0_3041
	s_and_b64 vcc, exec, s[24:25]
	s_cbranch_vccz .LBB0_3044
	s_barrier
